# LN prompt rows hand-written: g/b resident in registers, 3 rows in flight, no per-chunk vmcnt(0) round trips
# speedup vs baseline: 1.0826x; 1.0826x over previous
.LBB0_412:
	s_cmp_lt_i32 s30, 4
	s_cselect_b64 s[8:9], -1, 0
	s_and_b64 s[10:11], s[8:9], s[6:7]
	s_andn2_b64 vcc, exec, s[10:11]
	v_and_b32_e32 v136, 63, v231
	s_cbranch_vccnz .LBB0_427
	s_load_dwordx4 s[12:15], s[0:1], 0x58
	s_load_dwordx2 s[16:17], s[0:1], 0x8
	v_lshl_add_u32 v32, s2, 3, v230
	s_movk_i32 s3, 0x2000
	v_cmp_gt_i32_e32 vcc, s3, v32
	s_and_saveexec_b64 s[18:19], vcc
	s_cbranch_execz .LBB0_418
	s_load_dwordx4 s[60:63], s[0:1], 0x58
	v_lshl_add_u32 v2, s2, 3, v230
	v_lshlrev_b32_e32 v137, 4, v136
	v_lshlrev_b32_e32 v1, 3, v136
	v_lshl_add_u32 v1, v2, 12, v1
	v_add_u32_e32 v4, 0x1000, v137
	s_add_u32 s88, s28, 0xe600000
	s_addc_u32 s89, s29, 0
	s_add_u32 s90, s28, 0xc500000
	s_addc_u32 s91, s29, 0
	global_load_dwordx2 v[204:205], v1, s[88:89] offset:0
	global_load_dwordx2 v[206:207], v1, s[88:89] offset:512
	global_load_dwordx2 v[208:209], v1, s[88:89] offset:1024
	global_load_dwordx2 v[210:211], v1, s[88:89] offset:1536
	global_load_dwordx2 v[212:213], v1, s[88:89] offset:2048
	global_load_dwordx2 v[214:215], v1, s[88:89] offset:2560
	global_load_dwordx2 v[216:217], v1, s[88:89] offset:3072
	global_load_dwordx2 v[218:219], v1, s[88:89] offset:3584
	s_add_u32 s88, s88, 0x800000
	s_addc_u32 s89, s89, 0
	s_waitcnt lgkmcnt(0)
	global_load_dwordx4 v[140:143], v137, s[60:61] offset:0
	global_load_dwordx4 v[144:147], v137, s[60:61] offset:1024
	global_load_dwordx4 v[148:151], v137, s[60:61] offset:2048
	global_load_dwordx4 v[152:155], v137, s[60:61] offset:3072
	global_load_dwordx4 v[156:159], v4, s[60:61] offset:0
	global_load_dwordx4 v[160:163], v4, s[60:61] offset:1024
	global_load_dwordx4 v[164:167], v4, s[60:61] offset:2048
	global_load_dwordx4 v[168:171], v4, s[60:61] offset:3072
	global_load_dwordx4 v[172:175], v137, s[62:63] offset:0
	global_load_dwordx4 v[176:179], v137, s[62:63] offset:1024
	global_load_dwordx4 v[180:183], v137, s[62:63] offset:2048
	global_load_dwordx4 v[184:187], v137, s[62:63] offset:3072
	global_load_dwordx4 v[188:191], v4, s[62:63] offset:0
	global_load_dwordx4 v[192:195], v4, s[62:63] offset:1024
	global_load_dwordx4 v[196:199], v4, s[62:63] offset:2048
	global_load_dwordx4 v[200:203], v4, s[62:63] offset:3072
	global_load_dwordx2 v[110:111], v1, s[88:89] offset:0
	global_load_dwordx2 v[112:113], v1, s[88:89] offset:512
	global_load_dwordx2 v[114:115], v1, s[88:89] offset:1024
	global_load_dwordx2 v[116:117], v1, s[88:89] offset:1536
	global_load_dwordx2 v[118:119], v1, s[88:89] offset:2048
	global_load_dwordx2 v[120:121], v1, s[88:89] offset:2560
	global_load_dwordx2 v[122:123], v1, s[88:89] offset:3072
	global_load_dwordx2 v[124:125], v1, s[88:89] offset:3584
	s_add_u32 s88, s88, 0x800000
	s_addc_u32 s89, s89, 0
	global_load_dwordx2 v[24:25], v1, s[88:89] offset:0
	global_load_dwordx2 v[26:27], v1, s[88:89] offset:512
	global_load_dwordx2 v[8:9], v1, s[88:89] offset:1024
	global_load_dwordx2 v[10:11], v1, s[88:89] offset:1536
	global_load_dwordx2 v[220:221], v1, s[88:89] offset:2048
	global_load_dwordx2 v[222:223], v1, s[88:89] offset:2560
	global_load_dwordx2 v[224:225], v1, s[88:89] offset:3072
	global_load_dwordx2 v[226:227], v1, s[88:89] offset:3584
	s_add_u32 s88, s88, 0x800000
	s_addc_u32 s89, s89, 0
	s_waitcnt vmcnt(32)
	v_lshlrev_b32_e32 v126, 16, v204
	v_and_b32_e32 v127, 0xffff0000, v204
	v_lshlrev_b32_e32 v128, 16, v205
	v_and_b32_e32 v129, 0xffff0000, v205
	v_lshlrev_b32_e32 v130, 16, v206
	v_and_b32_e32 v131, 0xffff0000, v206
	v_lshlrev_b32_e32 v132, 16, v207
	v_and_b32_e32 v133, 0xffff0000, v207
	v_lshlrev_b32_e32 v240, 16, v208
	v_and_b32_e32 v241, 0xffff0000, v208
	v_lshlrev_b32_e32 v242, 16, v209
	v_and_b32_e32 v243, 0xffff0000, v209
	v_lshlrev_b32_e32 v244, 16, v210
	v_and_b32_e32 v245, 0xffff0000, v210
	v_lshlrev_b32_e32 v246, 16, v211
	v_and_b32_e32 v247, 0xffff0000, v211
	v_lshlrev_b32_e32 v248, 16, v212
	v_and_b32_e32 v249, 0xffff0000, v212
	v_lshlrev_b32_e32 v250, 16, v213
	v_and_b32_e32 v251, 0xffff0000, v213
	v_lshlrev_b32_e32 v32, 16, v214
	v_and_b32_e32 v33, 0xffff0000, v214
	v_lshlrev_b32_e32 v34, 16, v215
	v_and_b32_e32 v35, 0xffff0000, v215
	v_lshlrev_b32_e32 v36, 16, v216
	v_and_b32_e32 v37, 0xffff0000, v216
	v_lshlrev_b32_e32 v38, 16, v217
	v_and_b32_e32 v39, 0xffff0000, v217
	v_lshlrev_b32_e32 v20, 16, v218
	v_and_b32_e32 v21, 0xffff0000, v218
	v_lshlrev_b32_e32 v22, 16, v219
	v_and_b32_e32 v23, 0xffff0000, v219
	v_pk_add_f32 v[228:229], v[126:127], v[128:129]
	v_pk_add_f32 v[228:229], v[228:229], v[130:131]
	v_pk_add_f32 v[228:229], v[228:229], v[132:133]
	v_pk_add_f32 v[228:229], v[228:229], v[240:241]
	v_pk_add_f32 v[228:229], v[228:229], v[242:243]
	v_pk_add_f32 v[228:229], v[228:229], v[244:245]
	v_pk_add_f32 v[228:229], v[228:229], v[246:247]
	v_pk_add_f32 v[228:229], v[228:229], v[248:249]
	v_pk_add_f32 v[228:229], v[228:229], v[250:251]
	v_pk_add_f32 v[228:229], v[228:229], v[32:33]
	v_pk_add_f32 v[228:229], v[228:229], v[34:35]
	v_pk_add_f32 v[228:229], v[228:229], v[36:37]
	v_pk_add_f32 v[228:229], v[228:229], v[38:39]
	v_pk_add_f32 v[228:229], v[228:229], v[20:21]
	v_pk_add_f32 v[228:229], v[228:229], v[22:23]
	v_add_f32_e32 v228, v228, v229
	s_nop 1
	v_add_f32_dpp v228, v228, v228 quad_perm:[1,0,3,2] row_mask:0xf bank_mask:0xf bound_ctrl:1
	s_nop 1
	v_add_f32_dpp v228, v228, v228 quad_perm:[2,3,0,1] row_mask:0xf bank_mask:0xf bound_ctrl:1
	s_nop 1
	v_add_f32_dpp v228, v228, v228 row_half_mirror row_mask:0xf bank_mask:0xf bound_ctrl:1
	s_nop 1
	v_add_f32_dpp v228, v228, v228 row_mirror row_mask:0xf bank_mask:0xf bound_ctrl:1
	v_mov_b32_e32 v2, v228
	s_nop 1
	v_permlane16_swap_b32 v228, v2
	s_nop 0
	v_add_f32_e32 v228, v228, v2
	v_mov_b32_e32 v2, v228
	s_nop 1
	v_permlane32_swap_b32 v228, v2
	s_nop 0
	v_add_f32_e32 v228, v228, v2
	v_mul_f32_e32 v134, 0x3a000000, v228
	v_pk_add_f32 v[126:127], v[126:127], v[134:135] op_sel_hi:[1,0] neg_lo:[0,1] neg_hi:[0,1]
	v_pk_add_f32 v[128:129], v[128:129], v[134:135] op_sel_hi:[1,0] neg_lo:[0,1] neg_hi:[0,1]
	v_pk_add_f32 v[130:131], v[130:131], v[134:135] op_sel_hi:[1,0] neg_lo:[0,1] neg_hi:[0,1]
	v_pk_add_f32 v[132:133], v[132:133], v[134:135] op_sel_hi:[1,0] neg_lo:[0,1] neg_hi:[0,1]
	v_pk_add_f32 v[240:241], v[240:241], v[134:135] op_sel_hi:[1,0] neg_lo:[0,1] neg_hi:[0,1]
	v_pk_add_f32 v[242:243], v[242:243], v[134:135] op_sel_hi:[1,0] neg_lo:[0,1] neg_hi:[0,1]
	v_pk_add_f32 v[244:245], v[244:245], v[134:135] op_sel_hi:[1,0] neg_lo:[0,1] neg_hi:[0,1]
	v_pk_add_f32 v[246:247], v[246:247], v[134:135] op_sel_hi:[1,0] neg_lo:[0,1] neg_hi:[0,1]
	v_pk_add_f32 v[248:249], v[248:249], v[134:135] op_sel_hi:[1,0] neg_lo:[0,1] neg_hi:[0,1]
	v_pk_add_f32 v[250:251], v[250:251], v[134:135] op_sel_hi:[1,0] neg_lo:[0,1] neg_hi:[0,1]
	v_pk_add_f32 v[32:33], v[32:33], v[134:135] op_sel_hi:[1,0] neg_lo:[0,1] neg_hi:[0,1]
	v_pk_add_f32 v[34:35], v[34:35], v[134:135] op_sel_hi:[1,0] neg_lo:[0,1] neg_hi:[0,1]
	v_pk_add_f32 v[36:37], v[36:37], v[134:135] op_sel_hi:[1,0] neg_lo:[0,1] neg_hi:[0,1]
	v_pk_add_f32 v[38:39], v[38:39], v[134:135] op_sel_hi:[1,0] neg_lo:[0,1] neg_hi:[0,1]
	v_pk_add_f32 v[20:21], v[20:21], v[134:135] op_sel_hi:[1,0] neg_lo:[0,1] neg_hi:[0,1]
	v_pk_add_f32 v[22:23], v[22:23], v[134:135] op_sel_hi:[1,0] neg_lo:[0,1] neg_hi:[0,1]
	v_pk_mul_f32 v[228:229], v[126:127], v[126:127]
	v_pk_fma_f32 v[228:229], v[128:129], v[128:129], v[228:229]
	v_pk_fma_f32 v[228:229], v[130:131], v[130:131], v[228:229]
	v_pk_fma_f32 v[228:229], v[132:133], v[132:133], v[228:229]
	v_pk_fma_f32 v[228:229], v[240:241], v[240:241], v[228:229]
	v_pk_fma_f32 v[228:229], v[242:243], v[242:243], v[228:229]
	v_pk_fma_f32 v[228:229], v[244:245], v[244:245], v[228:229]
	v_pk_fma_f32 v[228:229], v[246:247], v[246:247], v[228:229]
	v_pk_fma_f32 v[228:229], v[248:249], v[248:249], v[228:229]
	v_pk_fma_f32 v[228:229], v[250:251], v[250:251], v[228:229]
	v_pk_fma_f32 v[228:229], v[32:33], v[32:33], v[228:229]
	v_pk_fma_f32 v[228:229], v[34:35], v[34:35], v[228:229]
	v_pk_fma_f32 v[228:229], v[36:37], v[36:37], v[228:229]
	v_pk_fma_f32 v[228:229], v[38:39], v[38:39], v[228:229]
	v_pk_fma_f32 v[228:229], v[20:21], v[20:21], v[228:229]
	v_pk_fma_f32 v[228:229], v[22:23], v[22:23], v[228:229]
	v_add_f32_e32 v228, v228, v229
	s_nop 1
	v_add_f32_dpp v228, v228, v228 quad_perm:[1,0,3,2] row_mask:0xf bank_mask:0xf bound_ctrl:1
	s_nop 1
	v_add_f32_dpp v228, v228, v228 quad_perm:[2,3,0,1] row_mask:0xf bank_mask:0xf bound_ctrl:1
	s_nop 1
	v_add_f32_dpp v228, v228, v228 row_half_mirror row_mask:0xf bank_mask:0xf bound_ctrl:1
	s_nop 1
	v_add_f32_dpp v228, v228, v228 row_mirror row_mask:0xf bank_mask:0xf bound_ctrl:1
	v_mov_b32_e32 v2, v228
	s_nop 1
	v_permlane16_swap_b32 v228, v2
	s_nop 0
	v_add_f32_e32 v228, v228, v2
	v_mov_b32_e32 v2, v228
	s_nop 1
	v_permlane32_swap_b32 v228, v2
	s_nop 0
	v_add_f32_e32 v228, v228, v2
	v_mul_f32_e32 v0, 0x3a000000, v228
	v_add_f32_e32 v0, 0x3727c5ac, v0
	v_rsq_f32_e32 v0, v0
	s_waitcnt vmcnt(16)
	v_pk_mul_f32 v[228:229], v[140:141], v[0:1] op_sel_hi:[1,0]
	v_pk_fma_f32 v[126:127], v[126:127], v[228:229], v[172:173]
	v_pk_mul_f32 v[228:229], v[142:143], v[0:1] op_sel_hi:[1,0]
	v_pk_fma_f32 v[128:129], v[128:129], v[228:229], v[174:175]
	v_pk_mul_f32 v[228:229], v[144:145], v[0:1] op_sel_hi:[1,0]
	v_pk_fma_f32 v[130:131], v[130:131], v[228:229], v[176:177]
	v_pk_mul_f32 v[228:229], v[146:147], v[0:1] op_sel_hi:[1,0]
	v_pk_fma_f32 v[132:133], v[132:133], v[228:229], v[178:179]
	v_pk_mul_f32 v[228:229], v[148:149], v[0:1] op_sel_hi:[1,0]
	v_pk_fma_f32 v[240:241], v[240:241], v[228:229], v[180:181]
	v_pk_mul_f32 v[228:229], v[150:151], v[0:1] op_sel_hi:[1,0]
	v_pk_fma_f32 v[242:243], v[242:243], v[228:229], v[182:183]
	v_pk_mul_f32 v[228:229], v[152:153], v[0:1] op_sel_hi:[1,0]
	v_pk_fma_f32 v[244:245], v[244:245], v[228:229], v[184:185]
	v_pk_mul_f32 v[228:229], v[154:155], v[0:1] op_sel_hi:[1,0]
	v_pk_fma_f32 v[246:247], v[246:247], v[228:229], v[186:187]
	v_pk_mul_f32 v[228:229], v[156:157], v[0:1] op_sel_hi:[1,0]
	v_pk_fma_f32 v[248:249], v[248:249], v[228:229], v[188:189]
	v_pk_mul_f32 v[228:229], v[158:159], v[0:1] op_sel_hi:[1,0]
	v_pk_fma_f32 v[250:251], v[250:251], v[228:229], v[190:191]
	v_pk_mul_f32 v[228:229], v[160:161], v[0:1] op_sel_hi:[1,0]
	v_pk_fma_f32 v[32:33], v[32:33], v[228:229], v[192:193]
	v_pk_mul_f32 v[228:229], v[162:163], v[0:1] op_sel_hi:[1,0]
	v_pk_fma_f32 v[34:35], v[34:35], v[228:229], v[194:195]
	v_pk_mul_f32 v[228:229], v[164:165], v[0:1] op_sel_hi:[1,0]
	v_pk_fma_f32 v[36:37], v[36:37], v[228:229], v[196:197]
	v_pk_mul_f32 v[228:229], v[166:167], v[0:1] op_sel_hi:[1,0]
	v_pk_fma_f32 v[38:39], v[38:39], v[228:229], v[198:199]
	v_pk_mul_f32 v[228:229], v[168:169], v[0:1] op_sel_hi:[1,0]
	v_pk_fma_f32 v[20:21], v[20:21], v[228:229], v[200:201]
	v_pk_mul_f32 v[228:229], v[170:171], v[0:1] op_sel_hi:[1,0]
	v_pk_fma_f32 v[22:23], v[22:23], v[228:229], v[202:203]
	v_cvt_pk_bf16_f32 v204, v126, v127
	v_cvt_pk_bf16_f32 v205, v128, v129
	v_cvt_pk_bf16_f32 v206, v130, v131
	v_cvt_pk_bf16_f32 v207, v132, v133
	v_cvt_pk_bf16_f32 v208, v240, v241
	v_cvt_pk_bf16_f32 v209, v242, v243
	v_cvt_pk_bf16_f32 v210, v244, v245
	v_cvt_pk_bf16_f32 v211, v246, v247
	v_cvt_pk_bf16_f32 v212, v248, v249
	v_cvt_pk_bf16_f32 v213, v250, v251
	v_cvt_pk_bf16_f32 v214, v32, v33
	v_cvt_pk_bf16_f32 v215, v34, v35
	v_cvt_pk_bf16_f32 v216, v36, v37
	v_cvt_pk_bf16_f32 v217, v38, v39
	v_cvt_pk_bf16_f32 v218, v20, v21
	v_cvt_pk_bf16_f32 v219, v22, v23
	global_store_dwordx2 v1, v[204:205], s[90:91] offset:0
	global_store_dwordx2 v1, v[206:207], s[90:91] offset:512
	global_store_dwordx2 v1, v[208:209], s[90:91] offset:1024
	global_store_dwordx2 v1, v[210:211], s[90:91] offset:1536
	global_store_dwordx2 v1, v[212:213], s[90:91] offset:2048
	global_store_dwordx2 v1, v[214:215], s[90:91] offset:2560
	global_store_dwordx2 v1, v[216:217], s[90:91] offset:3072
	global_store_dwordx2 v1, v[218:219], s[90:91] offset:3584
	s_add_u32 s90, s90, 0x800000
	s_addc_u32 s91, s91, 0
	global_load_dwordx2 v[204:205], v1, s[88:89] offset:0
	global_load_dwordx2 v[206:207], v1, s[88:89] offset:512
	global_load_dwordx2 v[208:209], v1, s[88:89] offset:1024
	global_load_dwordx2 v[210:211], v1, s[88:89] offset:1536
	global_load_dwordx2 v[212:213], v1, s[88:89] offset:2048
	global_load_dwordx2 v[214:215], v1, s[88:89] offset:2560
	global_load_dwordx2 v[216:217], v1, s[88:89] offset:3072
	global_load_dwordx2 v[218:219], v1, s[88:89] offset:3584
	s_add_u32 s88, s88, 0x800000
	s_addc_u32 s89, s89, 0
	s_waitcnt vmcnt(24)
	v_lshlrev_b32_e32 v126, 16, v110
	v_and_b32_e32 v127, 0xffff0000, v110
	v_lshlrev_b32_e32 v128, 16, v111
	v_and_b32_e32 v129, 0xffff0000, v111
	v_lshlrev_b32_e32 v130, 16, v112
	v_and_b32_e32 v131, 0xffff0000, v112
	v_lshlrev_b32_e32 v132, 16, v113
	v_and_b32_e32 v133, 0xffff0000, v113
	v_lshlrev_b32_e32 v240, 16, v114
	v_and_b32_e32 v241, 0xffff0000, v114
	v_lshlrev_b32_e32 v242, 16, v115
	v_and_b32_e32 v243, 0xffff0000, v115
	v_lshlrev_b32_e32 v244, 16, v116
	v_and_b32_e32 v245, 0xffff0000, v116
	v_lshlrev_b32_e32 v246, 16, v117
	v_and_b32_e32 v247, 0xffff0000, v117
	v_lshlrev_b32_e32 v248, 16, v118
	v_and_b32_e32 v249, 0xffff0000, v118
	v_lshlrev_b32_e32 v250, 16, v119
	v_and_b32_e32 v251, 0xffff0000, v119
	v_lshlrev_b32_e32 v32, 16, v120
	v_and_b32_e32 v33, 0xffff0000, v120
	v_lshlrev_b32_e32 v34, 16, v121
	v_and_b32_e32 v35, 0xffff0000, v121
	v_lshlrev_b32_e32 v36, 16, v122
	v_and_b32_e32 v37, 0xffff0000, v122
	v_lshlrev_b32_e32 v38, 16, v123
	v_and_b32_e32 v39, 0xffff0000, v123
	v_lshlrev_b32_e32 v20, 16, v124
	v_and_b32_e32 v21, 0xffff0000, v124
	v_lshlrev_b32_e32 v22, 16, v125
	v_and_b32_e32 v23, 0xffff0000, v125
	v_pk_add_f32 v[228:229], v[126:127], v[128:129]
	v_pk_add_f32 v[228:229], v[228:229], v[130:131]
	v_pk_add_f32 v[228:229], v[228:229], v[132:133]
	v_pk_add_f32 v[228:229], v[228:229], v[240:241]
	v_pk_add_f32 v[228:229], v[228:229], v[242:243]
	v_pk_add_f32 v[228:229], v[228:229], v[244:245]
	v_pk_add_f32 v[228:229], v[228:229], v[246:247]
	v_pk_add_f32 v[228:229], v[228:229], v[248:249]
	v_pk_add_f32 v[228:229], v[228:229], v[250:251]
	v_pk_add_f32 v[228:229], v[228:229], v[32:33]
	v_pk_add_f32 v[228:229], v[228:229], v[34:35]
	v_pk_add_f32 v[228:229], v[228:229], v[36:37]
	v_pk_add_f32 v[228:229], v[228:229], v[38:39]
	v_pk_add_f32 v[228:229], v[228:229], v[20:21]
	v_pk_add_f32 v[228:229], v[228:229], v[22:23]
	v_add_f32_e32 v228, v228, v229
	s_nop 1
	v_add_f32_dpp v228, v228, v228 quad_perm:[1,0,3,2] row_mask:0xf bank_mask:0xf bound_ctrl:1
	s_nop 1
	v_add_f32_dpp v228, v228, v228 quad_perm:[2,3,0,1] row_mask:0xf bank_mask:0xf bound_ctrl:1
	s_nop 1
	v_add_f32_dpp v228, v228, v228 row_half_mirror row_mask:0xf bank_mask:0xf bound_ctrl:1
	s_nop 1
	v_add_f32_dpp v228, v228, v228 row_mirror row_mask:0xf bank_mask:0xf bound_ctrl:1
	v_mov_b32_e32 v2, v228
	s_nop 1
	v_permlane16_swap_b32 v228, v2
	s_nop 0
	v_add_f32_e32 v228, v228, v2
	v_mov_b32_e32 v2, v228
	s_nop 1
	v_permlane32_swap_b32 v228, v2
	s_nop 0
	v_add_f32_e32 v228, v228, v2
	v_mul_f32_e32 v134, 0x3a000000, v228
	v_pk_add_f32 v[126:127], v[126:127], v[134:135] op_sel_hi:[1,0] neg_lo:[0,1] neg_hi:[0,1]
	v_pk_add_f32 v[128:129], v[128:129], v[134:135] op_sel_hi:[1,0] neg_lo:[0,1] neg_hi:[0,1]
	v_pk_add_f32 v[130:131], v[130:131], v[134:135] op_sel_hi:[1,0] neg_lo:[0,1] neg_hi:[0,1]
	v_pk_add_f32 v[132:133], v[132:133], v[134:135] op_sel_hi:[1,0] neg_lo:[0,1] neg_hi:[0,1]
	v_pk_add_f32 v[240:241], v[240:241], v[134:135] op_sel_hi:[1,0] neg_lo:[0,1] neg_hi:[0,1]
	v_pk_add_f32 v[242:243], v[242:243], v[134:135] op_sel_hi:[1,0] neg_lo:[0,1] neg_hi:[0,1]
	v_pk_add_f32 v[244:245], v[244:245], v[134:135] op_sel_hi:[1,0] neg_lo:[0,1] neg_hi:[0,1]
	v_pk_add_f32 v[246:247], v[246:247], v[134:135] op_sel_hi:[1,0] neg_lo:[0,1] neg_hi:[0,1]
	v_pk_add_f32 v[248:249], v[248:249], v[134:135] op_sel_hi:[1,0] neg_lo:[0,1] neg_hi:[0,1]
	v_pk_add_f32 v[250:251], v[250:251], v[134:135] op_sel_hi:[1,0] neg_lo:[0,1] neg_hi:[0,1]
	v_pk_add_f32 v[32:33], v[32:33], v[134:135] op_sel_hi:[1,0] neg_lo:[0,1] neg_hi:[0,1]
	v_pk_add_f32 v[34:35], v[34:35], v[134:135] op_sel_hi:[1,0] neg_lo:[0,1] neg_hi:[0,1]
	v_pk_add_f32 v[36:37], v[36:37], v[134:135] op_sel_hi:[1,0] neg_lo:[0,1] neg_hi:[0,1]
	v_pk_add_f32 v[38:39], v[38:39], v[134:135] op_sel_hi:[1,0] neg_lo:[0,1] neg_hi:[0,1]
	v_pk_add_f32 v[20:21], v[20:21], v[134:135] op_sel_hi:[1,0] neg_lo:[0,1] neg_hi:[0,1]
	v_pk_add_f32 v[22:23], v[22:23], v[134:135] op_sel_hi:[1,0] neg_lo:[0,1] neg_hi:[0,1]
	v_pk_mul_f32 v[228:229], v[126:127], v[126:127]
	v_pk_fma_f32 v[228:229], v[128:129], v[128:129], v[228:229]
	v_pk_fma_f32 v[228:229], v[130:131], v[130:131], v[228:229]
	v_pk_fma_f32 v[228:229], v[132:133], v[132:133], v[228:229]
	v_pk_fma_f32 v[228:229], v[240:241], v[240:241], v[228:229]
	v_pk_fma_f32 v[228:229], v[242:243], v[242:243], v[228:229]
	v_pk_fma_f32 v[228:229], v[244:245], v[244:245], v[228:229]
	v_pk_fma_f32 v[228:229], v[246:247], v[246:247], v[228:229]
	v_pk_fma_f32 v[228:229], v[248:249], v[248:249], v[228:229]
	v_pk_fma_f32 v[228:229], v[250:251], v[250:251], v[228:229]
	v_pk_fma_f32 v[228:229], v[32:33], v[32:33], v[228:229]
	v_pk_fma_f32 v[228:229], v[34:35], v[34:35], v[228:229]
	v_pk_fma_f32 v[228:229], v[36:37], v[36:37], v[228:229]
	v_pk_fma_f32 v[228:229], v[38:39], v[38:39], v[228:229]
	v_pk_fma_f32 v[228:229], v[20:21], v[20:21], v[228:229]
	v_pk_fma_f32 v[228:229], v[22:23], v[22:23], v[228:229]
	v_add_f32_e32 v228, v228, v229
	s_nop 1
	v_add_f32_dpp v228, v228, v228 quad_perm:[1,0,3,2] row_mask:0xf bank_mask:0xf bound_ctrl:1
	s_nop 1
	v_add_f32_dpp v228, v228, v228 quad_perm:[2,3,0,1] row_mask:0xf bank_mask:0xf bound_ctrl:1
	s_nop 1
	v_add_f32_dpp v228, v228, v228 row_half_mirror row_mask:0xf bank_mask:0xf bound_ctrl:1
	s_nop 1
	v_add_f32_dpp v228, v228, v228 row_mirror row_mask:0xf bank_mask:0xf bound_ctrl:1
	v_mov_b32_e32 v2, v228
	s_nop 1
	v_permlane16_swap_b32 v228, v2
	s_nop 0
	v_add_f32_e32 v228, v228, v2
	v_mov_b32_e32 v2, v228
	s_nop 1
	v_permlane32_swap_b32 v228, v2
	s_nop 0
	v_add_f32_e32 v228, v228, v2
	v_mul_f32_e32 v0, 0x3a000000, v228
	v_add_f32_e32 v0, 0x3727c5ac, v0
	v_rsq_f32_e32 v0, v0
	s_nop 0
	v_pk_mul_f32 v[228:229], v[140:141], v[0:1] op_sel_hi:[1,0]
	v_pk_fma_f32 v[126:127], v[126:127], v[228:229], v[172:173]
	v_pk_mul_f32 v[228:229], v[142:143], v[0:1] op_sel_hi:[1,0]
	v_pk_fma_f32 v[128:129], v[128:129], v[228:229], v[174:175]
	v_pk_mul_f32 v[228:229], v[144:145], v[0:1] op_sel_hi:[1,0]
	v_pk_fma_f32 v[130:131], v[130:131], v[228:229], v[176:177]
	v_pk_mul_f32 v[228:229], v[146:147], v[0:1] op_sel_hi:[1,0]
	v_pk_fma_f32 v[132:133], v[132:133], v[228:229], v[178:179]
	v_pk_mul_f32 v[228:229], v[148:149], v[0:1] op_sel_hi:[1,0]
	v_pk_fma_f32 v[240:241], v[240:241], v[228:229], v[180:181]
	v_pk_mul_f32 v[228:229], v[150:151], v[0:1] op_sel_hi:[1,0]
	v_pk_fma_f32 v[242:243], v[242:243], v[228:229], v[182:183]
	v_pk_mul_f32 v[228:229], v[152:153], v[0:1] op_sel_hi:[1,0]
	v_pk_fma_f32 v[244:245], v[244:245], v[228:229], v[184:185]
	v_pk_mul_f32 v[228:229], v[154:155], v[0:1] op_sel_hi:[1,0]
	v_pk_fma_f32 v[246:247], v[246:247], v[228:229], v[186:187]
	v_pk_mul_f32 v[228:229], v[156:157], v[0:1] op_sel_hi:[1,0]
	v_pk_fma_f32 v[248:249], v[248:249], v[228:229], v[188:189]
	v_pk_mul_f32 v[228:229], v[158:159], v[0:1] op_sel_hi:[1,0]
	v_pk_fma_f32 v[250:251], v[250:251], v[228:229], v[190:191]
	v_pk_mul_f32 v[228:229], v[160:161], v[0:1] op_sel_hi:[1,0]
	v_pk_fma_f32 v[32:33], v[32:33], v[228:229], v[192:193]
	v_pk_mul_f32 v[228:229], v[162:163], v[0:1] op_sel_hi:[1,0]
	v_pk_fma_f32 v[34:35], v[34:35], v[228:229], v[194:195]
	v_pk_mul_f32 v[228:229], v[164:165], v[0:1] op_sel_hi:[1,0]
	v_pk_fma_f32 v[36:37], v[36:37], v[228:229], v[196:197]
	v_pk_mul_f32 v[228:229], v[166:167], v[0:1] op_sel_hi:[1,0]
	v_pk_fma_f32 v[38:39], v[38:39], v[228:229], v[198:199]
	v_pk_mul_f32 v[228:229], v[168:169], v[0:1] op_sel_hi:[1,0]
	v_pk_fma_f32 v[20:21], v[20:21], v[228:229], v[200:201]
	v_pk_mul_f32 v[228:229], v[170:171], v[0:1] op_sel_hi:[1,0]
	v_pk_fma_f32 v[22:23], v[22:23], v[228:229], v[202:203]
	v_cvt_pk_bf16_f32 v110, v126, v127
	v_cvt_pk_bf16_f32 v111, v128, v129
	v_cvt_pk_bf16_f32 v112, v130, v131
	v_cvt_pk_bf16_f32 v113, v132, v133
	v_cvt_pk_bf16_f32 v114, v240, v241
	v_cvt_pk_bf16_f32 v115, v242, v243
	v_cvt_pk_bf16_f32 v116, v244, v245
	v_cvt_pk_bf16_f32 v117, v246, v247
	v_cvt_pk_bf16_f32 v118, v248, v249
	v_cvt_pk_bf16_f32 v119, v250, v251
	v_cvt_pk_bf16_f32 v120, v32, v33
	v_cvt_pk_bf16_f32 v121, v34, v35
	v_cvt_pk_bf16_f32 v122, v36, v37
	v_cvt_pk_bf16_f32 v123, v38, v39
	v_cvt_pk_bf16_f32 v124, v20, v21
	v_cvt_pk_bf16_f32 v125, v22, v23
	global_store_dwordx2 v1, v[110:111], s[90:91] offset:0
	global_store_dwordx2 v1, v[112:113], s[90:91] offset:512
	global_store_dwordx2 v1, v[114:115], s[90:91] offset:1024
	global_store_dwordx2 v1, v[116:117], s[90:91] offset:1536
	global_store_dwordx2 v1, v[118:119], s[90:91] offset:2048
	global_store_dwordx2 v1, v[120:121], s[90:91] offset:2560
	global_store_dwordx2 v1, v[122:123], s[90:91] offset:3072
	global_store_dwordx2 v1, v[124:125], s[90:91] offset:3584
	s_add_u32 s90, s90, 0x800000
	s_addc_u32 s91, s91, 0
	s_waitcnt vmcnt(24)
	v_lshlrev_b32_e32 v126, 16, v24
	v_and_b32_e32 v127, 0xffff0000, v24
	v_lshlrev_b32_e32 v128, 16, v25
	v_and_b32_e32 v129, 0xffff0000, v25
	v_lshlrev_b32_e32 v130, 16, v26
	v_and_b32_e32 v131, 0xffff0000, v26
	v_lshlrev_b32_e32 v132, 16, v27
	v_and_b32_e32 v133, 0xffff0000, v27
	v_lshlrev_b32_e32 v240, 16, v8
	v_and_b32_e32 v241, 0xffff0000, v8
	v_lshlrev_b32_e32 v242, 16, v9
	v_and_b32_e32 v243, 0xffff0000, v9
	v_lshlrev_b32_e32 v244, 16, v10
	v_and_b32_e32 v245, 0xffff0000, v10
	v_lshlrev_b32_e32 v246, 16, v11
	v_and_b32_e32 v247, 0xffff0000, v11
	v_lshlrev_b32_e32 v248, 16, v220
	v_and_b32_e32 v249, 0xffff0000, v220
	v_lshlrev_b32_e32 v250, 16, v221
	v_and_b32_e32 v251, 0xffff0000, v221
	v_lshlrev_b32_e32 v32, 16, v222
	v_and_b32_e32 v33, 0xffff0000, v222
	v_lshlrev_b32_e32 v34, 16, v223
	v_and_b32_e32 v35, 0xffff0000, v223
	v_lshlrev_b32_e32 v36, 16, v224
	v_and_b32_e32 v37, 0xffff0000, v224
	v_lshlrev_b32_e32 v38, 16, v225
	v_and_b32_e32 v39, 0xffff0000, v225
	v_lshlrev_b32_e32 v20, 16, v226
	v_and_b32_e32 v21, 0xffff0000, v226
	v_lshlrev_b32_e32 v22, 16, v227
	v_and_b32_e32 v23, 0xffff0000, v227
	v_pk_add_f32 v[228:229], v[126:127], v[128:129]
	v_pk_add_f32 v[228:229], v[228:229], v[130:131]
	v_pk_add_f32 v[228:229], v[228:229], v[132:133]
	v_pk_add_f32 v[228:229], v[228:229], v[240:241]
	v_pk_add_f32 v[228:229], v[228:229], v[242:243]
	v_pk_add_f32 v[228:229], v[228:229], v[244:245]
	v_pk_add_f32 v[228:229], v[228:229], v[246:247]
	v_pk_add_f32 v[228:229], v[228:229], v[248:249]
	v_pk_add_f32 v[228:229], v[228:229], v[250:251]
	v_pk_add_f32 v[228:229], v[228:229], v[32:33]
	v_pk_add_f32 v[228:229], v[228:229], v[34:35]
	v_pk_add_f32 v[228:229], v[228:229], v[36:37]
	v_pk_add_f32 v[228:229], v[228:229], v[38:39]
	v_pk_add_f32 v[228:229], v[228:229], v[20:21]
	v_pk_add_f32 v[228:229], v[228:229], v[22:23]
	v_add_f32_e32 v228, v228, v229
	s_nop 1
	v_add_f32_dpp v228, v228, v228 quad_perm:[1,0,3,2] row_mask:0xf bank_mask:0xf bound_ctrl:1
	s_nop 1
	v_add_f32_dpp v228, v228, v228 quad_perm:[2,3,0,1] row_mask:0xf bank_mask:0xf bound_ctrl:1
	s_nop 1
	v_add_f32_dpp v228, v228, v228 row_half_mirror row_mask:0xf bank_mask:0xf bound_ctrl:1
	s_nop 1
	v_add_f32_dpp v228, v228, v228 row_mirror row_mask:0xf bank_mask:0xf bound_ctrl:1
	v_mov_b32_e32 v2, v228
	s_nop 1
	v_permlane16_swap_b32 v228, v2
	s_nop 0
	v_add_f32_e32 v228, v228, v2
	v_mov_b32_e32 v2, v228
	s_nop 1
	v_permlane32_swap_b32 v228, v2
	s_nop 0
	v_add_f32_e32 v228, v228, v2
	v_mul_f32_e32 v134, 0x3a000000, v228
	v_pk_add_f32 v[126:127], v[126:127], v[134:135] op_sel_hi:[1,0] neg_lo:[0,1] neg_hi:[0,1]
	v_pk_add_f32 v[128:129], v[128:129], v[134:135] op_sel_hi:[1,0] neg_lo:[0,1] neg_hi:[0,1]
	v_pk_add_f32 v[130:131], v[130:131], v[134:135] op_sel_hi:[1,0] neg_lo:[0,1] neg_hi:[0,1]
	v_pk_add_f32 v[132:133], v[132:133], v[134:135] op_sel_hi:[1,0] neg_lo:[0,1] neg_hi:[0,1]
	v_pk_add_f32 v[240:241], v[240:241], v[134:135] op_sel_hi:[1,0] neg_lo:[0,1] neg_hi:[0,1]
	v_pk_add_f32 v[242:243], v[242:243], v[134:135] op_sel_hi:[1,0] neg_lo:[0,1] neg_hi:[0,1]
	v_pk_add_f32 v[244:245], v[244:245], v[134:135] op_sel_hi:[1,0] neg_lo:[0,1] neg_hi:[0,1]
	v_pk_add_f32 v[246:247], v[246:247], v[134:135] op_sel_hi:[1,0] neg_lo:[0,1] neg_hi:[0,1]
	v_pk_add_f32 v[248:249], v[248:249], v[134:135] op_sel_hi:[1,0] neg_lo:[0,1] neg_hi:[0,1]
	v_pk_add_f32 v[250:251], v[250:251], v[134:135] op_sel_hi:[1,0] neg_lo:[0,1] neg_hi:[0,1]
	v_pk_add_f32 v[32:33], v[32:33], v[134:135] op_sel_hi:[1,0] neg_lo:[0,1] neg_hi:[0,1]
	v_pk_add_f32 v[34:35], v[34:35], v[134:135] op_sel_hi:[1,0] neg_lo:[0,1] neg_hi:[0,1]
	v_pk_add_f32 v[36:37], v[36:37], v[134:135] op_sel_hi:[1,0] neg_lo:[0,1] neg_hi:[0,1]
	v_pk_add_f32 v[38:39], v[38:39], v[134:135] op_sel_hi:[1,0] neg_lo:[0,1] neg_hi:[0,1]
	v_pk_add_f32 v[20:21], v[20:21], v[134:135] op_sel_hi:[1,0] neg_lo:[0,1] neg_hi:[0,1]
	v_pk_add_f32 v[22:23], v[22:23], v[134:135] op_sel_hi:[1,0] neg_lo:[0,1] neg_hi:[0,1]
	v_pk_mul_f32 v[228:229], v[126:127], v[126:127]
	v_pk_fma_f32 v[228:229], v[128:129], v[128:129], v[228:229]
	v_pk_fma_f32 v[228:229], v[130:131], v[130:131], v[228:229]
	v_pk_fma_f32 v[228:229], v[132:133], v[132:133], v[228:229]
	v_pk_fma_f32 v[228:229], v[240:241], v[240:241], v[228:229]
	v_pk_fma_f32 v[228:229], v[242:243], v[242:243], v[228:229]
	v_pk_fma_f32 v[228:229], v[244:245], v[244:245], v[228:229]
	v_pk_fma_f32 v[228:229], v[246:247], v[246:247], v[228:229]
	v_pk_fma_f32 v[228:229], v[248:249], v[248:249], v[228:229]
	v_pk_fma_f32 v[228:229], v[250:251], v[250:251], v[228:229]
	v_pk_fma_f32 v[228:229], v[32:33], v[32:33], v[228:229]
	v_pk_fma_f32 v[228:229], v[34:35], v[34:35], v[228:229]
	v_pk_fma_f32 v[228:229], v[36:37], v[36:37], v[228:229]
	v_pk_fma_f32 v[228:229], v[38:39], v[38:39], v[228:229]
	v_pk_fma_f32 v[228:229], v[20:21], v[20:21], v[228:229]
	v_pk_fma_f32 v[228:229], v[22:23], v[22:23], v[228:229]
	v_add_f32_e32 v228, v228, v229
	s_nop 1
	v_add_f32_dpp v228, v228, v228 quad_perm:[1,0,3,2] row_mask:0xf bank_mask:0xf bound_ctrl:1
	s_nop 1
	v_add_f32_dpp v228, v228, v228 quad_perm:[2,3,0,1] row_mask:0xf bank_mask:0xf bound_ctrl:1
	s_nop 1
	v_add_f32_dpp v228, v228, v228 row_half_mirror row_mask:0xf bank_mask:0xf bound_ctrl:1
	s_nop 1
	v_add_f32_dpp v228, v228, v228 row_mirror row_mask:0xf bank_mask:0xf bound_ctrl:1
	v_mov_b32_e32 v2, v228
	s_nop 1
	v_permlane16_swap_b32 v228, v2
	s_nop 0
	v_add_f32_e32 v228, v228, v2
	v_mov_b32_e32 v2, v228
	s_nop 1
	v_permlane32_swap_b32 v228, v2
	s_nop 0
	v_add_f32_e32 v228, v228, v2
	v_mul_f32_e32 v0, 0x3a000000, v228
	v_add_f32_e32 v0, 0x3727c5ac, v0
	v_rsq_f32_e32 v0, v0
	s_nop 0
	v_pk_mul_f32 v[228:229], v[140:141], v[0:1] op_sel_hi:[1,0]
	v_pk_fma_f32 v[126:127], v[126:127], v[228:229], v[172:173]
	v_pk_mul_f32 v[228:229], v[142:143], v[0:1] op_sel_hi:[1,0]
	v_pk_fma_f32 v[128:129], v[128:129], v[228:229], v[174:175]
	v_pk_mul_f32 v[228:229], v[144:145], v[0:1] op_sel_hi:[1,0]
	v_pk_fma_f32 v[130:131], v[130:131], v[228:229], v[176:177]
	v_pk_mul_f32 v[228:229], v[146:147], v[0:1] op_sel_hi:[1,0]
	v_pk_fma_f32 v[132:133], v[132:133], v[228:229], v[178:179]
	v_pk_mul_f32 v[228:229], v[148:149], v[0:1] op_sel_hi:[1,0]
	v_pk_fma_f32 v[240:241], v[240:241], v[228:229], v[180:181]
	v_pk_mul_f32 v[228:229], v[150:151], v[0:1] op_sel_hi:[1,0]
	v_pk_fma_f32 v[242:243], v[242:243], v[228:229], v[182:183]
	v_pk_mul_f32 v[228:229], v[152:153], v[0:1] op_sel_hi:[1,0]
	v_pk_fma_f32 v[244:245], v[244:245], v[228:229], v[184:185]
	v_pk_mul_f32 v[228:229], v[154:155], v[0:1] op_sel_hi:[1,0]
	v_pk_fma_f32 v[246:247], v[246:247], v[228:229], v[186:187]
	v_pk_mul_f32 v[228:229], v[156:157], v[0:1] op_sel_hi:[1,0]
	v_pk_fma_f32 v[248:249], v[248:249], v[228:229], v[188:189]
	v_pk_mul_f32 v[228:229], v[158:159], v[0:1] op_sel_hi:[1,0]
	v_pk_fma_f32 v[250:251], v[250:251], v[228:229], v[190:191]
	v_pk_mul_f32 v[228:229], v[160:161], v[0:1] op_sel_hi:[1,0]
	v_pk_fma_f32 v[32:33], v[32:33], v[228:229], v[192:193]
	v_pk_mul_f32 v[228:229], v[162:163], v[0:1] op_sel_hi:[1,0]
	v_pk_fma_f32 v[34:35], v[34:35], v[228:229], v[194:195]
	v_pk_mul_f32 v[228:229], v[164:165], v[0:1] op_sel_hi:[1,0]
	v_pk_fma_f32 v[36:37], v[36:37], v[228:229], v[196:197]
	v_pk_mul_f32 v[228:229], v[166:167], v[0:1] op_sel_hi:[1,0]
	v_pk_fma_f32 v[38:39], v[38:39], v[228:229], v[198:199]
	v_pk_mul_f32 v[228:229], v[168:169], v[0:1] op_sel_hi:[1,0]
	v_pk_fma_f32 v[20:21], v[20:21], v[228:229], v[200:201]
	v_pk_mul_f32 v[228:229], v[170:171], v[0:1] op_sel_hi:[1,0]
	v_pk_fma_f32 v[22:23], v[22:23], v[228:229], v[202:203]
	v_cvt_pk_bf16_f32 v24, v126, v127
	v_cvt_pk_bf16_f32 v25, v128, v129
	v_cvt_pk_bf16_f32 v26, v130, v131
	v_cvt_pk_bf16_f32 v27, v132, v133
	v_cvt_pk_bf16_f32 v8, v240, v241
	v_cvt_pk_bf16_f32 v9, v242, v243
	v_cvt_pk_bf16_f32 v10, v244, v245
	v_cvt_pk_bf16_f32 v11, v246, v247
	v_cvt_pk_bf16_f32 v220, v248, v249
	v_cvt_pk_bf16_f32 v221, v250, v251
	v_cvt_pk_bf16_f32 v222, v32, v33
	v_cvt_pk_bf16_f32 v223, v34, v35
	v_cvt_pk_bf16_f32 v224, v36, v37
	v_cvt_pk_bf16_f32 v225, v38, v39
	v_cvt_pk_bf16_f32 v226, v20, v21
	v_cvt_pk_bf16_f32 v227, v22, v23
	global_store_dwordx2 v1, v[24:25], s[90:91] offset:0
	global_store_dwordx2 v1, v[26:27], s[90:91] offset:512
	global_store_dwordx2 v1, v[8:9], s[90:91] offset:1024
	global_store_dwordx2 v1, v[10:11], s[90:91] offset:1536
	global_store_dwordx2 v1, v[220:221], s[90:91] offset:2048
	global_store_dwordx2 v1, v[222:223], s[90:91] offset:2560
	global_store_dwordx2 v1, v[224:225], s[90:91] offset:3072
	global_store_dwordx2 v1, v[226:227], s[90:91] offset:3584
	s_add_u32 s90, s90, 0x800000
	s_addc_u32 s91, s91, 0
	s_waitcnt vmcnt(16)
	v_lshlrev_b32_e32 v126, 16, v204
	v_and_b32_e32 v127, 0xffff0000, v204
	v_lshlrev_b32_e32 v128, 16, v205
	v_and_b32_e32 v129, 0xffff0000, v205
	v_lshlrev_b32_e32 v130, 16, v206
	v_and_b32_e32 v131, 0xffff0000, v206
	v_lshlrev_b32_e32 v132, 16, v207
	v_and_b32_e32 v133, 0xffff0000, v207
	v_lshlrev_b32_e32 v240, 16, v208
	v_and_b32_e32 v241, 0xffff0000, v208
	v_lshlrev_b32_e32 v242, 16, v209
	v_and_b32_e32 v243, 0xffff0000, v209
	v_lshlrev_b32_e32 v244, 16, v210
	v_and_b32_e32 v245, 0xffff0000, v210
	v_lshlrev_b32_e32 v246, 16, v211
	v_and_b32_e32 v247, 0xffff0000, v211
	v_lshlrev_b32_e32 v248, 16, v212
	v_and_b32_e32 v249, 0xffff0000, v212
	v_lshlrev_b32_e32 v250, 16, v213
	v_and_b32_e32 v251, 0xffff0000, v213
	v_lshlrev_b32_e32 v32, 16, v214
	v_and_b32_e32 v33, 0xffff0000, v214
	v_lshlrev_b32_e32 v34, 16, v215
	v_and_b32_e32 v35, 0xffff0000, v215
	v_lshlrev_b32_e32 v36, 16, v216
	v_and_b32_e32 v37, 0xffff0000, v216
	v_lshlrev_b32_e32 v38, 16, v217
	v_and_b32_e32 v39, 0xffff0000, v217
	v_lshlrev_b32_e32 v20, 16, v218
	v_and_b32_e32 v21, 0xffff0000, v218
	v_lshlrev_b32_e32 v22, 16, v219
	v_and_b32_e32 v23, 0xffff0000, v219
	v_pk_add_f32 v[228:229], v[126:127], v[128:129]
	v_pk_add_f32 v[228:229], v[228:229], v[130:131]
	v_pk_add_f32 v[228:229], v[228:229], v[132:133]
	v_pk_add_f32 v[228:229], v[228:229], v[240:241]
	v_pk_add_f32 v[228:229], v[228:229], v[242:243]
	v_pk_add_f32 v[228:229], v[228:229], v[244:245]
	v_pk_add_f32 v[228:229], v[228:229], v[246:247]
	v_pk_add_f32 v[228:229], v[228:229], v[248:249]
	v_pk_add_f32 v[228:229], v[228:229], v[250:251]
	v_pk_add_f32 v[228:229], v[228:229], v[32:33]
	v_pk_add_f32 v[228:229], v[228:229], v[34:35]
	v_pk_add_f32 v[228:229], v[228:229], v[36:37]
	v_pk_add_f32 v[228:229], v[228:229], v[38:39]
	v_pk_add_f32 v[228:229], v[228:229], v[20:21]
	v_pk_add_f32 v[228:229], v[228:229], v[22:23]
	v_add_f32_e32 v228, v228, v229
	s_nop 1
	v_add_f32_dpp v228, v228, v228 quad_perm:[1,0,3,2] row_mask:0xf bank_mask:0xf bound_ctrl:1
	s_nop 1
	v_add_f32_dpp v228, v228, v228 quad_perm:[2,3,0,1] row_mask:0xf bank_mask:0xf bound_ctrl:1
	s_nop 1
	v_add_f32_dpp v228, v228, v228 row_half_mirror row_mask:0xf bank_mask:0xf bound_ctrl:1
	s_nop 1
	v_add_f32_dpp v228, v228, v228 row_mirror row_mask:0xf bank_mask:0xf bound_ctrl:1
	v_mov_b32_e32 v2, v228
	s_nop 1
	v_permlane16_swap_b32 v228, v2
	s_nop 0
	v_add_f32_e32 v228, v228, v2
	v_mov_b32_e32 v2, v228
	s_nop 1
	v_permlane32_swap_b32 v228, v2
	s_nop 0
	v_add_f32_e32 v228, v228, v2
	v_mul_f32_e32 v134, 0x3a000000, v228
	v_pk_add_f32 v[126:127], v[126:127], v[134:135] op_sel_hi:[1,0] neg_lo:[0,1] neg_hi:[0,1]
	v_pk_add_f32 v[128:129], v[128:129], v[134:135] op_sel_hi:[1,0] neg_lo:[0,1] neg_hi:[0,1]
	v_pk_add_f32 v[130:131], v[130:131], v[134:135] op_sel_hi:[1,0] neg_lo:[0,1] neg_hi:[0,1]
	v_pk_add_f32 v[132:133], v[132:133], v[134:135] op_sel_hi:[1,0] neg_lo:[0,1] neg_hi:[0,1]
	v_pk_add_f32 v[240:241], v[240:241], v[134:135] op_sel_hi:[1,0] neg_lo:[0,1] neg_hi:[0,1]
	v_pk_add_f32 v[242:243], v[242:243], v[134:135] op_sel_hi:[1,0] neg_lo:[0,1] neg_hi:[0,1]
	v_pk_add_f32 v[244:245], v[244:245], v[134:135] op_sel_hi:[1,0] neg_lo:[0,1] neg_hi:[0,1]
	v_pk_add_f32 v[246:247], v[246:247], v[134:135] op_sel_hi:[1,0] neg_lo:[0,1] neg_hi:[0,1]
	v_pk_add_f32 v[248:249], v[248:249], v[134:135] op_sel_hi:[1,0] neg_lo:[0,1] neg_hi:[0,1]
	v_pk_add_f32 v[250:251], v[250:251], v[134:135] op_sel_hi:[1,0] neg_lo:[0,1] neg_hi:[0,1]
	v_pk_add_f32 v[32:33], v[32:33], v[134:135] op_sel_hi:[1,0] neg_lo:[0,1] neg_hi:[0,1]
	v_pk_add_f32 v[34:35], v[34:35], v[134:135] op_sel_hi:[1,0] neg_lo:[0,1] neg_hi:[0,1]
	v_pk_add_f32 v[36:37], v[36:37], v[134:135] op_sel_hi:[1,0] neg_lo:[0,1] neg_hi:[0,1]
	v_pk_add_f32 v[38:39], v[38:39], v[134:135] op_sel_hi:[1,0] neg_lo:[0,1] neg_hi:[0,1]
	v_pk_add_f32 v[20:21], v[20:21], v[134:135] op_sel_hi:[1,0] neg_lo:[0,1] neg_hi:[0,1]
	v_pk_add_f32 v[22:23], v[22:23], v[134:135] op_sel_hi:[1,0] neg_lo:[0,1] neg_hi:[0,1]
	v_pk_mul_f32 v[228:229], v[126:127], v[126:127]
	v_pk_fma_f32 v[228:229], v[128:129], v[128:129], v[228:229]
	v_pk_fma_f32 v[228:229], v[130:131], v[130:131], v[228:229]
	v_pk_fma_f32 v[228:229], v[132:133], v[132:133], v[228:229]
	v_pk_fma_f32 v[228:229], v[240:241], v[240:241], v[228:229]
	v_pk_fma_f32 v[228:229], v[242:243], v[242:243], v[228:229]
	v_pk_fma_f32 v[228:229], v[244:245], v[244:245], v[228:229]
	v_pk_fma_f32 v[228:229], v[246:247], v[246:247], v[228:229]
	v_pk_fma_f32 v[228:229], v[248:249], v[248:249], v[228:229]
	v_pk_fma_f32 v[228:229], v[250:251], v[250:251], v[228:229]
	v_pk_fma_f32 v[228:229], v[32:33], v[32:33], v[228:229]
	v_pk_fma_f32 v[228:229], v[34:35], v[34:35], v[228:229]
	v_pk_fma_f32 v[228:229], v[36:37], v[36:37], v[228:229]
	v_pk_fma_f32 v[228:229], v[38:39], v[38:39], v[228:229]
	v_pk_fma_f32 v[228:229], v[20:21], v[20:21], v[228:229]
	v_pk_fma_f32 v[228:229], v[22:23], v[22:23], v[228:229]
	v_add_f32_e32 v228, v228, v229
	s_nop 1
	v_add_f32_dpp v228, v228, v228 quad_perm:[1,0,3,2] row_mask:0xf bank_mask:0xf bound_ctrl:1
	s_nop 1
	v_add_f32_dpp v228, v228, v228 quad_perm:[2,3,0,1] row_mask:0xf bank_mask:0xf bound_ctrl:1
	s_nop 1
	v_add_f32_dpp v228, v228, v228 row_half_mirror row_mask:0xf bank_mask:0xf bound_ctrl:1
	s_nop 1
	v_add_f32_dpp v228, v228, v228 row_mirror row_mask:0xf bank_mask:0xf bound_ctrl:1
	v_mov_b32_e32 v2, v228
	s_nop 1
	v_permlane16_swap_b32 v228, v2
	s_nop 0
	v_add_f32_e32 v228, v228, v2
	v_mov_b32_e32 v2, v228
	s_nop 1
	v_permlane32_swap_b32 v228, v2
	s_nop 0
	v_add_f32_e32 v228, v228, v2
	v_mul_f32_e32 v0, 0x3a000000, v228
	v_add_f32_e32 v0, 0x3727c5ac, v0
	v_rsq_f32_e32 v0, v0
	s_nop 0
	v_pk_mul_f32 v[228:229], v[140:141], v[0:1] op_sel_hi:[1,0]
	v_pk_fma_f32 v[126:127], v[126:127], v[228:229], v[172:173]
	v_pk_mul_f32 v[228:229], v[142:143], v[0:1] op_sel_hi:[1,0]
	v_pk_fma_f32 v[128:129], v[128:129], v[228:229], v[174:175]
	v_pk_mul_f32 v[228:229], v[144:145], v[0:1] op_sel_hi:[1,0]
	v_pk_fma_f32 v[130:131], v[130:131], v[228:229], v[176:177]
	v_pk_mul_f32 v[228:229], v[146:147], v[0:1] op_sel_hi:[1,0]
	v_pk_fma_f32 v[132:133], v[132:133], v[228:229], v[178:179]
	v_pk_mul_f32 v[228:229], v[148:149], v[0:1] op_sel_hi:[1,0]
	v_pk_fma_f32 v[240:241], v[240:241], v[228:229], v[180:181]
	v_pk_mul_f32 v[228:229], v[150:151], v[0:1] op_sel_hi:[1,0]
	v_pk_fma_f32 v[242:243], v[242:243], v[228:229], v[182:183]
	v_pk_mul_f32 v[228:229], v[152:153], v[0:1] op_sel_hi:[1,0]
	v_pk_fma_f32 v[244:245], v[244:245], v[228:229], v[184:185]
	v_pk_mul_f32 v[228:229], v[154:155], v[0:1] op_sel_hi:[1,0]
	v_pk_fma_f32 v[246:247], v[246:247], v[228:229], v[186:187]
	v_pk_mul_f32 v[228:229], v[156:157], v[0:1] op_sel_hi:[1,0]
	v_pk_fma_f32 v[248:249], v[248:249], v[228:229], v[188:189]
	v_pk_mul_f32 v[228:229], v[158:159], v[0:1] op_sel_hi:[1,0]
	v_pk_fma_f32 v[250:251], v[250:251], v[228:229], v[190:191]
	v_pk_mul_f32 v[228:229], v[160:161], v[0:1] op_sel_hi:[1,0]
	v_pk_fma_f32 v[32:33], v[32:33], v[228:229], v[192:193]
	v_pk_mul_f32 v[228:229], v[162:163], v[0:1] op_sel_hi:[1,0]
	v_pk_fma_f32 v[34:35], v[34:35], v[228:229], v[194:195]
	v_pk_mul_f32 v[228:229], v[164:165], v[0:1] op_sel_hi:[1,0]
	v_pk_fma_f32 v[36:37], v[36:37], v[228:229], v[196:197]
	v_pk_mul_f32 v[228:229], v[166:167], v[0:1] op_sel_hi:[1,0]
	v_pk_fma_f32 v[38:39], v[38:39], v[228:229], v[198:199]
	v_pk_mul_f32 v[228:229], v[168:169], v[0:1] op_sel_hi:[1,0]
	v_pk_fma_f32 v[20:21], v[20:21], v[228:229], v[200:201]
	v_pk_mul_f32 v[228:229], v[170:171], v[0:1] op_sel_hi:[1,0]
	v_pk_fma_f32 v[22:23], v[22:23], v[228:229], v[202:203]
	v_cvt_pk_bf16_f32 v204, v126, v127
	v_cvt_pk_bf16_f32 v205, v128, v129
	v_cvt_pk_bf16_f32 v206, v130, v131
	v_cvt_pk_bf16_f32 v207, v132, v133
	v_cvt_pk_bf16_f32 v208, v240, v241
	v_cvt_pk_bf16_f32 v209, v242, v243
	v_cvt_pk_bf16_f32 v210, v244, v245
	v_cvt_pk_bf16_f32 v211, v246, v247
	v_cvt_pk_bf16_f32 v212, v248, v249
	v_cvt_pk_bf16_f32 v213, v250, v251
	v_cvt_pk_bf16_f32 v214, v32, v33
	v_cvt_pk_bf16_f32 v215, v34, v35
	v_cvt_pk_bf16_f32 v216, v36, v37
	v_cvt_pk_bf16_f32 v217, v38, v39
	v_cvt_pk_bf16_f32 v218, v20, v21
	v_cvt_pk_bf16_f32 v219, v22, v23
	global_store_dwordx2 v1, v[204:205], s[90:91] offset:0
	global_store_dwordx2 v1, v[206:207], s[90:91] offset:512
	global_store_dwordx2 v1, v[208:209], s[90:91] offset:1024
	global_store_dwordx2 v1, v[210:211], s[90:91] offset:1536
	global_store_dwordx2 v1, v[212:213], s[90:91] offset:2048
	global_store_dwordx2 v1, v[214:215], s[90:91] offset:2560
	global_store_dwordx2 v1, v[216:217], s[90:91] offset:3072
	global_store_dwordx2 v1, v[218:219], s[90:91] offset:3584
	s_add_u32 s90, s90, 0x800000
	s_addc_u32 s91, s91, 0

.LBB0_1726:
	s_cmp_lt_i32 s30, 11
	s_cselect_b64 s[8:9], -1, 0
	s_and_b64 s[10:11], s[8:9], s[6:7]
	s_andn2_b64 vcc, exec, s[10:11]
	s_cbranch_vccnz .LBB0_1738
	s_load_dwordx4 s[12:15], s[0:1], 0x100
	v_lshl_add_u32 v32, s2, 3, v230
	s_movk_i32 s3, 0x2000
	v_cmp_gt_i32_e32 vcc, s3, v32
	s_and_saveexec_b64 s[16:17], vcc
	s_cbranch_execz .LBB0_1732
	s_load_dwordx4 s[60:63], s[0:1], 0x100
	v_lshl_add_u32 v2, s2, 3, v230
	v_lshlrev_b32_e32 v137, 4, v136
	v_lshlrev_b32_e32 v1, 3, v136
	v_lshl_add_u32 v1, v2, 12, v1
	v_add_u32_e32 v4, 0x1000, v137
	s_add_u32 s88, s28, 0xe600000
	s_addc_u32 s89, s29, 0
	s_add_u32 s90, s28, 0xc500000
	s_addc_u32 s91, s29, 0
	global_load_dwordx2 v[204:205], v1, s[88:89] offset:0
	global_load_dwordx2 v[206:207], v1, s[88:89] offset:512
	global_load_dwordx2 v[208:209], v1, s[88:89] offset:1024
	global_load_dwordx2 v[210:211], v1, s[88:89] offset:1536
	global_load_dwordx2 v[212:213], v1, s[88:89] offset:2048
	global_load_dwordx2 v[214:215], v1, s[88:89] offset:2560
	global_load_dwordx2 v[216:217], v1, s[88:89] offset:3072
	global_load_dwordx2 v[218:219], v1, s[88:89] offset:3584
	s_add_u32 s88, s88, 0x800000
	s_addc_u32 s89, s89, 0
	s_waitcnt lgkmcnt(0)
	global_load_dwordx4 v[140:143], v137, s[60:61] offset:0
	global_load_dwordx4 v[144:147], v137, s[60:61] offset:1024
	global_load_dwordx4 v[148:151], v137, s[60:61] offset:2048
	global_load_dwordx4 v[152:155], v137, s[60:61] offset:3072
	global_load_dwordx4 v[156:159], v4, s[60:61] offset:0
	global_load_dwordx4 v[160:163], v4, s[60:61] offset:1024
	global_load_dwordx4 v[164:167], v4, s[60:61] offset:2048
	global_load_dwordx4 v[168:171], v4, s[60:61] offset:3072
	global_load_dwordx4 v[172:175], v137, s[62:63] offset:0
	global_load_dwordx4 v[176:179], v137, s[62:63] offset:1024
	global_load_dwordx4 v[180:183], v137, s[62:63] offset:2048
	global_load_dwordx4 v[184:187], v137, s[62:63] offset:3072
	global_load_dwordx4 v[188:191], v4, s[62:63] offset:0
	global_load_dwordx4 v[192:195], v4, s[62:63] offset:1024
	global_load_dwordx4 v[196:199], v4, s[62:63] offset:2048
	global_load_dwordx4 v[200:203], v4, s[62:63] offset:3072
	global_load_dwordx2 v[110:111], v1, s[88:89] offset:0
	global_load_dwordx2 v[112:113], v1, s[88:89] offset:512
	global_load_dwordx2 v[114:115], v1, s[88:89] offset:1024
	global_load_dwordx2 v[116:117], v1, s[88:89] offset:1536
	global_load_dwordx2 v[118:119], v1, s[88:89] offset:2048
	global_load_dwordx2 v[120:121], v1, s[88:89] offset:2560
	global_load_dwordx2 v[122:123], v1, s[88:89] offset:3072
	global_load_dwordx2 v[124:125], v1, s[88:89] offset:3584
	s_add_u32 s88, s88, 0x800000
	s_addc_u32 s89, s89, 0
	global_load_dwordx2 v[24:25], v1, s[88:89] offset:0
	global_load_dwordx2 v[26:27], v1, s[88:89] offset:512
	global_load_dwordx2 v[8:9], v1, s[88:89] offset:1024
	global_load_dwordx2 v[10:11], v1, s[88:89] offset:1536
	global_load_dwordx2 v[220:221], v1, s[88:89] offset:2048
	global_load_dwordx2 v[222:223], v1, s[88:89] offset:2560
	global_load_dwordx2 v[224:225], v1, s[88:89] offset:3072
	global_load_dwordx2 v[226:227], v1, s[88:89] offset:3584
	s_add_u32 s88, s88, 0x800000
	s_addc_u32 s89, s89, 0
	s_waitcnt vmcnt(32)
	v_lshlrev_b32_e32 v126, 16, v204
	v_and_b32_e32 v127, 0xffff0000, v204
	v_lshlrev_b32_e32 v128, 16, v205
	v_and_b32_e32 v129, 0xffff0000, v205
	v_lshlrev_b32_e32 v130, 16, v206
	v_and_b32_e32 v131, 0xffff0000, v206
	v_lshlrev_b32_e32 v132, 16, v207
	v_and_b32_e32 v133, 0xffff0000, v207
	v_lshlrev_b32_e32 v240, 16, v208
	v_and_b32_e32 v241, 0xffff0000, v208
	v_lshlrev_b32_e32 v242, 16, v209
	v_and_b32_e32 v243, 0xffff0000, v209
	v_lshlrev_b32_e32 v244, 16, v210
	v_and_b32_e32 v245, 0xffff0000, v210
	v_lshlrev_b32_e32 v246, 16, v211
	v_and_b32_e32 v247, 0xffff0000, v211
	v_lshlrev_b32_e32 v248, 16, v212
	v_and_b32_e32 v249, 0xffff0000, v212
	v_lshlrev_b32_e32 v250, 16, v213
	v_and_b32_e32 v251, 0xffff0000, v213
	v_lshlrev_b32_e32 v32, 16, v214
	v_and_b32_e32 v33, 0xffff0000, v214
	v_lshlrev_b32_e32 v34, 16, v215
	v_and_b32_e32 v35, 0xffff0000, v215
	v_lshlrev_b32_e32 v36, 16, v216
	v_and_b32_e32 v37, 0xffff0000, v216
	v_lshlrev_b32_e32 v38, 16, v217
	v_and_b32_e32 v39, 0xffff0000, v217
	v_lshlrev_b32_e32 v20, 16, v218
	v_and_b32_e32 v21, 0xffff0000, v218
	v_lshlrev_b32_e32 v22, 16, v219
	v_and_b32_e32 v23, 0xffff0000, v219
	v_pk_add_f32 v[228:229], v[126:127], v[128:129]
	v_pk_add_f32 v[228:229], v[228:229], v[130:131]
	v_pk_add_f32 v[228:229], v[228:229], v[132:133]
	v_pk_add_f32 v[228:229], v[228:229], v[240:241]
	v_pk_add_f32 v[228:229], v[228:229], v[242:243]
	v_pk_add_f32 v[228:229], v[228:229], v[244:245]
	v_pk_add_f32 v[228:229], v[228:229], v[246:247]
	v_pk_add_f32 v[228:229], v[228:229], v[248:249]
	v_pk_add_f32 v[228:229], v[228:229], v[250:251]
	v_pk_add_f32 v[228:229], v[228:229], v[32:33]
	v_pk_add_f32 v[228:229], v[228:229], v[34:35]
	v_pk_add_f32 v[228:229], v[228:229], v[36:37]
	v_pk_add_f32 v[228:229], v[228:229], v[38:39]
	v_pk_add_f32 v[228:229], v[228:229], v[20:21]
	v_pk_add_f32 v[228:229], v[228:229], v[22:23]
	v_add_f32_e32 v228, v228, v229
	s_nop 1
	v_add_f32_dpp v228, v228, v228 quad_perm:[1,0,3,2] row_mask:0xf bank_mask:0xf bound_ctrl:1
	s_nop 1
	v_add_f32_dpp v228, v228, v228 quad_perm:[2,3,0,1] row_mask:0xf bank_mask:0xf bound_ctrl:1
	s_nop 1
	v_add_f32_dpp v228, v228, v228 row_half_mirror row_mask:0xf bank_mask:0xf bound_ctrl:1
	s_nop 1
	v_add_f32_dpp v228, v228, v228 row_mirror row_mask:0xf bank_mask:0xf bound_ctrl:1
	v_mov_b32_e32 v2, v228
	s_nop 1
	v_permlane16_swap_b32 v228, v2
	s_nop 0
	v_add_f32_e32 v228, v228, v2
	v_mov_b32_e32 v2, v228
	s_nop 1
	v_permlane32_swap_b32 v228, v2
	s_nop 0
	v_add_f32_e32 v228, v228, v2
	v_mul_f32_e32 v134, 0x3a000000, v228
	v_pk_add_f32 v[126:127], v[126:127], v[134:135] op_sel_hi:[1,0] neg_lo:[0,1] neg_hi:[0,1]
	v_pk_add_f32 v[128:129], v[128:129], v[134:135] op_sel_hi:[1,0] neg_lo:[0,1] neg_hi:[0,1]
	v_pk_add_f32 v[130:131], v[130:131], v[134:135] op_sel_hi:[1,0] neg_lo:[0,1] neg_hi:[0,1]
	v_pk_add_f32 v[132:133], v[132:133], v[134:135] op_sel_hi:[1,0] neg_lo:[0,1] neg_hi:[0,1]
	v_pk_add_f32 v[240:241], v[240:241], v[134:135] op_sel_hi:[1,0] neg_lo:[0,1] neg_hi:[0,1]
	v_pk_add_f32 v[242:243], v[242:243], v[134:135] op_sel_hi:[1,0] neg_lo:[0,1] neg_hi:[0,1]
	v_pk_add_f32 v[244:245], v[244:245], v[134:135] op_sel_hi:[1,0] neg_lo:[0,1] neg_hi:[0,1]
	v_pk_add_f32 v[246:247], v[246:247], v[134:135] op_sel_hi:[1,0] neg_lo:[0,1] neg_hi:[0,1]
	v_pk_add_f32 v[248:249], v[248:249], v[134:135] op_sel_hi:[1,0] neg_lo:[0,1] neg_hi:[0,1]
	v_pk_add_f32 v[250:251], v[250:251], v[134:135] op_sel_hi:[1,0] neg_lo:[0,1] neg_hi:[0,1]
	v_pk_add_f32 v[32:33], v[32:33], v[134:135] op_sel_hi:[1,0] neg_lo:[0,1] neg_hi:[0,1]
	v_pk_add_f32 v[34:35], v[34:35], v[134:135] op_sel_hi:[1,0] neg_lo:[0,1] neg_hi:[0,1]
	v_pk_add_f32 v[36:37], v[36:37], v[134:135] op_sel_hi:[1,0] neg_lo:[0,1] neg_hi:[0,1]
	v_pk_add_f32 v[38:39], v[38:39], v[134:135] op_sel_hi:[1,0] neg_lo:[0,1] neg_hi:[0,1]
	v_pk_add_f32 v[20:21], v[20:21], v[134:135] op_sel_hi:[1,0] neg_lo:[0,1] neg_hi:[0,1]
	v_pk_add_f32 v[22:23], v[22:23], v[134:135] op_sel_hi:[1,0] neg_lo:[0,1] neg_hi:[0,1]
	v_pk_mul_f32 v[228:229], v[126:127], v[126:127]
	v_pk_fma_f32 v[228:229], v[128:129], v[128:129], v[228:229]
	v_pk_fma_f32 v[228:229], v[130:131], v[130:131], v[228:229]
	v_pk_fma_f32 v[228:229], v[132:133], v[132:133], v[228:229]
	v_pk_fma_f32 v[228:229], v[240:241], v[240:241], v[228:229]
	v_pk_fma_f32 v[228:229], v[242:243], v[242:243], v[228:229]
	v_pk_fma_f32 v[228:229], v[244:245], v[244:245], v[228:229]
	v_pk_fma_f32 v[228:229], v[246:247], v[246:247], v[228:229]
	v_pk_fma_f32 v[228:229], v[248:249], v[248:249], v[228:229]
	v_pk_fma_f32 v[228:229], v[250:251], v[250:251], v[228:229]
	v_pk_fma_f32 v[228:229], v[32:33], v[32:33], v[228:229]
	v_pk_fma_f32 v[228:229], v[34:35], v[34:35], v[228:229]
	v_pk_fma_f32 v[228:229], v[36:37], v[36:37], v[228:229]
	v_pk_fma_f32 v[228:229], v[38:39], v[38:39], v[228:229]
	v_pk_fma_f32 v[228:229], v[20:21], v[20:21], v[228:229]
	v_pk_fma_f32 v[228:229], v[22:23], v[22:23], v[228:229]
	v_add_f32_e32 v228, v228, v229
	s_nop 1
	v_add_f32_dpp v228, v228, v228 quad_perm:[1,0,3,2] row_mask:0xf bank_mask:0xf bound_ctrl:1
	s_nop 1
	v_add_f32_dpp v228, v228, v228 quad_perm:[2,3,0,1] row_mask:0xf bank_mask:0xf bound_ctrl:1
	s_nop 1
	v_add_f32_dpp v228, v228, v228 row_half_mirror row_mask:0xf bank_mask:0xf bound_ctrl:1
	s_nop 1
	v_add_f32_dpp v228, v228, v228 row_mirror row_mask:0xf bank_mask:0xf bound_ctrl:1
	v_mov_b32_e32 v2, v228
	s_nop 1
	v_permlane16_swap_b32 v228, v2
	s_nop 0
	v_add_f32_e32 v228, v228, v2
	v_mov_b32_e32 v2, v228
	s_nop 1
	v_permlane32_swap_b32 v228, v2
	s_nop 0
	v_add_f32_e32 v228, v228, v2
	v_mul_f32_e32 v0, 0x3a000000, v228
	v_add_f32_e32 v0, 0x3727c5ac, v0
	v_rsq_f32_e32 v0, v0
	s_waitcnt vmcnt(16)
	v_pk_mul_f32 v[228:229], v[140:141], v[0:1] op_sel_hi:[1,0]
	v_pk_fma_f32 v[126:127], v[126:127], v[228:229], v[172:173]
	v_pk_mul_f32 v[228:229], v[142:143], v[0:1] op_sel_hi:[1,0]
	v_pk_fma_f32 v[128:129], v[128:129], v[228:229], v[174:175]
	v_pk_mul_f32 v[228:229], v[144:145], v[0:1] op_sel_hi:[1,0]
	v_pk_fma_f32 v[130:131], v[130:131], v[228:229], v[176:177]
	v_pk_mul_f32 v[228:229], v[146:147], v[0:1] op_sel_hi:[1,0]
	v_pk_fma_f32 v[132:133], v[132:133], v[228:229], v[178:179]
	v_pk_mul_f32 v[228:229], v[148:149], v[0:1] op_sel_hi:[1,0]
	v_pk_fma_f32 v[240:241], v[240:241], v[228:229], v[180:181]
	v_pk_mul_f32 v[228:229], v[150:151], v[0:1] op_sel_hi:[1,0]
	v_pk_fma_f32 v[242:243], v[242:243], v[228:229], v[182:183]
	v_pk_mul_f32 v[228:229], v[152:153], v[0:1] op_sel_hi:[1,0]
	v_pk_fma_f32 v[244:245], v[244:245], v[228:229], v[184:185]
	v_pk_mul_f32 v[228:229], v[154:155], v[0:1] op_sel_hi:[1,0]
	v_pk_fma_f32 v[246:247], v[246:247], v[228:229], v[186:187]
	v_pk_mul_f32 v[228:229], v[156:157], v[0:1] op_sel_hi:[1,0]
	v_pk_fma_f32 v[248:249], v[248:249], v[228:229], v[188:189]
	v_pk_mul_f32 v[228:229], v[158:159], v[0:1] op_sel_hi:[1,0]
	v_pk_fma_f32 v[250:251], v[250:251], v[228:229], v[190:191]
	v_pk_mul_f32 v[228:229], v[160:161], v[0:1] op_sel_hi:[1,0]
	v_pk_fma_f32 v[32:33], v[32:33], v[228:229], v[192:193]
	v_pk_mul_f32 v[228:229], v[162:163], v[0:1] op_sel_hi:[1,0]
	v_pk_fma_f32 v[34:35], v[34:35], v[228:229], v[194:195]
	v_pk_mul_f32 v[228:229], v[164:165], v[0:1] op_sel_hi:[1,0]
	v_pk_fma_f32 v[36:37], v[36:37], v[228:229], v[196:197]
	v_pk_mul_f32 v[228:229], v[166:167], v[0:1] op_sel_hi:[1,0]
	v_pk_fma_f32 v[38:39], v[38:39], v[228:229], v[198:199]
	v_pk_mul_f32 v[228:229], v[168:169], v[0:1] op_sel_hi:[1,0]
	v_pk_fma_f32 v[20:21], v[20:21], v[228:229], v[200:201]
	v_pk_mul_f32 v[228:229], v[170:171], v[0:1] op_sel_hi:[1,0]
	v_pk_fma_f32 v[22:23], v[22:23], v[228:229], v[202:203]
	v_cvt_pk_bf16_f32 v204, v126, v127
	v_cvt_pk_bf16_f32 v205, v128, v129
	v_cvt_pk_bf16_f32 v206, v130, v131
	v_cvt_pk_bf16_f32 v207, v132, v133
	v_cvt_pk_bf16_f32 v208, v240, v241
	v_cvt_pk_bf16_f32 v209, v242, v243
	v_cvt_pk_bf16_f32 v210, v244, v245
	v_cvt_pk_bf16_f32 v211, v246, v247
	v_cvt_pk_bf16_f32 v212, v248, v249
	v_cvt_pk_bf16_f32 v213, v250, v251
	v_cvt_pk_bf16_f32 v214, v32, v33
	v_cvt_pk_bf16_f32 v215, v34, v35
	v_cvt_pk_bf16_f32 v216, v36, v37
	v_cvt_pk_bf16_f32 v217, v38, v39
	v_cvt_pk_bf16_f32 v218, v20, v21
	v_cvt_pk_bf16_f32 v219, v22, v23
	global_store_dwordx2 v1, v[204:205], s[90:91] offset:0
	global_store_dwordx2 v1, v[206:207], s[90:91] offset:512
	global_store_dwordx2 v1, v[208:209], s[90:91] offset:1024
	global_store_dwordx2 v1, v[210:211], s[90:91] offset:1536
	global_store_dwordx2 v1, v[212:213], s[90:91] offset:2048
	global_store_dwordx2 v1, v[214:215], s[90:91] offset:2560
	global_store_dwordx2 v1, v[216:217], s[90:91] offset:3072
	global_store_dwordx2 v1, v[218:219], s[90:91] offset:3584
	s_add_u32 s90, s90, 0x800000
	s_addc_u32 s91, s91, 0
	global_load_dwordx2 v[204:205], v1, s[88:89] offset:0
	global_load_dwordx2 v[206:207], v1, s[88:89] offset:512
	global_load_dwordx2 v[208:209], v1, s[88:89] offset:1024
	global_load_dwordx2 v[210:211], v1, s[88:89] offset:1536
	global_load_dwordx2 v[212:213], v1, s[88:89] offset:2048
	global_load_dwordx2 v[214:215], v1, s[88:89] offset:2560
	global_load_dwordx2 v[216:217], v1, s[88:89] offset:3072
	global_load_dwordx2 v[218:219], v1, s[88:89] offset:3584
	s_add_u32 s88, s88, 0x800000
	s_addc_u32 s89, s89, 0
	s_waitcnt vmcnt(24)
	v_lshlrev_b32_e32 v126, 16, v110
	v_and_b32_e32 v127, 0xffff0000, v110
	v_lshlrev_b32_e32 v128, 16, v111
	v_and_b32_e32 v129, 0xffff0000, v111
	v_lshlrev_b32_e32 v130, 16, v112
	v_and_b32_e32 v131, 0xffff0000, v112
	v_lshlrev_b32_e32 v132, 16, v113
	v_and_b32_e32 v133, 0xffff0000, v113
	v_lshlrev_b32_e32 v240, 16, v114
	v_and_b32_e32 v241, 0xffff0000, v114
	v_lshlrev_b32_e32 v242, 16, v115
	v_and_b32_e32 v243, 0xffff0000, v115
	v_lshlrev_b32_e32 v244, 16, v116
	v_and_b32_e32 v245, 0xffff0000, v116
	v_lshlrev_b32_e32 v246, 16, v117
	v_and_b32_e32 v247, 0xffff0000, v117
	v_lshlrev_b32_e32 v248, 16, v118
	v_and_b32_e32 v249, 0xffff0000, v118
	v_lshlrev_b32_e32 v250, 16, v119
	v_and_b32_e32 v251, 0xffff0000, v119
	v_lshlrev_b32_e32 v32, 16, v120
	v_and_b32_e32 v33, 0xffff0000, v120
	v_lshlrev_b32_e32 v34, 16, v121
	v_and_b32_e32 v35, 0xffff0000, v121
	v_lshlrev_b32_e32 v36, 16, v122
	v_and_b32_e32 v37, 0xffff0000, v122
	v_lshlrev_b32_e32 v38, 16, v123
	v_and_b32_e32 v39, 0xffff0000, v123
	v_lshlrev_b32_e32 v20, 16, v124
	v_and_b32_e32 v21, 0xffff0000, v124
	v_lshlrev_b32_e32 v22, 16, v125
	v_and_b32_e32 v23, 0xffff0000, v125
	v_pk_add_f32 v[228:229], v[126:127], v[128:129]
	v_pk_add_f32 v[228:229], v[228:229], v[130:131]
	v_pk_add_f32 v[228:229], v[228:229], v[132:133]
	v_pk_add_f32 v[228:229], v[228:229], v[240:241]
	v_pk_add_f32 v[228:229], v[228:229], v[242:243]
	v_pk_add_f32 v[228:229], v[228:229], v[244:245]
	v_pk_add_f32 v[228:229], v[228:229], v[246:247]
	v_pk_add_f32 v[228:229], v[228:229], v[248:249]
	v_pk_add_f32 v[228:229], v[228:229], v[250:251]
	v_pk_add_f32 v[228:229], v[228:229], v[32:33]
	v_pk_add_f32 v[228:229], v[228:229], v[34:35]
	v_pk_add_f32 v[228:229], v[228:229], v[36:37]
	v_pk_add_f32 v[228:229], v[228:229], v[38:39]
	v_pk_add_f32 v[228:229], v[228:229], v[20:21]
	v_pk_add_f32 v[228:229], v[228:229], v[22:23]
	v_add_f32_e32 v228, v228, v229
	s_nop 1
	v_add_f32_dpp v228, v228, v228 quad_perm:[1,0,3,2] row_mask:0xf bank_mask:0xf bound_ctrl:1
	s_nop 1
	v_add_f32_dpp v228, v228, v228 quad_perm:[2,3,0,1] row_mask:0xf bank_mask:0xf bound_ctrl:1
	s_nop 1
	v_add_f32_dpp v228, v228, v228 row_half_mirror row_mask:0xf bank_mask:0xf bound_ctrl:1
	s_nop 1
	v_add_f32_dpp v228, v228, v228 row_mirror row_mask:0xf bank_mask:0xf bound_ctrl:1
	v_mov_b32_e32 v2, v228
	s_nop 1
	v_permlane16_swap_b32 v228, v2
	s_nop 0
	v_add_f32_e32 v228, v228, v2
	v_mov_b32_e32 v2, v228
	s_nop 1
	v_permlane32_swap_b32 v228, v2
	s_nop 0
	v_add_f32_e32 v228, v228, v2
	v_mul_f32_e32 v134, 0x3a000000, v228
	v_pk_add_f32 v[126:127], v[126:127], v[134:135] op_sel_hi:[1,0] neg_lo:[0,1] neg_hi:[0,1]
	v_pk_add_f32 v[128:129], v[128:129], v[134:135] op_sel_hi:[1,0] neg_lo:[0,1] neg_hi:[0,1]
	v_pk_add_f32 v[130:131], v[130:131], v[134:135] op_sel_hi:[1,0] neg_lo:[0,1] neg_hi:[0,1]
	v_pk_add_f32 v[132:133], v[132:133], v[134:135] op_sel_hi:[1,0] neg_lo:[0,1] neg_hi:[0,1]
	v_pk_add_f32 v[240:241], v[240:241], v[134:135] op_sel_hi:[1,0] neg_lo:[0,1] neg_hi:[0,1]
	v_pk_add_f32 v[242:243], v[242:243], v[134:135] op_sel_hi:[1,0] neg_lo:[0,1] neg_hi:[0,1]
	v_pk_add_f32 v[244:245], v[244:245], v[134:135] op_sel_hi:[1,0] neg_lo:[0,1] neg_hi:[0,1]
	v_pk_add_f32 v[246:247], v[246:247], v[134:135] op_sel_hi:[1,0] neg_lo:[0,1] neg_hi:[0,1]
	v_pk_add_f32 v[248:249], v[248:249], v[134:135] op_sel_hi:[1,0] neg_lo:[0,1] neg_hi:[0,1]
	v_pk_add_f32 v[250:251], v[250:251], v[134:135] op_sel_hi:[1,0] neg_lo:[0,1] neg_hi:[0,1]
	v_pk_add_f32 v[32:33], v[32:33], v[134:135] op_sel_hi:[1,0] neg_lo:[0,1] neg_hi:[0,1]
	v_pk_add_f32 v[34:35], v[34:35], v[134:135] op_sel_hi:[1,0] neg_lo:[0,1] neg_hi:[0,1]
	v_pk_add_f32 v[36:37], v[36:37], v[134:135] op_sel_hi:[1,0] neg_lo:[0,1] neg_hi:[0,1]
	v_pk_add_f32 v[38:39], v[38:39], v[134:135] op_sel_hi:[1,0] neg_lo:[0,1] neg_hi:[0,1]
	v_pk_add_f32 v[20:21], v[20:21], v[134:135] op_sel_hi:[1,0] neg_lo:[0,1] neg_hi:[0,1]
	v_pk_add_f32 v[22:23], v[22:23], v[134:135] op_sel_hi:[1,0] neg_lo:[0,1] neg_hi:[0,1]
	v_pk_mul_f32 v[228:229], v[126:127], v[126:127]
	v_pk_fma_f32 v[228:229], v[128:129], v[128:129], v[228:229]
	v_pk_fma_f32 v[228:229], v[130:131], v[130:131], v[228:229]
	v_pk_fma_f32 v[228:229], v[132:133], v[132:133], v[228:229]
	v_pk_fma_f32 v[228:229], v[240:241], v[240:241], v[228:229]
	v_pk_fma_f32 v[228:229], v[242:243], v[242:243], v[228:229]
	v_pk_fma_f32 v[228:229], v[244:245], v[244:245], v[228:229]
	v_pk_fma_f32 v[228:229], v[246:247], v[246:247], v[228:229]
	v_pk_fma_f32 v[228:229], v[248:249], v[248:249], v[228:229]
	v_pk_fma_f32 v[228:229], v[250:251], v[250:251], v[228:229]
	v_pk_fma_f32 v[228:229], v[32:33], v[32:33], v[228:229]
	v_pk_fma_f32 v[228:229], v[34:35], v[34:35], v[228:229]
	v_pk_fma_f32 v[228:229], v[36:37], v[36:37], v[228:229]
	v_pk_fma_f32 v[228:229], v[38:39], v[38:39], v[228:229]
	v_pk_fma_f32 v[228:229], v[20:21], v[20:21], v[228:229]
	v_pk_fma_f32 v[228:229], v[22:23], v[22:23], v[228:229]
	v_add_f32_e32 v228, v228, v229
	s_nop 1
	v_add_f32_dpp v228, v228, v228 quad_perm:[1,0,3,2] row_mask:0xf bank_mask:0xf bound_ctrl:1
	s_nop 1
	v_add_f32_dpp v228, v228, v228 quad_perm:[2,3,0,1] row_mask:0xf bank_mask:0xf bound_ctrl:1
	s_nop 1
	v_add_f32_dpp v228, v228, v228 row_half_mirror row_mask:0xf bank_mask:0xf bound_ctrl:1
	s_nop 1
	v_add_f32_dpp v228, v228, v228 row_mirror row_mask:0xf bank_mask:0xf bound_ctrl:1
	v_mov_b32_e32 v2, v228
	s_nop 1
	v_permlane16_swap_b32 v228, v2
	s_nop 0
	v_add_f32_e32 v228, v228, v2
	v_mov_b32_e32 v2, v228
	s_nop 1
	v_permlane32_swap_b32 v228, v2
	s_nop 0
	v_add_f32_e32 v228, v228, v2
	v_mul_f32_e32 v0, 0x3a000000, v228
	v_add_f32_e32 v0, 0x3727c5ac, v0
	v_rsq_f32_e32 v0, v0
	s_nop 0
	v_pk_mul_f32 v[228:229], v[140:141], v[0:1] op_sel_hi:[1,0]
	v_pk_fma_f32 v[126:127], v[126:127], v[228:229], v[172:173]
	v_pk_mul_f32 v[228:229], v[142:143], v[0:1] op_sel_hi:[1,0]
	v_pk_fma_f32 v[128:129], v[128:129], v[228:229], v[174:175]
	v_pk_mul_f32 v[228:229], v[144:145], v[0:1] op_sel_hi:[1,0]
	v_pk_fma_f32 v[130:131], v[130:131], v[228:229], v[176:177]
	v_pk_mul_f32 v[228:229], v[146:147], v[0:1] op_sel_hi:[1,0]
	v_pk_fma_f32 v[132:133], v[132:133], v[228:229], v[178:179]
	v_pk_mul_f32 v[228:229], v[148:149], v[0:1] op_sel_hi:[1,0]
	v_pk_fma_f32 v[240:241], v[240:241], v[228:229], v[180:181]
	v_pk_mul_f32 v[228:229], v[150:151], v[0:1] op_sel_hi:[1,0]
	v_pk_fma_f32 v[242:243], v[242:243], v[228:229], v[182:183]
	v_pk_mul_f32 v[228:229], v[152:153], v[0:1] op_sel_hi:[1,0]
	v_pk_fma_f32 v[244:245], v[244:245], v[228:229], v[184:185]
	v_pk_mul_f32 v[228:229], v[154:155], v[0:1] op_sel_hi:[1,0]
	v_pk_fma_f32 v[246:247], v[246:247], v[228:229], v[186:187]
	v_pk_mul_f32 v[228:229], v[156:157], v[0:1] op_sel_hi:[1,0]
	v_pk_fma_f32 v[248:249], v[248:249], v[228:229], v[188:189]
	v_pk_mul_f32 v[228:229], v[158:159], v[0:1] op_sel_hi:[1,0]
	v_pk_fma_f32 v[250:251], v[250:251], v[228:229], v[190:191]
	v_pk_mul_f32 v[228:229], v[160:161], v[0:1] op_sel_hi:[1,0]
	v_pk_fma_f32 v[32:33], v[32:33], v[228:229], v[192:193]
	v_pk_mul_f32 v[228:229], v[162:163], v[0:1] op_sel_hi:[1,0]
	v_pk_fma_f32 v[34:35], v[34:35], v[228:229], v[194:195]
	v_pk_mul_f32 v[228:229], v[164:165], v[0:1] op_sel_hi:[1,0]
	v_pk_fma_f32 v[36:37], v[36:37], v[228:229], v[196:197]
	v_pk_mul_f32 v[228:229], v[166:167], v[0:1] op_sel_hi:[1,0]
	v_pk_fma_f32 v[38:39], v[38:39], v[228:229], v[198:199]
	v_pk_mul_f32 v[228:229], v[168:169], v[0:1] op_sel_hi:[1,0]
	v_pk_fma_f32 v[20:21], v[20:21], v[228:229], v[200:201]
	v_pk_mul_f32 v[228:229], v[170:171], v[0:1] op_sel_hi:[1,0]
	v_pk_fma_f32 v[22:23], v[22:23], v[228:229], v[202:203]
	v_cvt_pk_bf16_f32 v110, v126, v127
	v_cvt_pk_bf16_f32 v111, v128, v129
	v_cvt_pk_bf16_f32 v112, v130, v131
	v_cvt_pk_bf16_f32 v113, v132, v133
	v_cvt_pk_bf16_f32 v114, v240, v241
	v_cvt_pk_bf16_f32 v115, v242, v243
	v_cvt_pk_bf16_f32 v116, v244, v245
	v_cvt_pk_bf16_f32 v117, v246, v247
	v_cvt_pk_bf16_f32 v118, v248, v249
	v_cvt_pk_bf16_f32 v119, v250, v251
	v_cvt_pk_bf16_f32 v120, v32, v33
	v_cvt_pk_bf16_f32 v121, v34, v35
	v_cvt_pk_bf16_f32 v122, v36, v37
	v_cvt_pk_bf16_f32 v123, v38, v39
	v_cvt_pk_bf16_f32 v124, v20, v21
	v_cvt_pk_bf16_f32 v125, v22, v23
	global_store_dwordx2 v1, v[110:111], s[90:91] offset:0
	global_store_dwordx2 v1, v[112:113], s[90:91] offset:512
	global_store_dwordx2 v1, v[114:115], s[90:91] offset:1024
	global_store_dwordx2 v1, v[116:117], s[90:91] offset:1536
	global_store_dwordx2 v1, v[118:119], s[90:91] offset:2048
	global_store_dwordx2 v1, v[120:121], s[90:91] offset:2560
	global_store_dwordx2 v1, v[122:123], s[90:91] offset:3072
	global_store_dwordx2 v1, v[124:125], s[90:91] offset:3584
	s_add_u32 s90, s90, 0x800000
	s_addc_u32 s91, s91, 0
	s_waitcnt vmcnt(24)
	v_lshlrev_b32_e32 v126, 16, v24
	v_and_b32_e32 v127, 0xffff0000, v24
	v_lshlrev_b32_e32 v128, 16, v25
	v_and_b32_e32 v129, 0xffff0000, v25
	v_lshlrev_b32_e32 v130, 16, v26
	v_and_b32_e32 v131, 0xffff0000, v26
	v_lshlrev_b32_e32 v132, 16, v27
	v_and_b32_e32 v133, 0xffff0000, v27
	v_lshlrev_b32_e32 v240, 16, v8
	v_and_b32_e32 v241, 0xffff0000, v8
	v_lshlrev_b32_e32 v242, 16, v9
	v_and_b32_e32 v243, 0xffff0000, v9
	v_lshlrev_b32_e32 v244, 16, v10
	v_and_b32_e32 v245, 0xffff0000, v10
	v_lshlrev_b32_e32 v246, 16, v11
	v_and_b32_e32 v247, 0xffff0000, v11
	v_lshlrev_b32_e32 v248, 16, v220
	v_and_b32_e32 v249, 0xffff0000, v220
	v_lshlrev_b32_e32 v250, 16, v221
	v_and_b32_e32 v251, 0xffff0000, v221
	v_lshlrev_b32_e32 v32, 16, v222
	v_and_b32_e32 v33, 0xffff0000, v222
	v_lshlrev_b32_e32 v34, 16, v223
	v_and_b32_e32 v35, 0xffff0000, v223
	v_lshlrev_b32_e32 v36, 16, v224
	v_and_b32_e32 v37, 0xffff0000, v224
	v_lshlrev_b32_e32 v38, 16, v225
	v_and_b32_e32 v39, 0xffff0000, v225
	v_lshlrev_b32_e32 v20, 16, v226
	v_and_b32_e32 v21, 0xffff0000, v226
	v_lshlrev_b32_e32 v22, 16, v227
	v_and_b32_e32 v23, 0xffff0000, v227
	v_pk_add_f32 v[228:229], v[126:127], v[128:129]
	v_pk_add_f32 v[228:229], v[228:229], v[130:131]
	v_pk_add_f32 v[228:229], v[228:229], v[132:133]
	v_pk_add_f32 v[228:229], v[228:229], v[240:241]
	v_pk_add_f32 v[228:229], v[228:229], v[242:243]
	v_pk_add_f32 v[228:229], v[228:229], v[244:245]
	v_pk_add_f32 v[228:229], v[228:229], v[246:247]
	v_pk_add_f32 v[228:229], v[228:229], v[248:249]
	v_pk_add_f32 v[228:229], v[228:229], v[250:251]
	v_pk_add_f32 v[228:229], v[228:229], v[32:33]
	v_pk_add_f32 v[228:229], v[228:229], v[34:35]
	v_pk_add_f32 v[228:229], v[228:229], v[36:37]
	v_pk_add_f32 v[228:229], v[228:229], v[38:39]
	v_pk_add_f32 v[228:229], v[228:229], v[20:21]
	v_pk_add_f32 v[228:229], v[228:229], v[22:23]
	v_add_f32_e32 v228, v228, v229
	s_nop 1
	v_add_f32_dpp v228, v228, v228 quad_perm:[1,0,3,2] row_mask:0xf bank_mask:0xf bound_ctrl:1
	s_nop 1
	v_add_f32_dpp v228, v228, v228 quad_perm:[2,3,0,1] row_mask:0xf bank_mask:0xf bound_ctrl:1
	s_nop 1
	v_add_f32_dpp v228, v228, v228 row_half_mirror row_mask:0xf bank_mask:0xf bound_ctrl:1
	s_nop 1
	v_add_f32_dpp v228, v228, v228 row_mirror row_mask:0xf bank_mask:0xf bound_ctrl:1
	v_mov_b32_e32 v2, v228
	s_nop 1
	v_permlane16_swap_b32 v228, v2
	s_nop 0
	v_add_f32_e32 v228, v228, v2
	v_mov_b32_e32 v2, v228
	s_nop 1
	v_permlane32_swap_b32 v228, v2
	s_nop 0
	v_add_f32_e32 v228, v228, v2
	v_mul_f32_e32 v134, 0x3a000000, v228
	v_pk_add_f32 v[126:127], v[126:127], v[134:135] op_sel_hi:[1,0] neg_lo:[0,1] neg_hi:[0,1]
	v_pk_add_f32 v[128:129], v[128:129], v[134:135] op_sel_hi:[1,0] neg_lo:[0,1] neg_hi:[0,1]
	v_pk_add_f32 v[130:131], v[130:131], v[134:135] op_sel_hi:[1,0] neg_lo:[0,1] neg_hi:[0,1]
	v_pk_add_f32 v[132:133], v[132:133], v[134:135] op_sel_hi:[1,0] neg_lo:[0,1] neg_hi:[0,1]
	v_pk_add_f32 v[240:241], v[240:241], v[134:135] op_sel_hi:[1,0] neg_lo:[0,1] neg_hi:[0,1]
	v_pk_add_f32 v[242:243], v[242:243], v[134:135] op_sel_hi:[1,0] neg_lo:[0,1] neg_hi:[0,1]
	v_pk_add_f32 v[244:245], v[244:245], v[134:135] op_sel_hi:[1,0] neg_lo:[0,1] neg_hi:[0,1]
	v_pk_add_f32 v[246:247], v[246:247], v[134:135] op_sel_hi:[1,0] neg_lo:[0,1] neg_hi:[0,1]
	v_pk_add_f32 v[248:249], v[248:249], v[134:135] op_sel_hi:[1,0] neg_lo:[0,1] neg_hi:[0,1]
	v_pk_add_f32 v[250:251], v[250:251], v[134:135] op_sel_hi:[1,0] neg_lo:[0,1] neg_hi:[0,1]
	v_pk_add_f32 v[32:33], v[32:33], v[134:135] op_sel_hi:[1,0] neg_lo:[0,1] neg_hi:[0,1]
	v_pk_add_f32 v[34:35], v[34:35], v[134:135] op_sel_hi:[1,0] neg_lo:[0,1] neg_hi:[0,1]
	v_pk_add_f32 v[36:37], v[36:37], v[134:135] op_sel_hi:[1,0] neg_lo:[0,1] neg_hi:[0,1]
	v_pk_add_f32 v[38:39], v[38:39], v[134:135] op_sel_hi:[1,0] neg_lo:[0,1] neg_hi:[0,1]
	v_pk_add_f32 v[20:21], v[20:21], v[134:135] op_sel_hi:[1,0] neg_lo:[0,1] neg_hi:[0,1]
	v_pk_add_f32 v[22:23], v[22:23], v[134:135] op_sel_hi:[1,0] neg_lo:[0,1] neg_hi:[0,1]
	v_pk_mul_f32 v[228:229], v[126:127], v[126:127]
	v_pk_fma_f32 v[228:229], v[128:129], v[128:129], v[228:229]
	v_pk_fma_f32 v[228:229], v[130:131], v[130:131], v[228:229]
	v_pk_fma_f32 v[228:229], v[132:133], v[132:133], v[228:229]
	v_pk_fma_f32 v[228:229], v[240:241], v[240:241], v[228:229]
	v_pk_fma_f32 v[228:229], v[242:243], v[242:243], v[228:229]
	v_pk_fma_f32 v[228:229], v[244:245], v[244:245], v[228:229]
	v_pk_fma_f32 v[228:229], v[246:247], v[246:247], v[228:229]
	v_pk_fma_f32 v[228:229], v[248:249], v[248:249], v[228:229]
	v_pk_fma_f32 v[228:229], v[250:251], v[250:251], v[228:229]
	v_pk_fma_f32 v[228:229], v[32:33], v[32:33], v[228:229]
	v_pk_fma_f32 v[228:229], v[34:35], v[34:35], v[228:229]
	v_pk_fma_f32 v[228:229], v[36:37], v[36:37], v[228:229]
	v_pk_fma_f32 v[228:229], v[38:39], v[38:39], v[228:229]
	v_pk_fma_f32 v[228:229], v[20:21], v[20:21], v[228:229]
	v_pk_fma_f32 v[228:229], v[22:23], v[22:23], v[228:229]
	v_add_f32_e32 v228, v228, v229
	s_nop 1
	v_add_f32_dpp v228, v228, v228 quad_perm:[1,0,3,2] row_mask:0xf bank_mask:0xf bound_ctrl:1
	s_nop 1
	v_add_f32_dpp v228, v228, v228 quad_perm:[2,3,0,1] row_mask:0xf bank_mask:0xf bound_ctrl:1
	s_nop 1
	v_add_f32_dpp v228, v228, v228 row_half_mirror row_mask:0xf bank_mask:0xf bound_ctrl:1
	s_nop 1
	v_add_f32_dpp v228, v228, v228 row_mirror row_mask:0xf bank_mask:0xf bound_ctrl:1
	v_mov_b32_e32 v2, v228
	s_nop 1
	v_permlane16_swap_b32 v228, v2
	s_nop 0
	v_add_f32_e32 v228, v228, v2
	v_mov_b32_e32 v2, v228
	s_nop 1
	v_permlane32_swap_b32 v228, v2
	s_nop 0
	v_add_f32_e32 v228, v228, v2
	v_mul_f32_e32 v0, 0x3a000000, v228
	v_add_f32_e32 v0, 0x3727c5ac, v0
	v_rsq_f32_e32 v0, v0
	s_nop 0
	v_pk_mul_f32 v[228:229], v[140:141], v[0:1] op_sel_hi:[1,0]
	v_pk_fma_f32 v[126:127], v[126:127], v[228:229], v[172:173]
	v_pk_mul_f32 v[228:229], v[142:143], v[0:1] op_sel_hi:[1,0]
	v_pk_fma_f32 v[128:129], v[128:129], v[228:229], v[174:175]
	v_pk_mul_f32 v[228:229], v[144:145], v[0:1] op_sel_hi:[1,0]
	v_pk_fma_f32 v[130:131], v[130:131], v[228:229], v[176:177]
	v_pk_mul_f32 v[228:229], v[146:147], v[0:1] op_sel_hi:[1,0]
	v_pk_fma_f32 v[132:133], v[132:133], v[228:229], v[178:179]
	v_pk_mul_f32 v[228:229], v[148:149], v[0:1] op_sel_hi:[1,0]
	v_pk_fma_f32 v[240:241], v[240:241], v[228:229], v[180:181]
	v_pk_mul_f32 v[228:229], v[150:151], v[0:1] op_sel_hi:[1,0]
	v_pk_fma_f32 v[242:243], v[242:243], v[228:229], v[182:183]
	v_pk_mul_f32 v[228:229], v[152:153], v[0:1] op_sel_hi:[1,0]
	v_pk_fma_f32 v[244:245], v[244:245], v[228:229], v[184:185]
	v_pk_mul_f32 v[228:229], v[154:155], v[0:1] op_sel_hi:[1,0]
	v_pk_fma_f32 v[246:247], v[246:247], v[228:229], v[186:187]
	v_pk_mul_f32 v[228:229], v[156:157], v[0:1] op_sel_hi:[1,0]
	v_pk_fma_f32 v[248:249], v[248:249], v[228:229], v[188:189]
	v_pk_mul_f32 v[228:229], v[158:159], v[0:1] op_sel_hi:[1,0]
	v_pk_fma_f32 v[250:251], v[250:251], v[228:229], v[190:191]
	v_pk_mul_f32 v[228:229], v[160:161], v[0:1] op_sel_hi:[1,0]
	v_pk_fma_f32 v[32:33], v[32:33], v[228:229], v[192:193]
	v_pk_mul_f32 v[228:229], v[162:163], v[0:1] op_sel_hi:[1,0]
	v_pk_fma_f32 v[34:35], v[34:35], v[228:229], v[194:195]
	v_pk_mul_f32 v[228:229], v[164:165], v[0:1] op_sel_hi:[1,0]
	v_pk_fma_f32 v[36:37], v[36:37], v[228:229], v[196:197]
	v_pk_mul_f32 v[228:229], v[166:167], v[0:1] op_sel_hi:[1,0]
	v_pk_fma_f32 v[38:39], v[38:39], v[228:229], v[198:199]
	v_pk_mul_f32 v[228:229], v[168:169], v[0:1] op_sel_hi:[1,0]
	v_pk_fma_f32 v[20:21], v[20:21], v[228:229], v[200:201]
	v_pk_mul_f32 v[228:229], v[170:171], v[0:1] op_sel_hi:[1,0]
	v_pk_fma_f32 v[22:23], v[22:23], v[228:229], v[202:203]
	v_cvt_pk_bf16_f32 v24, v126, v127
	v_cvt_pk_bf16_f32 v25, v128, v129
	v_cvt_pk_bf16_f32 v26, v130, v131
	v_cvt_pk_bf16_f32 v27, v132, v133
	v_cvt_pk_bf16_f32 v8, v240, v241
	v_cvt_pk_bf16_f32 v9, v242, v243
	v_cvt_pk_bf16_f32 v10, v244, v245
	v_cvt_pk_bf16_f32 v11, v246, v247
	v_cvt_pk_bf16_f32 v220, v248, v249
	v_cvt_pk_bf16_f32 v221, v250, v251
	v_cvt_pk_bf16_f32 v222, v32, v33
	v_cvt_pk_bf16_f32 v223, v34, v35
	v_cvt_pk_bf16_f32 v224, v36, v37
	v_cvt_pk_bf16_f32 v225, v38, v39
	v_cvt_pk_bf16_f32 v226, v20, v21
	v_cvt_pk_bf16_f32 v227, v22, v23
	global_store_dwordx2 v1, v[24:25], s[90:91] offset:0
	global_store_dwordx2 v1, v[26:27], s[90:91] offset:512
	global_store_dwordx2 v1, v[8:9], s[90:91] offset:1024
	global_store_dwordx2 v1, v[10:11], s[90:91] offset:1536
	global_store_dwordx2 v1, v[220:221], s[90:91] offset:2048
	global_store_dwordx2 v1, v[222:223], s[90:91] offset:2560
	global_store_dwordx2 v1, v[224:225], s[90:91] offset:3072
	global_store_dwordx2 v1, v[226:227], s[90:91] offset:3584
	s_add_u32 s90, s90, 0x800000
	s_addc_u32 s91, s91, 0
	s_waitcnt vmcnt(16)
	v_lshlrev_b32_e32 v126, 16, v204
	v_and_b32_e32 v127, 0xffff0000, v204
	v_lshlrev_b32_e32 v128, 16, v205
	v_and_b32_e32 v129, 0xffff0000, v205
	v_lshlrev_b32_e32 v130, 16, v206
	v_and_b32_e32 v131, 0xffff0000, v206
	v_lshlrev_b32_e32 v132, 16, v207
	v_and_b32_e32 v133, 0xffff0000, v207
	v_lshlrev_b32_e32 v240, 16, v208
	v_and_b32_e32 v241, 0xffff0000, v208
	v_lshlrev_b32_e32 v242, 16, v209
	v_and_b32_e32 v243, 0xffff0000, v209
	v_lshlrev_b32_e32 v244, 16, v210
	v_and_b32_e32 v245, 0xffff0000, v210
	v_lshlrev_b32_e32 v246, 16, v211
	v_and_b32_e32 v247, 0xffff0000, v211
	v_lshlrev_b32_e32 v248, 16, v212
	v_and_b32_e32 v249, 0xffff0000, v212
	v_lshlrev_b32_e32 v250, 16, v213
	v_and_b32_e32 v251, 0xffff0000, v213
	v_lshlrev_b32_e32 v32, 16, v214
	v_and_b32_e32 v33, 0xffff0000, v214
	v_lshlrev_b32_e32 v34, 16, v215
	v_and_b32_e32 v35, 0xffff0000, v215
	v_lshlrev_b32_e32 v36, 16, v216
	v_and_b32_e32 v37, 0xffff0000, v216
	v_lshlrev_b32_e32 v38, 16, v217
	v_and_b32_e32 v39, 0xffff0000, v217
	v_lshlrev_b32_e32 v20, 16, v218
	v_and_b32_e32 v21, 0xffff0000, v218
	v_lshlrev_b32_e32 v22, 16, v219
	v_and_b32_e32 v23, 0xffff0000, v219
	v_pk_add_f32 v[228:229], v[126:127], v[128:129]
	v_pk_add_f32 v[228:229], v[228:229], v[130:131]
	v_pk_add_f32 v[228:229], v[228:229], v[132:133]
	v_pk_add_f32 v[228:229], v[228:229], v[240:241]
	v_pk_add_f32 v[228:229], v[228:229], v[242:243]
	v_pk_add_f32 v[228:229], v[228:229], v[244:245]
	v_pk_add_f32 v[228:229], v[228:229], v[246:247]
	v_pk_add_f32 v[228:229], v[228:229], v[248:249]
	v_pk_add_f32 v[228:229], v[228:229], v[250:251]
	v_pk_add_f32 v[228:229], v[228:229], v[32:33]
	v_pk_add_f32 v[228:229], v[228:229], v[34:35]
	v_pk_add_f32 v[228:229], v[228:229], v[36:37]
	v_pk_add_f32 v[228:229], v[228:229], v[38:39]
	v_pk_add_f32 v[228:229], v[228:229], v[20:21]
	v_pk_add_f32 v[228:229], v[228:229], v[22:23]
	v_add_f32_e32 v228, v228, v229
	s_nop 1
	v_add_f32_dpp v228, v228, v228 quad_perm:[1,0,3,2] row_mask:0xf bank_mask:0xf bound_ctrl:1
	s_nop 1
	v_add_f32_dpp v228, v228, v228 quad_perm:[2,3,0,1] row_mask:0xf bank_mask:0xf bound_ctrl:1
	s_nop 1
	v_add_f32_dpp v228, v228, v228 row_half_mirror row_mask:0xf bank_mask:0xf bound_ctrl:1
	s_nop 1
	v_add_f32_dpp v228, v228, v228 row_mirror row_mask:0xf bank_mask:0xf bound_ctrl:1
	v_mov_b32_e32 v2, v228
	s_nop 1
	v_permlane16_swap_b32 v228, v2
	s_nop 0
	v_add_f32_e32 v228, v228, v2
	v_mov_b32_e32 v2, v228
	s_nop 1
	v_permlane32_swap_b32 v228, v2
	s_nop 0
	v_add_f32_e32 v228, v228, v2
	v_mul_f32_e32 v134, 0x3a000000, v228
	v_pk_add_f32 v[126:127], v[126:127], v[134:135] op_sel_hi:[1,0] neg_lo:[0,1] neg_hi:[0,1]
	v_pk_add_f32 v[128:129], v[128:129], v[134:135] op_sel_hi:[1,0] neg_lo:[0,1] neg_hi:[0,1]
	v_pk_add_f32 v[130:131], v[130:131], v[134:135] op_sel_hi:[1,0] neg_lo:[0,1] neg_hi:[0,1]
	v_pk_add_f32 v[132:133], v[132:133], v[134:135] op_sel_hi:[1,0] neg_lo:[0,1] neg_hi:[0,1]
	v_pk_add_f32 v[240:241], v[240:241], v[134:135] op_sel_hi:[1,0] neg_lo:[0,1] neg_hi:[0,1]
	v_pk_add_f32 v[242:243], v[242:243], v[134:135] op_sel_hi:[1,0] neg_lo:[0,1] neg_hi:[0,1]
	v_pk_add_f32 v[244:245], v[244:245], v[134:135] op_sel_hi:[1,0] neg_lo:[0,1] neg_hi:[0,1]
	v_pk_add_f32 v[246:247], v[246:247], v[134:135] op_sel_hi:[1,0] neg_lo:[0,1] neg_hi:[0,1]
	v_pk_add_f32 v[248:249], v[248:249], v[134:135] op_sel_hi:[1,0] neg_lo:[0,1] neg_hi:[0,1]
	v_pk_add_f32 v[250:251], v[250:251], v[134:135] op_sel_hi:[1,0] neg_lo:[0,1] neg_hi:[0,1]
	v_pk_add_f32 v[32:33], v[32:33], v[134:135] op_sel_hi:[1,0] neg_lo:[0,1] neg_hi:[0,1]
	v_pk_add_f32 v[34:35], v[34:35], v[134:135] op_sel_hi:[1,0] neg_lo:[0,1] neg_hi:[0,1]
	v_pk_add_f32 v[36:37], v[36:37], v[134:135] op_sel_hi:[1,0] neg_lo:[0,1] neg_hi:[0,1]
	v_pk_add_f32 v[38:39], v[38:39], v[134:135] op_sel_hi:[1,0] neg_lo:[0,1] neg_hi:[0,1]
	v_pk_add_f32 v[20:21], v[20:21], v[134:135] op_sel_hi:[1,0] neg_lo:[0,1] neg_hi:[0,1]
	v_pk_add_f32 v[22:23], v[22:23], v[134:135] op_sel_hi:[1,0] neg_lo:[0,1] neg_hi:[0,1]
	v_pk_mul_f32 v[228:229], v[126:127], v[126:127]
	v_pk_fma_f32 v[228:229], v[128:129], v[128:129], v[228:229]
	v_pk_fma_f32 v[228:229], v[130:131], v[130:131], v[228:229]
	v_pk_fma_f32 v[228:229], v[132:133], v[132:133], v[228:229]
	v_pk_fma_f32 v[228:229], v[240:241], v[240:241], v[228:229]
	v_pk_fma_f32 v[228:229], v[242:243], v[242:243], v[228:229]
	v_pk_fma_f32 v[228:229], v[244:245], v[244:245], v[228:229]
	v_pk_fma_f32 v[228:229], v[246:247], v[246:247], v[228:229]
	v_pk_fma_f32 v[228:229], v[248:249], v[248:249], v[228:229]
	v_pk_fma_f32 v[228:229], v[250:251], v[250:251], v[228:229]
	v_pk_fma_f32 v[228:229], v[32:33], v[32:33], v[228:229]
	v_pk_fma_f32 v[228:229], v[34:35], v[34:35], v[228:229]
	v_pk_fma_f32 v[228:229], v[36:37], v[36:37], v[228:229]
	v_pk_fma_f32 v[228:229], v[38:39], v[38:39], v[228:229]
	v_pk_fma_f32 v[228:229], v[20:21], v[20:21], v[228:229]
	v_pk_fma_f32 v[228:229], v[22:23], v[22:23], v[228:229]
	v_add_f32_e32 v228, v228, v229
	s_nop 1
	v_add_f32_dpp v228, v228, v228 quad_perm:[1,0,3,2] row_mask:0xf bank_mask:0xf bound_ctrl:1
	s_nop 1
	v_add_f32_dpp v228, v228, v228 quad_perm:[2,3,0,1] row_mask:0xf bank_mask:0xf bound_ctrl:1
	s_nop 1
	v_add_f32_dpp v228, v228, v228 row_half_mirror row_mask:0xf bank_mask:0xf bound_ctrl:1
	s_nop 1
	v_add_f32_dpp v228, v228, v228 row_mirror row_mask:0xf bank_mask:0xf bound_ctrl:1
	v_mov_b32_e32 v2, v228
	s_nop 1
	v_permlane16_swap_b32 v228, v2
	s_nop 0
	v_add_f32_e32 v228, v228, v2
	v_mov_b32_e32 v2, v228
	s_nop 1
	v_permlane32_swap_b32 v228, v2
	s_nop 0
	v_add_f32_e32 v228, v228, v2
	v_mul_f32_e32 v0, 0x3a000000, v228
	v_add_f32_e32 v0, 0x3727c5ac, v0
	v_rsq_f32_e32 v0, v0
	s_nop 0
	v_pk_mul_f32 v[228:229], v[140:141], v[0:1] op_sel_hi:[1,0]
	v_pk_fma_f32 v[126:127], v[126:127], v[228:229], v[172:173]
	v_pk_mul_f32 v[228:229], v[142:143], v[0:1] op_sel_hi:[1,0]
	v_pk_fma_f32 v[128:129], v[128:129], v[228:229], v[174:175]
	v_pk_mul_f32 v[228:229], v[144:145], v[0:1] op_sel_hi:[1,0]
	v_pk_fma_f32 v[130:131], v[130:131], v[228:229], v[176:177]
	v_pk_mul_f32 v[228:229], v[146:147], v[0:1] op_sel_hi:[1,0]
	v_pk_fma_f32 v[132:133], v[132:133], v[228:229], v[178:179]
	v_pk_mul_f32 v[228:229], v[148:149], v[0:1] op_sel_hi:[1,0]
	v_pk_fma_f32 v[240:241], v[240:241], v[228:229], v[180:181]
	v_pk_mul_f32 v[228:229], v[150:151], v[0:1] op_sel_hi:[1,0]
	v_pk_fma_f32 v[242:243], v[242:243], v[228:229], v[182:183]
	v_pk_mul_f32 v[228:229], v[152:153], v[0:1] op_sel_hi:[1,0]
	v_pk_fma_f32 v[244:245], v[244:245], v[228:229], v[184:185]
	v_pk_mul_f32 v[228:229], v[154:155], v[0:1] op_sel_hi:[1,0]
	v_pk_fma_f32 v[246:247], v[246:247], v[228:229], v[186:187]
	v_pk_mul_f32 v[228:229], v[156:157], v[0:1] op_sel_hi:[1,0]
	v_pk_fma_f32 v[248:249], v[248:249], v[228:229], v[188:189]
	v_pk_mul_f32 v[228:229], v[158:159], v[0:1] op_sel_hi:[1,0]
	v_pk_fma_f32 v[250:251], v[250:251], v[228:229], v[190:191]
	v_pk_mul_f32 v[228:229], v[160:161], v[0:1] op_sel_hi:[1,0]
	v_pk_fma_f32 v[32:33], v[32:33], v[228:229], v[192:193]
	v_pk_mul_f32 v[228:229], v[162:163], v[0:1] op_sel_hi:[1,0]
	v_pk_fma_f32 v[34:35], v[34:35], v[228:229], v[194:195]
	v_pk_mul_f32 v[228:229], v[164:165], v[0:1] op_sel_hi:[1,0]
	v_pk_fma_f32 v[36:37], v[36:37], v[228:229], v[196:197]
	v_pk_mul_f32 v[228:229], v[166:167], v[0:1] op_sel_hi:[1,0]
	v_pk_fma_f32 v[38:39], v[38:39], v[228:229], v[198:199]
	v_pk_mul_f32 v[228:229], v[168:169], v[0:1] op_sel_hi:[1,0]
	v_pk_fma_f32 v[20:21], v[20:21], v[228:229], v[200:201]
	v_pk_mul_f32 v[228:229], v[170:171], v[0:1] op_sel_hi:[1,0]
	v_pk_fma_f32 v[22:23], v[22:23], v[228:229], v[202:203]
	v_cvt_pk_bf16_f32 v204, v126, v127
	v_cvt_pk_bf16_f32 v205, v128, v129
	v_cvt_pk_bf16_f32 v206, v130, v131
	v_cvt_pk_bf16_f32 v207, v132, v133
	v_cvt_pk_bf16_f32 v208, v240, v241
	v_cvt_pk_bf16_f32 v209, v242, v243
	v_cvt_pk_bf16_f32 v210, v244, v245
	v_cvt_pk_bf16_f32 v211, v246, v247
	v_cvt_pk_bf16_f32 v212, v248, v249
	v_cvt_pk_bf16_f32 v213, v250, v251
	v_cvt_pk_bf16_f32 v214, v32, v33
	v_cvt_pk_bf16_f32 v215, v34, v35
	v_cvt_pk_bf16_f32 v216, v36, v37
	v_cvt_pk_bf16_f32 v217, v38, v39
	v_cvt_pk_bf16_f32 v218, v20, v21
	v_cvt_pk_bf16_f32 v219, v22, v23
	global_store_dwordx2 v1, v[204:205], s[90:91] offset:0
	global_store_dwordx2 v1, v[206:207], s[90:91] offset:512
	global_store_dwordx2 v1, v[208:209], s[90:91] offset:1024
	global_store_dwordx2 v1, v[210:211], s[90:91] offset:1536
	global_store_dwordx2 v1, v[212:213], s[90:91] offset:2048
	global_store_dwordx2 v1, v[214:215], s[90:91] offset:2560
	global_store_dwordx2 v1, v[216:217], s[90:91] offset:3072
	global_store_dwordx2 v1, v[218:219], s[90:91] offset:3584
	s_add_u32 s90, s90, 0x800000
	s_addc_u32 s91, s91, 0

.LBB0_2203:
	s_cmp_lt_i32 s30, 16
	s_cselect_b64 s[8:9], -1, 0
	s_and_b64 s[10:11], s[8:9], s[6:7]
	s_andn2_b64 vcc, exec, s[10:11]
	s_cbranch_vccnz .LBB0_2215
	s_load_dwordx4 s[12:15], s[0:1], 0x130
	v_lshl_add_u32 v32, s2, 3, v230
	s_movk_i32 s3, 0x2000
	v_cmp_gt_i32_e32 vcc, s3, v32
	s_and_saveexec_b64 s[16:17], vcc
	s_cbranch_execz .LBB0_2209
	s_load_dwordx4 s[60:63], s[0:1], 0x130
	v_lshl_add_u32 v2, s2, 3, v230
	v_lshlrev_b32_e32 v137, 4, v136
	v_lshlrev_b32_e32 v1, 3, v136
	v_lshl_add_u32 v1, v2, 12, v1
	v_add_u32_e32 v4, 0x1000, v137
	s_add_u32 s88, s28, 0xe600000
	s_addc_u32 s89, s29, 0
	s_add_u32 s90, s28, 0xc500000
	s_addc_u32 s91, s29, 0
	global_load_dwordx2 v[204:205], v1, s[88:89] offset:0
	global_load_dwordx2 v[206:207], v1, s[88:89] offset:512
	global_load_dwordx2 v[208:209], v1, s[88:89] offset:1024
	global_load_dwordx2 v[210:211], v1, s[88:89] offset:1536
	global_load_dwordx2 v[212:213], v1, s[88:89] offset:2048
	global_load_dwordx2 v[214:215], v1, s[88:89] offset:2560
	global_load_dwordx2 v[216:217], v1, s[88:89] offset:3072
	global_load_dwordx2 v[218:219], v1, s[88:89] offset:3584
	s_add_u32 s88, s88, 0x800000
	s_addc_u32 s89, s89, 0
	s_waitcnt lgkmcnt(0)
	global_load_dwordx4 v[140:143], v137, s[60:61] offset:0
	global_load_dwordx4 v[144:147], v137, s[60:61] offset:1024
	global_load_dwordx4 v[148:151], v137, s[60:61] offset:2048
	global_load_dwordx4 v[152:155], v137, s[60:61] offset:3072
	global_load_dwordx4 v[156:159], v4, s[60:61] offset:0
	global_load_dwordx4 v[160:163], v4, s[60:61] offset:1024
	global_load_dwordx4 v[164:167], v4, s[60:61] offset:2048
	global_load_dwordx4 v[168:171], v4, s[60:61] offset:3072
	global_load_dwordx4 v[172:175], v137, s[62:63] offset:0
	global_load_dwordx4 v[176:179], v137, s[62:63] offset:1024
	global_load_dwordx4 v[180:183], v137, s[62:63] offset:2048
	global_load_dwordx4 v[184:187], v137, s[62:63] offset:3072
	global_load_dwordx4 v[188:191], v4, s[62:63] offset:0
	global_load_dwordx4 v[192:195], v4, s[62:63] offset:1024
	global_load_dwordx4 v[196:199], v4, s[62:63] offset:2048
	global_load_dwordx4 v[200:203], v4, s[62:63] offset:3072
	global_load_dwordx2 v[110:111], v1, s[88:89] offset:0
	global_load_dwordx2 v[112:113], v1, s[88:89] offset:512
	global_load_dwordx2 v[114:115], v1, s[88:89] offset:1024
	global_load_dwordx2 v[116:117], v1, s[88:89] offset:1536
	global_load_dwordx2 v[118:119], v1, s[88:89] offset:2048
	global_load_dwordx2 v[120:121], v1, s[88:89] offset:2560
	global_load_dwordx2 v[122:123], v1, s[88:89] offset:3072
	global_load_dwordx2 v[124:125], v1, s[88:89] offset:3584
	s_add_u32 s88, s88, 0x800000
	s_addc_u32 s89, s89, 0
	global_load_dwordx2 v[24:25], v1, s[88:89] offset:0
	global_load_dwordx2 v[26:27], v1, s[88:89] offset:512
	global_load_dwordx2 v[8:9], v1, s[88:89] offset:1024
	global_load_dwordx2 v[10:11], v1, s[88:89] offset:1536
	global_load_dwordx2 v[220:221], v1, s[88:89] offset:2048
	global_load_dwordx2 v[222:223], v1, s[88:89] offset:2560
	global_load_dwordx2 v[224:225], v1, s[88:89] offset:3072
	global_load_dwordx2 v[226:227], v1, s[88:89] offset:3584
	s_add_u32 s88, s88, 0x800000
	s_addc_u32 s89, s89, 0
	s_waitcnt vmcnt(32)
	v_lshlrev_b32_e32 v126, 16, v204
	v_and_b32_e32 v127, 0xffff0000, v204
	v_lshlrev_b32_e32 v128, 16, v205
	v_and_b32_e32 v129, 0xffff0000, v205
	v_lshlrev_b32_e32 v130, 16, v206
	v_and_b32_e32 v131, 0xffff0000, v206
	v_lshlrev_b32_e32 v132, 16, v207
	v_and_b32_e32 v133, 0xffff0000, v207
	v_lshlrev_b32_e32 v240, 16, v208
	v_and_b32_e32 v241, 0xffff0000, v208
	v_lshlrev_b32_e32 v242, 16, v209
	v_and_b32_e32 v243, 0xffff0000, v209
	v_lshlrev_b32_e32 v244, 16, v210
	v_and_b32_e32 v245, 0xffff0000, v210
	v_lshlrev_b32_e32 v246, 16, v211
	v_and_b32_e32 v247, 0xffff0000, v211
	v_lshlrev_b32_e32 v248, 16, v212
	v_and_b32_e32 v249, 0xffff0000, v212
	v_lshlrev_b32_e32 v250, 16, v213
	v_and_b32_e32 v251, 0xffff0000, v213
	v_lshlrev_b32_e32 v32, 16, v214
	v_and_b32_e32 v33, 0xffff0000, v214
	v_lshlrev_b32_e32 v34, 16, v215
	v_and_b32_e32 v35, 0xffff0000, v215
	v_lshlrev_b32_e32 v36, 16, v216
	v_and_b32_e32 v37, 0xffff0000, v216
	v_lshlrev_b32_e32 v38, 16, v217
	v_and_b32_e32 v39, 0xffff0000, v217
	v_lshlrev_b32_e32 v20, 16, v218
	v_and_b32_e32 v21, 0xffff0000, v218
	v_lshlrev_b32_e32 v22, 16, v219
	v_and_b32_e32 v23, 0xffff0000, v219
	v_pk_add_f32 v[228:229], v[126:127], v[128:129]
	v_pk_add_f32 v[228:229], v[228:229], v[130:131]
	v_pk_add_f32 v[228:229], v[228:229], v[132:133]
	v_pk_add_f32 v[228:229], v[228:229], v[240:241]
	v_pk_add_f32 v[228:229], v[228:229], v[242:243]
	v_pk_add_f32 v[228:229], v[228:229], v[244:245]
	v_pk_add_f32 v[228:229], v[228:229], v[246:247]
	v_pk_add_f32 v[228:229], v[228:229], v[248:249]
	v_pk_add_f32 v[228:229], v[228:229], v[250:251]
	v_pk_add_f32 v[228:229], v[228:229], v[32:33]
	v_pk_add_f32 v[228:229], v[228:229], v[34:35]
	v_pk_add_f32 v[228:229], v[228:229], v[36:37]
	v_pk_add_f32 v[228:229], v[228:229], v[38:39]
	v_pk_add_f32 v[228:229], v[228:229], v[20:21]
	v_pk_add_f32 v[228:229], v[228:229], v[22:23]
	v_add_f32_e32 v228, v228, v229
	s_nop 1
	v_add_f32_dpp v228, v228, v228 quad_perm:[1,0,3,2] row_mask:0xf bank_mask:0xf bound_ctrl:1
	s_nop 1
	v_add_f32_dpp v228, v228, v228 quad_perm:[2,3,0,1] row_mask:0xf bank_mask:0xf bound_ctrl:1
	s_nop 1
	v_add_f32_dpp v228, v228, v228 row_half_mirror row_mask:0xf bank_mask:0xf bound_ctrl:1
	s_nop 1
	v_add_f32_dpp v228, v228, v228 row_mirror row_mask:0xf bank_mask:0xf bound_ctrl:1
	v_mov_b32_e32 v2, v228
	s_nop 1
	v_permlane16_swap_b32 v228, v2
	s_nop 0
	v_add_f32_e32 v228, v228, v2
	v_mov_b32_e32 v2, v228
	s_nop 1
	v_permlane32_swap_b32 v228, v2
	s_nop 0
	v_add_f32_e32 v228, v228, v2
	v_mul_f32_e32 v134, 0x3a000000, v228
	v_pk_add_f32 v[126:127], v[126:127], v[134:135] op_sel_hi:[1,0] neg_lo:[0,1] neg_hi:[0,1]
	v_pk_add_f32 v[128:129], v[128:129], v[134:135] op_sel_hi:[1,0] neg_lo:[0,1] neg_hi:[0,1]
	v_pk_add_f32 v[130:131], v[130:131], v[134:135] op_sel_hi:[1,0] neg_lo:[0,1] neg_hi:[0,1]
	v_pk_add_f32 v[132:133], v[132:133], v[134:135] op_sel_hi:[1,0] neg_lo:[0,1] neg_hi:[0,1]
	v_pk_add_f32 v[240:241], v[240:241], v[134:135] op_sel_hi:[1,0] neg_lo:[0,1] neg_hi:[0,1]
	v_pk_add_f32 v[242:243], v[242:243], v[134:135] op_sel_hi:[1,0] neg_lo:[0,1] neg_hi:[0,1]
	v_pk_add_f32 v[244:245], v[244:245], v[134:135] op_sel_hi:[1,0] neg_lo:[0,1] neg_hi:[0,1]
	v_pk_add_f32 v[246:247], v[246:247], v[134:135] op_sel_hi:[1,0] neg_lo:[0,1] neg_hi:[0,1]
	v_pk_add_f32 v[248:249], v[248:249], v[134:135] op_sel_hi:[1,0] neg_lo:[0,1] neg_hi:[0,1]
	v_pk_add_f32 v[250:251], v[250:251], v[134:135] op_sel_hi:[1,0] neg_lo:[0,1] neg_hi:[0,1]
	v_pk_add_f32 v[32:33], v[32:33], v[134:135] op_sel_hi:[1,0] neg_lo:[0,1] neg_hi:[0,1]
	v_pk_add_f32 v[34:35], v[34:35], v[134:135] op_sel_hi:[1,0] neg_lo:[0,1] neg_hi:[0,1]
	v_pk_add_f32 v[36:37], v[36:37], v[134:135] op_sel_hi:[1,0] neg_lo:[0,1] neg_hi:[0,1]
	v_pk_add_f32 v[38:39], v[38:39], v[134:135] op_sel_hi:[1,0] neg_lo:[0,1] neg_hi:[0,1]
	v_pk_add_f32 v[20:21], v[20:21], v[134:135] op_sel_hi:[1,0] neg_lo:[0,1] neg_hi:[0,1]
	v_pk_add_f32 v[22:23], v[22:23], v[134:135] op_sel_hi:[1,0] neg_lo:[0,1] neg_hi:[0,1]
	v_pk_mul_f32 v[228:229], v[126:127], v[126:127]
	v_pk_fma_f32 v[228:229], v[128:129], v[128:129], v[228:229]
	v_pk_fma_f32 v[228:229], v[130:131], v[130:131], v[228:229]
	v_pk_fma_f32 v[228:229], v[132:133], v[132:133], v[228:229]
	v_pk_fma_f32 v[228:229], v[240:241], v[240:241], v[228:229]
	v_pk_fma_f32 v[228:229], v[242:243], v[242:243], v[228:229]
	v_pk_fma_f32 v[228:229], v[244:245], v[244:245], v[228:229]
	v_pk_fma_f32 v[228:229], v[246:247], v[246:247], v[228:229]
	v_pk_fma_f32 v[228:229], v[248:249], v[248:249], v[228:229]
	v_pk_fma_f32 v[228:229], v[250:251], v[250:251], v[228:229]
	v_pk_fma_f32 v[228:229], v[32:33], v[32:33], v[228:229]
	v_pk_fma_f32 v[228:229], v[34:35], v[34:35], v[228:229]
	v_pk_fma_f32 v[228:229], v[36:37], v[36:37], v[228:229]
	v_pk_fma_f32 v[228:229], v[38:39], v[38:39], v[228:229]
	v_pk_fma_f32 v[228:229], v[20:21], v[20:21], v[228:229]
	v_pk_fma_f32 v[228:229], v[22:23], v[22:23], v[228:229]
	v_add_f32_e32 v228, v228, v229
	s_nop 1
	v_add_f32_dpp v228, v228, v228 quad_perm:[1,0,3,2] row_mask:0xf bank_mask:0xf bound_ctrl:1
	s_nop 1
	v_add_f32_dpp v228, v228, v228 quad_perm:[2,3,0,1] row_mask:0xf bank_mask:0xf bound_ctrl:1
	s_nop 1
	v_add_f32_dpp v228, v228, v228 row_half_mirror row_mask:0xf bank_mask:0xf bound_ctrl:1
	s_nop 1
	v_add_f32_dpp v228, v228, v228 row_mirror row_mask:0xf bank_mask:0xf bound_ctrl:1
	v_mov_b32_e32 v2, v228
	s_nop 1
	v_permlane16_swap_b32 v228, v2
	s_nop 0
	v_add_f32_e32 v228, v228, v2
	v_mov_b32_e32 v2, v228
	s_nop 1
	v_permlane32_swap_b32 v228, v2
	s_nop 0
	v_add_f32_e32 v228, v228, v2
	v_mul_f32_e32 v0, 0x3a000000, v228
	v_add_f32_e32 v0, 0x3727c5ac, v0
	v_rsq_f32_e32 v0, v0
	s_waitcnt vmcnt(16)
	v_pk_mul_f32 v[228:229], v[140:141], v[0:1] op_sel_hi:[1,0]
	v_pk_fma_f32 v[126:127], v[126:127], v[228:229], v[172:173]
	v_pk_mul_f32 v[228:229], v[142:143], v[0:1] op_sel_hi:[1,0]
	v_pk_fma_f32 v[128:129], v[128:129], v[228:229], v[174:175]
	v_pk_mul_f32 v[228:229], v[144:145], v[0:1] op_sel_hi:[1,0]
	v_pk_fma_f32 v[130:131], v[130:131], v[228:229], v[176:177]
	v_pk_mul_f32 v[228:229], v[146:147], v[0:1] op_sel_hi:[1,0]
	v_pk_fma_f32 v[132:133], v[132:133], v[228:229], v[178:179]
	v_pk_mul_f32 v[228:229], v[148:149], v[0:1] op_sel_hi:[1,0]
	v_pk_fma_f32 v[240:241], v[240:241], v[228:229], v[180:181]
	v_pk_mul_f32 v[228:229], v[150:151], v[0:1] op_sel_hi:[1,0]
	v_pk_fma_f32 v[242:243], v[242:243], v[228:229], v[182:183]
	v_pk_mul_f32 v[228:229], v[152:153], v[0:1] op_sel_hi:[1,0]
	v_pk_fma_f32 v[244:245], v[244:245], v[228:229], v[184:185]
	v_pk_mul_f32 v[228:229], v[154:155], v[0:1] op_sel_hi:[1,0]
	v_pk_fma_f32 v[246:247], v[246:247], v[228:229], v[186:187]
	v_pk_mul_f32 v[228:229], v[156:157], v[0:1] op_sel_hi:[1,0]
	v_pk_fma_f32 v[248:249], v[248:249], v[228:229], v[188:189]
	v_pk_mul_f32 v[228:229], v[158:159], v[0:1] op_sel_hi:[1,0]
	v_pk_fma_f32 v[250:251], v[250:251], v[228:229], v[190:191]
	v_pk_mul_f32 v[228:229], v[160:161], v[0:1] op_sel_hi:[1,0]
	v_pk_fma_f32 v[32:33], v[32:33], v[228:229], v[192:193]
	v_pk_mul_f32 v[228:229], v[162:163], v[0:1] op_sel_hi:[1,0]
	v_pk_fma_f32 v[34:35], v[34:35], v[228:229], v[194:195]
	v_pk_mul_f32 v[228:229], v[164:165], v[0:1] op_sel_hi:[1,0]
	v_pk_fma_f32 v[36:37], v[36:37], v[228:229], v[196:197]
	v_pk_mul_f32 v[228:229], v[166:167], v[0:1] op_sel_hi:[1,0]
	v_pk_fma_f32 v[38:39], v[38:39], v[228:229], v[198:199]
	v_pk_mul_f32 v[228:229], v[168:169], v[0:1] op_sel_hi:[1,0]
	v_pk_fma_f32 v[20:21], v[20:21], v[228:229], v[200:201]
	v_pk_mul_f32 v[228:229], v[170:171], v[0:1] op_sel_hi:[1,0]
	v_pk_fma_f32 v[22:23], v[22:23], v[228:229], v[202:203]
	v_cvt_pk_bf16_f32 v204, v126, v127
	v_cvt_pk_bf16_f32 v205, v128, v129
	v_cvt_pk_bf16_f32 v206, v130, v131
	v_cvt_pk_bf16_f32 v207, v132, v133
	v_cvt_pk_bf16_f32 v208, v240, v241
	v_cvt_pk_bf16_f32 v209, v242, v243
	v_cvt_pk_bf16_f32 v210, v244, v245
	v_cvt_pk_bf16_f32 v211, v246, v247
	v_cvt_pk_bf16_f32 v212, v248, v249
	v_cvt_pk_bf16_f32 v213, v250, v251
	v_cvt_pk_bf16_f32 v214, v32, v33
	v_cvt_pk_bf16_f32 v215, v34, v35
	v_cvt_pk_bf16_f32 v216, v36, v37
	v_cvt_pk_bf16_f32 v217, v38, v39
	v_cvt_pk_bf16_f32 v218, v20, v21
	v_cvt_pk_bf16_f32 v219, v22, v23
	global_store_dwordx2 v1, v[204:205], s[90:91] offset:0
	global_store_dwordx2 v1, v[206:207], s[90:91] offset:512
	global_store_dwordx2 v1, v[208:209], s[90:91] offset:1024
	global_store_dwordx2 v1, v[210:211], s[90:91] offset:1536
	global_store_dwordx2 v1, v[212:213], s[90:91] offset:2048
	global_store_dwordx2 v1, v[214:215], s[90:91] offset:2560
	global_store_dwordx2 v1, v[216:217], s[90:91] offset:3072
	global_store_dwordx2 v1, v[218:219], s[90:91] offset:3584
	s_add_u32 s90, s90, 0x800000
	s_addc_u32 s91, s91, 0
	global_load_dwordx2 v[204:205], v1, s[88:89] offset:0
	global_load_dwordx2 v[206:207], v1, s[88:89] offset:512
	global_load_dwordx2 v[208:209], v1, s[88:89] offset:1024
	global_load_dwordx2 v[210:211], v1, s[88:89] offset:1536
	global_load_dwordx2 v[212:213], v1, s[88:89] offset:2048
	global_load_dwordx2 v[214:215], v1, s[88:89] offset:2560
	global_load_dwordx2 v[216:217], v1, s[88:89] offset:3072
	global_load_dwordx2 v[218:219], v1, s[88:89] offset:3584
	s_add_u32 s88, s88, 0x800000
	s_addc_u32 s89, s89, 0
	s_waitcnt vmcnt(24)
	v_lshlrev_b32_e32 v126, 16, v110
	v_and_b32_e32 v127, 0xffff0000, v110
	v_lshlrev_b32_e32 v128, 16, v111
	v_and_b32_e32 v129, 0xffff0000, v111
	v_lshlrev_b32_e32 v130, 16, v112
	v_and_b32_e32 v131, 0xffff0000, v112
	v_lshlrev_b32_e32 v132, 16, v113
	v_and_b32_e32 v133, 0xffff0000, v113
	v_lshlrev_b32_e32 v240, 16, v114
	v_and_b32_e32 v241, 0xffff0000, v114
	v_lshlrev_b32_e32 v242, 16, v115
	v_and_b32_e32 v243, 0xffff0000, v115
	v_lshlrev_b32_e32 v244, 16, v116
	v_and_b32_e32 v245, 0xffff0000, v116
	v_lshlrev_b32_e32 v246, 16, v117
	v_and_b32_e32 v247, 0xffff0000, v117
	v_lshlrev_b32_e32 v248, 16, v118
	v_and_b32_e32 v249, 0xffff0000, v118
	v_lshlrev_b32_e32 v250, 16, v119
	v_and_b32_e32 v251, 0xffff0000, v119
	v_lshlrev_b32_e32 v32, 16, v120
	v_and_b32_e32 v33, 0xffff0000, v120
	v_lshlrev_b32_e32 v34, 16, v121
	v_and_b32_e32 v35, 0xffff0000, v121
	v_lshlrev_b32_e32 v36, 16, v122
	v_and_b32_e32 v37, 0xffff0000, v122
	v_lshlrev_b32_e32 v38, 16, v123
	v_and_b32_e32 v39, 0xffff0000, v123
	v_lshlrev_b32_e32 v20, 16, v124
	v_and_b32_e32 v21, 0xffff0000, v124
	v_lshlrev_b32_e32 v22, 16, v125
	v_and_b32_e32 v23, 0xffff0000, v125
	v_pk_add_f32 v[228:229], v[126:127], v[128:129]
	v_pk_add_f32 v[228:229], v[228:229], v[130:131]
	v_pk_add_f32 v[228:229], v[228:229], v[132:133]
	v_pk_add_f32 v[228:229], v[228:229], v[240:241]
	v_pk_add_f32 v[228:229], v[228:229], v[242:243]
	v_pk_add_f32 v[228:229], v[228:229], v[244:245]
	v_pk_add_f32 v[228:229], v[228:229], v[246:247]
	v_pk_add_f32 v[228:229], v[228:229], v[248:249]
	v_pk_add_f32 v[228:229], v[228:229], v[250:251]
	v_pk_add_f32 v[228:229], v[228:229], v[32:33]
	v_pk_add_f32 v[228:229], v[228:229], v[34:35]
	v_pk_add_f32 v[228:229], v[228:229], v[36:37]
	v_pk_add_f32 v[228:229], v[228:229], v[38:39]
	v_pk_add_f32 v[228:229], v[228:229], v[20:21]
	v_pk_add_f32 v[228:229], v[228:229], v[22:23]
	v_add_f32_e32 v228, v228, v229
	s_nop 1
	v_add_f32_dpp v228, v228, v228 quad_perm:[1,0,3,2] row_mask:0xf bank_mask:0xf bound_ctrl:1
	s_nop 1
	v_add_f32_dpp v228, v228, v228 quad_perm:[2,3,0,1] row_mask:0xf bank_mask:0xf bound_ctrl:1
	s_nop 1
	v_add_f32_dpp v228, v228, v228 row_half_mirror row_mask:0xf bank_mask:0xf bound_ctrl:1
	s_nop 1
	v_add_f32_dpp v228, v228, v228 row_mirror row_mask:0xf bank_mask:0xf bound_ctrl:1
	v_mov_b32_e32 v2, v228
	s_nop 1
	v_permlane16_swap_b32 v228, v2
	s_nop 0
	v_add_f32_e32 v228, v228, v2
	v_mov_b32_e32 v2, v228
	s_nop 1
	v_permlane32_swap_b32 v228, v2
	s_nop 0
	v_add_f32_e32 v228, v228, v2
	v_mul_f32_e32 v134, 0x3a000000, v228
	v_pk_add_f32 v[126:127], v[126:127], v[134:135] op_sel_hi:[1,0] neg_lo:[0,1] neg_hi:[0,1]
	v_pk_add_f32 v[128:129], v[128:129], v[134:135] op_sel_hi:[1,0] neg_lo:[0,1] neg_hi:[0,1]
	v_pk_add_f32 v[130:131], v[130:131], v[134:135] op_sel_hi:[1,0] neg_lo:[0,1] neg_hi:[0,1]
	v_pk_add_f32 v[132:133], v[132:133], v[134:135] op_sel_hi:[1,0] neg_lo:[0,1] neg_hi:[0,1]
	v_pk_add_f32 v[240:241], v[240:241], v[134:135] op_sel_hi:[1,0] neg_lo:[0,1] neg_hi:[0,1]
	v_pk_add_f32 v[242:243], v[242:243], v[134:135] op_sel_hi:[1,0] neg_lo:[0,1] neg_hi:[0,1]
	v_pk_add_f32 v[244:245], v[244:245], v[134:135] op_sel_hi:[1,0] neg_lo:[0,1] neg_hi:[0,1]
	v_pk_add_f32 v[246:247], v[246:247], v[134:135] op_sel_hi:[1,0] neg_lo:[0,1] neg_hi:[0,1]
	v_pk_add_f32 v[248:249], v[248:249], v[134:135] op_sel_hi:[1,0] neg_lo:[0,1] neg_hi:[0,1]
	v_pk_add_f32 v[250:251], v[250:251], v[134:135] op_sel_hi:[1,0] neg_lo:[0,1] neg_hi:[0,1]
	v_pk_add_f32 v[32:33], v[32:33], v[134:135] op_sel_hi:[1,0] neg_lo:[0,1] neg_hi:[0,1]
	v_pk_add_f32 v[34:35], v[34:35], v[134:135] op_sel_hi:[1,0] neg_lo:[0,1] neg_hi:[0,1]
	v_pk_add_f32 v[36:37], v[36:37], v[134:135] op_sel_hi:[1,0] neg_lo:[0,1] neg_hi:[0,1]
	v_pk_add_f32 v[38:39], v[38:39], v[134:135] op_sel_hi:[1,0] neg_lo:[0,1] neg_hi:[0,1]
	v_pk_add_f32 v[20:21], v[20:21], v[134:135] op_sel_hi:[1,0] neg_lo:[0,1] neg_hi:[0,1]
	v_pk_add_f32 v[22:23], v[22:23], v[134:135] op_sel_hi:[1,0] neg_lo:[0,1] neg_hi:[0,1]
	v_pk_mul_f32 v[228:229], v[126:127], v[126:127]
	v_pk_fma_f32 v[228:229], v[128:129], v[128:129], v[228:229]
	v_pk_fma_f32 v[228:229], v[130:131], v[130:131], v[228:229]
	v_pk_fma_f32 v[228:229], v[132:133], v[132:133], v[228:229]
	v_pk_fma_f32 v[228:229], v[240:241], v[240:241], v[228:229]
	v_pk_fma_f32 v[228:229], v[242:243], v[242:243], v[228:229]
	v_pk_fma_f32 v[228:229], v[244:245], v[244:245], v[228:229]
	v_pk_fma_f32 v[228:229], v[246:247], v[246:247], v[228:229]
	v_pk_fma_f32 v[228:229], v[248:249], v[248:249], v[228:229]
	v_pk_fma_f32 v[228:229], v[250:251], v[250:251], v[228:229]
	v_pk_fma_f32 v[228:229], v[32:33], v[32:33], v[228:229]
	v_pk_fma_f32 v[228:229], v[34:35], v[34:35], v[228:229]
	v_pk_fma_f32 v[228:229], v[36:37], v[36:37], v[228:229]
	v_pk_fma_f32 v[228:229], v[38:39], v[38:39], v[228:229]
	v_pk_fma_f32 v[228:229], v[20:21], v[20:21], v[228:229]
	v_pk_fma_f32 v[228:229], v[22:23], v[22:23], v[228:229]
	v_add_f32_e32 v228, v228, v229
	s_nop 1
	v_add_f32_dpp v228, v228, v228 quad_perm:[1,0,3,2] row_mask:0xf bank_mask:0xf bound_ctrl:1
	s_nop 1
	v_add_f32_dpp v228, v228, v228 quad_perm:[2,3,0,1] row_mask:0xf bank_mask:0xf bound_ctrl:1
	s_nop 1
	v_add_f32_dpp v228, v228, v228 row_half_mirror row_mask:0xf bank_mask:0xf bound_ctrl:1
	s_nop 1
	v_add_f32_dpp v228, v228, v228 row_mirror row_mask:0xf bank_mask:0xf bound_ctrl:1
	v_mov_b32_e32 v2, v228
	s_nop 1
	v_permlane16_swap_b32 v228, v2
	s_nop 0
	v_add_f32_e32 v228, v228, v2
	v_mov_b32_e32 v2, v228
	s_nop 1
	v_permlane32_swap_b32 v228, v2
	s_nop 0
	v_add_f32_e32 v228, v228, v2
	v_mul_f32_e32 v0, 0x3a000000, v228
	v_add_f32_e32 v0, 0x3727c5ac, v0
	v_rsq_f32_e32 v0, v0
	s_nop 0
	v_pk_mul_f32 v[228:229], v[140:141], v[0:1] op_sel_hi:[1,0]
	v_pk_fma_f32 v[126:127], v[126:127], v[228:229], v[172:173]
	v_pk_mul_f32 v[228:229], v[142:143], v[0:1] op_sel_hi:[1,0]
	v_pk_fma_f32 v[128:129], v[128:129], v[228:229], v[174:175]
	v_pk_mul_f32 v[228:229], v[144:145], v[0:1] op_sel_hi:[1,0]
	v_pk_fma_f32 v[130:131], v[130:131], v[228:229], v[176:177]
	v_pk_mul_f32 v[228:229], v[146:147], v[0:1] op_sel_hi:[1,0]
	v_pk_fma_f32 v[132:133], v[132:133], v[228:229], v[178:179]
	v_pk_mul_f32 v[228:229], v[148:149], v[0:1] op_sel_hi:[1,0]
	v_pk_fma_f32 v[240:241], v[240:241], v[228:229], v[180:181]
	v_pk_mul_f32 v[228:229], v[150:151], v[0:1] op_sel_hi:[1,0]
	v_pk_fma_f32 v[242:243], v[242:243], v[228:229], v[182:183]
	v_pk_mul_f32 v[228:229], v[152:153], v[0:1] op_sel_hi:[1,0]
	v_pk_fma_f32 v[244:245], v[244:245], v[228:229], v[184:185]
	v_pk_mul_f32 v[228:229], v[154:155], v[0:1] op_sel_hi:[1,0]
	v_pk_fma_f32 v[246:247], v[246:247], v[228:229], v[186:187]
	v_pk_mul_f32 v[228:229], v[156:157], v[0:1] op_sel_hi:[1,0]
	v_pk_fma_f32 v[248:249], v[248:249], v[228:229], v[188:189]
	v_pk_mul_f32 v[228:229], v[158:159], v[0:1] op_sel_hi:[1,0]
	v_pk_fma_f32 v[250:251], v[250:251], v[228:229], v[190:191]
	v_pk_mul_f32 v[228:229], v[160:161], v[0:1] op_sel_hi:[1,0]
	v_pk_fma_f32 v[32:33], v[32:33], v[228:229], v[192:193]
	v_pk_mul_f32 v[228:229], v[162:163], v[0:1] op_sel_hi:[1,0]
	v_pk_fma_f32 v[34:35], v[34:35], v[228:229], v[194:195]
	v_pk_mul_f32 v[228:229], v[164:165], v[0:1] op_sel_hi:[1,0]
	v_pk_fma_f32 v[36:37], v[36:37], v[228:229], v[196:197]
	v_pk_mul_f32 v[228:229], v[166:167], v[0:1] op_sel_hi:[1,0]
	v_pk_fma_f32 v[38:39], v[38:39], v[228:229], v[198:199]
	v_pk_mul_f32 v[228:229], v[168:169], v[0:1] op_sel_hi:[1,0]
	v_pk_fma_f32 v[20:21], v[20:21], v[228:229], v[200:201]
	v_pk_mul_f32 v[228:229], v[170:171], v[0:1] op_sel_hi:[1,0]
	v_pk_fma_f32 v[22:23], v[22:23], v[228:229], v[202:203]
	v_cvt_pk_bf16_f32 v110, v126, v127
	v_cvt_pk_bf16_f32 v111, v128, v129
	v_cvt_pk_bf16_f32 v112, v130, v131
	v_cvt_pk_bf16_f32 v113, v132, v133
	v_cvt_pk_bf16_f32 v114, v240, v241
	v_cvt_pk_bf16_f32 v115, v242, v243
	v_cvt_pk_bf16_f32 v116, v244, v245
	v_cvt_pk_bf16_f32 v117, v246, v247
	v_cvt_pk_bf16_f32 v118, v248, v249
	v_cvt_pk_bf16_f32 v119, v250, v251
	v_cvt_pk_bf16_f32 v120, v32, v33
	v_cvt_pk_bf16_f32 v121, v34, v35
	v_cvt_pk_bf16_f32 v122, v36, v37
	v_cvt_pk_bf16_f32 v123, v38, v39
	v_cvt_pk_bf16_f32 v124, v20, v21
	v_cvt_pk_bf16_f32 v125, v22, v23
	global_store_dwordx2 v1, v[110:111], s[90:91] offset:0
	global_store_dwordx2 v1, v[112:113], s[90:91] offset:512
	global_store_dwordx2 v1, v[114:115], s[90:91] offset:1024
	global_store_dwordx2 v1, v[116:117], s[90:91] offset:1536
	global_store_dwordx2 v1, v[118:119], s[90:91] offset:2048
	global_store_dwordx2 v1, v[120:121], s[90:91] offset:2560
	global_store_dwordx2 v1, v[122:123], s[90:91] offset:3072
	global_store_dwordx2 v1, v[124:125], s[90:91] offset:3584
	s_add_u32 s90, s90, 0x800000
	s_addc_u32 s91, s91, 0
	s_waitcnt vmcnt(24)
	v_lshlrev_b32_e32 v126, 16, v24
	v_and_b32_e32 v127, 0xffff0000, v24
	v_lshlrev_b32_e32 v128, 16, v25
	v_and_b32_e32 v129, 0xffff0000, v25
	v_lshlrev_b32_e32 v130, 16, v26
	v_and_b32_e32 v131, 0xffff0000, v26
	v_lshlrev_b32_e32 v132, 16, v27
	v_and_b32_e32 v133, 0xffff0000, v27
	v_lshlrev_b32_e32 v240, 16, v8
	v_and_b32_e32 v241, 0xffff0000, v8
	v_lshlrev_b32_e32 v242, 16, v9
	v_and_b32_e32 v243, 0xffff0000, v9
	v_lshlrev_b32_e32 v244, 16, v10
	v_and_b32_e32 v245, 0xffff0000, v10
	v_lshlrev_b32_e32 v246, 16, v11
	v_and_b32_e32 v247, 0xffff0000, v11
	v_lshlrev_b32_e32 v248, 16, v220
	v_and_b32_e32 v249, 0xffff0000, v220
	v_lshlrev_b32_e32 v250, 16, v221
	v_and_b32_e32 v251, 0xffff0000, v221
	v_lshlrev_b32_e32 v32, 16, v222
	v_and_b32_e32 v33, 0xffff0000, v222
	v_lshlrev_b32_e32 v34, 16, v223
	v_and_b32_e32 v35, 0xffff0000, v223
	v_lshlrev_b32_e32 v36, 16, v224
	v_and_b32_e32 v37, 0xffff0000, v224
	v_lshlrev_b32_e32 v38, 16, v225
	v_and_b32_e32 v39, 0xffff0000, v225
	v_lshlrev_b32_e32 v20, 16, v226
	v_and_b32_e32 v21, 0xffff0000, v226
	v_lshlrev_b32_e32 v22, 16, v227
	v_and_b32_e32 v23, 0xffff0000, v227
	v_pk_add_f32 v[228:229], v[126:127], v[128:129]
	v_pk_add_f32 v[228:229], v[228:229], v[130:131]
	v_pk_add_f32 v[228:229], v[228:229], v[132:133]
	v_pk_add_f32 v[228:229], v[228:229], v[240:241]
	v_pk_add_f32 v[228:229], v[228:229], v[242:243]
	v_pk_add_f32 v[228:229], v[228:229], v[244:245]
	v_pk_add_f32 v[228:229], v[228:229], v[246:247]
	v_pk_add_f32 v[228:229], v[228:229], v[248:249]
	v_pk_add_f32 v[228:229], v[228:229], v[250:251]
	v_pk_add_f32 v[228:229], v[228:229], v[32:33]
	v_pk_add_f32 v[228:229], v[228:229], v[34:35]
	v_pk_add_f32 v[228:229], v[228:229], v[36:37]
	v_pk_add_f32 v[228:229], v[228:229], v[38:39]
	v_pk_add_f32 v[228:229], v[228:229], v[20:21]
	v_pk_add_f32 v[228:229], v[228:229], v[22:23]
	v_add_f32_e32 v228, v228, v229
	s_nop 1
	v_add_f32_dpp v228, v228, v228 quad_perm:[1,0,3,2] row_mask:0xf bank_mask:0xf bound_ctrl:1
	s_nop 1
	v_add_f32_dpp v228, v228, v228 quad_perm:[2,3,0,1] row_mask:0xf bank_mask:0xf bound_ctrl:1
	s_nop 1
	v_add_f32_dpp v228, v228, v228 row_half_mirror row_mask:0xf bank_mask:0xf bound_ctrl:1
	s_nop 1
	v_add_f32_dpp v228, v228, v228 row_mirror row_mask:0xf bank_mask:0xf bound_ctrl:1
	v_mov_b32_e32 v2, v228
	s_nop 1
	v_permlane16_swap_b32 v228, v2
	s_nop 0
	v_add_f32_e32 v228, v228, v2
	v_mov_b32_e32 v2, v228
	s_nop 1
	v_permlane32_swap_b32 v228, v2
	s_nop 0
	v_add_f32_e32 v228, v228, v2
	v_mul_f32_e32 v134, 0x3a000000, v228
	v_pk_add_f32 v[126:127], v[126:127], v[134:135] op_sel_hi:[1,0] neg_lo:[0,1] neg_hi:[0,1]
	v_pk_add_f32 v[128:129], v[128:129], v[134:135] op_sel_hi:[1,0] neg_lo:[0,1] neg_hi:[0,1]
	v_pk_add_f32 v[130:131], v[130:131], v[134:135] op_sel_hi:[1,0] neg_lo:[0,1] neg_hi:[0,1]
	v_pk_add_f32 v[132:133], v[132:133], v[134:135] op_sel_hi:[1,0] neg_lo:[0,1] neg_hi:[0,1]
	v_pk_add_f32 v[240:241], v[240:241], v[134:135] op_sel_hi:[1,0] neg_lo:[0,1] neg_hi:[0,1]
	v_pk_add_f32 v[242:243], v[242:243], v[134:135] op_sel_hi:[1,0] neg_lo:[0,1] neg_hi:[0,1]
	v_pk_add_f32 v[244:245], v[244:245], v[134:135] op_sel_hi:[1,0] neg_lo:[0,1] neg_hi:[0,1]
	v_pk_add_f32 v[246:247], v[246:247], v[134:135] op_sel_hi:[1,0] neg_lo:[0,1] neg_hi:[0,1]
	v_pk_add_f32 v[248:249], v[248:249], v[134:135] op_sel_hi:[1,0] neg_lo:[0,1] neg_hi:[0,1]
	v_pk_add_f32 v[250:251], v[250:251], v[134:135] op_sel_hi:[1,0] neg_lo:[0,1] neg_hi:[0,1]
	v_pk_add_f32 v[32:33], v[32:33], v[134:135] op_sel_hi:[1,0] neg_lo:[0,1] neg_hi:[0,1]
	v_pk_add_f32 v[34:35], v[34:35], v[134:135] op_sel_hi:[1,0] neg_lo:[0,1] neg_hi:[0,1]
	v_pk_add_f32 v[36:37], v[36:37], v[134:135] op_sel_hi:[1,0] neg_lo:[0,1] neg_hi:[0,1]
	v_pk_add_f32 v[38:39], v[38:39], v[134:135] op_sel_hi:[1,0] neg_lo:[0,1] neg_hi:[0,1]
	v_pk_add_f32 v[20:21], v[20:21], v[134:135] op_sel_hi:[1,0] neg_lo:[0,1] neg_hi:[0,1]
	v_pk_add_f32 v[22:23], v[22:23], v[134:135] op_sel_hi:[1,0] neg_lo:[0,1] neg_hi:[0,1]
	v_pk_mul_f32 v[228:229], v[126:127], v[126:127]
	v_pk_fma_f32 v[228:229], v[128:129], v[128:129], v[228:229]
	v_pk_fma_f32 v[228:229], v[130:131], v[130:131], v[228:229]
	v_pk_fma_f32 v[228:229], v[132:133], v[132:133], v[228:229]
	v_pk_fma_f32 v[228:229], v[240:241], v[240:241], v[228:229]
	v_pk_fma_f32 v[228:229], v[242:243], v[242:243], v[228:229]
	v_pk_fma_f32 v[228:229], v[244:245], v[244:245], v[228:229]
	v_pk_fma_f32 v[228:229], v[246:247], v[246:247], v[228:229]
	v_pk_fma_f32 v[228:229], v[248:249], v[248:249], v[228:229]
	v_pk_fma_f32 v[228:229], v[250:251], v[250:251], v[228:229]
	v_pk_fma_f32 v[228:229], v[32:33], v[32:33], v[228:229]
	v_pk_fma_f32 v[228:229], v[34:35], v[34:35], v[228:229]
	v_pk_fma_f32 v[228:229], v[36:37], v[36:37], v[228:229]
	v_pk_fma_f32 v[228:229], v[38:39], v[38:39], v[228:229]
	v_pk_fma_f32 v[228:229], v[20:21], v[20:21], v[228:229]
	v_pk_fma_f32 v[228:229], v[22:23], v[22:23], v[228:229]
	v_add_f32_e32 v228, v228, v229
	s_nop 1
	v_add_f32_dpp v228, v228, v228 quad_perm:[1,0,3,2] row_mask:0xf bank_mask:0xf bound_ctrl:1
	s_nop 1
	v_add_f32_dpp v228, v228, v228 quad_perm:[2,3,0,1] row_mask:0xf bank_mask:0xf bound_ctrl:1
	s_nop 1
	v_add_f32_dpp v228, v228, v228 row_half_mirror row_mask:0xf bank_mask:0xf bound_ctrl:1
	s_nop 1
	v_add_f32_dpp v228, v228, v228 row_mirror row_mask:0xf bank_mask:0xf bound_ctrl:1
	v_mov_b32_e32 v2, v228
	s_nop 1
	v_permlane16_swap_b32 v228, v2
	s_nop 0
	v_add_f32_e32 v228, v228, v2
	v_mov_b32_e32 v2, v228
	s_nop 1
	v_permlane32_swap_b32 v228, v2
	s_nop 0
	v_add_f32_e32 v228, v228, v2
	v_mul_f32_e32 v0, 0x3a000000, v228
	v_add_f32_e32 v0, 0x3727c5ac, v0
	v_rsq_f32_e32 v0, v0
	s_nop 0
	v_pk_mul_f32 v[228:229], v[140:141], v[0:1] op_sel_hi:[1,0]
	v_pk_fma_f32 v[126:127], v[126:127], v[228:229], v[172:173]
	v_pk_mul_f32 v[228:229], v[142:143], v[0:1] op_sel_hi:[1,0]
	v_pk_fma_f32 v[128:129], v[128:129], v[228:229], v[174:175]
	v_pk_mul_f32 v[228:229], v[144:145], v[0:1] op_sel_hi:[1,0]
	v_pk_fma_f32 v[130:131], v[130:131], v[228:229], v[176:177]
	v_pk_mul_f32 v[228:229], v[146:147], v[0:1] op_sel_hi:[1,0]
	v_pk_fma_f32 v[132:133], v[132:133], v[228:229], v[178:179]
	v_pk_mul_f32 v[228:229], v[148:149], v[0:1] op_sel_hi:[1,0]
	v_pk_fma_f32 v[240:241], v[240:241], v[228:229], v[180:181]
	v_pk_mul_f32 v[228:229], v[150:151], v[0:1] op_sel_hi:[1,0]
	v_pk_fma_f32 v[242:243], v[242:243], v[228:229], v[182:183]
	v_pk_mul_f32 v[228:229], v[152:153], v[0:1] op_sel_hi:[1,0]
	v_pk_fma_f32 v[244:245], v[244:245], v[228:229], v[184:185]
	v_pk_mul_f32 v[228:229], v[154:155], v[0:1] op_sel_hi:[1,0]
	v_pk_fma_f32 v[246:247], v[246:247], v[228:229], v[186:187]
	v_pk_mul_f32 v[228:229], v[156:157], v[0:1] op_sel_hi:[1,0]
	v_pk_fma_f32 v[248:249], v[248:249], v[228:229], v[188:189]
	v_pk_mul_f32 v[228:229], v[158:159], v[0:1] op_sel_hi:[1,0]
	v_pk_fma_f32 v[250:251], v[250:251], v[228:229], v[190:191]
	v_pk_mul_f32 v[228:229], v[160:161], v[0:1] op_sel_hi:[1,0]
	v_pk_fma_f32 v[32:33], v[32:33], v[228:229], v[192:193]
	v_pk_mul_f32 v[228:229], v[162:163], v[0:1] op_sel_hi:[1,0]
	v_pk_fma_f32 v[34:35], v[34:35], v[228:229], v[194:195]
	v_pk_mul_f32 v[228:229], v[164:165], v[0:1] op_sel_hi:[1,0]
	v_pk_fma_f32 v[36:37], v[36:37], v[228:229], v[196:197]
	v_pk_mul_f32 v[228:229], v[166:167], v[0:1] op_sel_hi:[1,0]
	v_pk_fma_f32 v[38:39], v[38:39], v[228:229], v[198:199]
	v_pk_mul_f32 v[228:229], v[168:169], v[0:1] op_sel_hi:[1,0]
	v_pk_fma_f32 v[20:21], v[20:21], v[228:229], v[200:201]
	v_pk_mul_f32 v[228:229], v[170:171], v[0:1] op_sel_hi:[1,0]
	v_pk_fma_f32 v[22:23], v[22:23], v[228:229], v[202:203]
	v_cvt_pk_bf16_f32 v24, v126, v127
	v_cvt_pk_bf16_f32 v25, v128, v129
	v_cvt_pk_bf16_f32 v26, v130, v131
	v_cvt_pk_bf16_f32 v27, v132, v133
	v_cvt_pk_bf16_f32 v8, v240, v241
	v_cvt_pk_bf16_f32 v9, v242, v243
	v_cvt_pk_bf16_f32 v10, v244, v245
	v_cvt_pk_bf16_f32 v11, v246, v247
	v_cvt_pk_bf16_f32 v220, v248, v249
	v_cvt_pk_bf16_f32 v221, v250, v251
	v_cvt_pk_bf16_f32 v222, v32, v33
	v_cvt_pk_bf16_f32 v223, v34, v35
	v_cvt_pk_bf16_f32 v224, v36, v37
	v_cvt_pk_bf16_f32 v225, v38, v39
	v_cvt_pk_bf16_f32 v226, v20, v21
	v_cvt_pk_bf16_f32 v227, v22, v23
	global_store_dwordx2 v1, v[24:25], s[90:91] offset:0
	global_store_dwordx2 v1, v[26:27], s[90:91] offset:512
	global_store_dwordx2 v1, v[8:9], s[90:91] offset:1024
	global_store_dwordx2 v1, v[10:11], s[90:91] offset:1536
	global_store_dwordx2 v1, v[220:221], s[90:91] offset:2048
	global_store_dwordx2 v1, v[222:223], s[90:91] offset:2560
	global_store_dwordx2 v1, v[224:225], s[90:91] offset:3072
	global_store_dwordx2 v1, v[226:227], s[90:91] offset:3584
	s_add_u32 s90, s90, 0x800000
	s_addc_u32 s91, s91, 0
	s_waitcnt vmcnt(16)
	v_lshlrev_b32_e32 v126, 16, v204
	v_and_b32_e32 v127, 0xffff0000, v204
	v_lshlrev_b32_e32 v128, 16, v205
	v_and_b32_e32 v129, 0xffff0000, v205
	v_lshlrev_b32_e32 v130, 16, v206
	v_and_b32_e32 v131, 0xffff0000, v206
	v_lshlrev_b32_e32 v132, 16, v207
	v_and_b32_e32 v133, 0xffff0000, v207
	v_lshlrev_b32_e32 v240, 16, v208
	v_and_b32_e32 v241, 0xffff0000, v208
	v_lshlrev_b32_e32 v242, 16, v209
	v_and_b32_e32 v243, 0xffff0000, v209
	v_lshlrev_b32_e32 v244, 16, v210
	v_and_b32_e32 v245, 0xffff0000, v210
	v_lshlrev_b32_e32 v246, 16, v211
	v_and_b32_e32 v247, 0xffff0000, v211
	v_lshlrev_b32_e32 v248, 16, v212
	v_and_b32_e32 v249, 0xffff0000, v212
	v_lshlrev_b32_e32 v250, 16, v213
	v_and_b32_e32 v251, 0xffff0000, v213
	v_lshlrev_b32_e32 v32, 16, v214
	v_and_b32_e32 v33, 0xffff0000, v214
	v_lshlrev_b32_e32 v34, 16, v215
	v_and_b32_e32 v35, 0xffff0000, v215
	v_lshlrev_b32_e32 v36, 16, v216
	v_and_b32_e32 v37, 0xffff0000, v216
	v_lshlrev_b32_e32 v38, 16, v217
	v_and_b32_e32 v39, 0xffff0000, v217
	v_lshlrev_b32_e32 v20, 16, v218
	v_and_b32_e32 v21, 0xffff0000, v218
	v_lshlrev_b32_e32 v22, 16, v219
	v_and_b32_e32 v23, 0xffff0000, v219
	v_pk_add_f32 v[228:229], v[126:127], v[128:129]
	v_pk_add_f32 v[228:229], v[228:229], v[130:131]
	v_pk_add_f32 v[228:229], v[228:229], v[132:133]
	v_pk_add_f32 v[228:229], v[228:229], v[240:241]
	v_pk_add_f32 v[228:229], v[228:229], v[242:243]
	v_pk_add_f32 v[228:229], v[228:229], v[244:245]
	v_pk_add_f32 v[228:229], v[228:229], v[246:247]
	v_pk_add_f32 v[228:229], v[228:229], v[248:249]
	v_pk_add_f32 v[228:229], v[228:229], v[250:251]
	v_pk_add_f32 v[228:229], v[228:229], v[32:33]
	v_pk_add_f32 v[228:229], v[228:229], v[34:35]
	v_pk_add_f32 v[228:229], v[228:229], v[36:37]
	v_pk_add_f32 v[228:229], v[228:229], v[38:39]
	v_pk_add_f32 v[228:229], v[228:229], v[20:21]
	v_pk_add_f32 v[228:229], v[228:229], v[22:23]
	v_add_f32_e32 v228, v228, v229
	s_nop 1
	v_add_f32_dpp v228, v228, v228 quad_perm:[1,0,3,2] row_mask:0xf bank_mask:0xf bound_ctrl:1
	s_nop 1
	v_add_f32_dpp v228, v228, v228 quad_perm:[2,3,0,1] row_mask:0xf bank_mask:0xf bound_ctrl:1
	s_nop 1
	v_add_f32_dpp v228, v228, v228 row_half_mirror row_mask:0xf bank_mask:0xf bound_ctrl:1
	s_nop 1
	v_add_f32_dpp v228, v228, v228 row_mirror row_mask:0xf bank_mask:0xf bound_ctrl:1
	v_mov_b32_e32 v2, v228
	s_nop 1
	v_permlane16_swap_b32 v228, v2
	s_nop 0
	v_add_f32_e32 v228, v228, v2
	v_mov_b32_e32 v2, v228
	s_nop 1
	v_permlane32_swap_b32 v228, v2
	s_nop 0
	v_add_f32_e32 v228, v228, v2
	v_mul_f32_e32 v134, 0x3a000000, v228
	v_pk_add_f32 v[126:127], v[126:127], v[134:135] op_sel_hi:[1,0] neg_lo:[0,1] neg_hi:[0,1]
	v_pk_add_f32 v[128:129], v[128:129], v[134:135] op_sel_hi:[1,0] neg_lo:[0,1] neg_hi:[0,1]
	v_pk_add_f32 v[130:131], v[130:131], v[134:135] op_sel_hi:[1,0] neg_lo:[0,1] neg_hi:[0,1]
	v_pk_add_f32 v[132:133], v[132:133], v[134:135] op_sel_hi:[1,0] neg_lo:[0,1] neg_hi:[0,1]
	v_pk_add_f32 v[240:241], v[240:241], v[134:135] op_sel_hi:[1,0] neg_lo:[0,1] neg_hi:[0,1]
	v_pk_add_f32 v[242:243], v[242:243], v[134:135] op_sel_hi:[1,0] neg_lo:[0,1] neg_hi:[0,1]
	v_pk_add_f32 v[244:245], v[244:245], v[134:135] op_sel_hi:[1,0] neg_lo:[0,1] neg_hi:[0,1]
	v_pk_add_f32 v[246:247], v[246:247], v[134:135] op_sel_hi:[1,0] neg_lo:[0,1] neg_hi:[0,1]
	v_pk_add_f32 v[248:249], v[248:249], v[134:135] op_sel_hi:[1,0] neg_lo:[0,1] neg_hi:[0,1]
	v_pk_add_f32 v[250:251], v[250:251], v[134:135] op_sel_hi:[1,0] neg_lo:[0,1] neg_hi:[0,1]
	v_pk_add_f32 v[32:33], v[32:33], v[134:135] op_sel_hi:[1,0] neg_lo:[0,1] neg_hi:[0,1]
	v_pk_add_f32 v[34:35], v[34:35], v[134:135] op_sel_hi:[1,0] neg_lo:[0,1] neg_hi:[0,1]
	v_pk_add_f32 v[36:37], v[36:37], v[134:135] op_sel_hi:[1,0] neg_lo:[0,1] neg_hi:[0,1]
	v_pk_add_f32 v[38:39], v[38:39], v[134:135] op_sel_hi:[1,0] neg_lo:[0,1] neg_hi:[0,1]
	v_pk_add_f32 v[20:21], v[20:21], v[134:135] op_sel_hi:[1,0] neg_lo:[0,1] neg_hi:[0,1]
	v_pk_add_f32 v[22:23], v[22:23], v[134:135] op_sel_hi:[1,0] neg_lo:[0,1] neg_hi:[0,1]
	v_pk_mul_f32 v[228:229], v[126:127], v[126:127]
	v_pk_fma_f32 v[228:229], v[128:129], v[128:129], v[228:229]
	v_pk_fma_f32 v[228:229], v[130:131], v[130:131], v[228:229]
	v_pk_fma_f32 v[228:229], v[132:133], v[132:133], v[228:229]
	v_pk_fma_f32 v[228:229], v[240:241], v[240:241], v[228:229]
	v_pk_fma_f32 v[228:229], v[242:243], v[242:243], v[228:229]
	v_pk_fma_f32 v[228:229], v[244:245], v[244:245], v[228:229]
	v_pk_fma_f32 v[228:229], v[246:247], v[246:247], v[228:229]
	v_pk_fma_f32 v[228:229], v[248:249], v[248:249], v[228:229]
	v_pk_fma_f32 v[228:229], v[250:251], v[250:251], v[228:229]
	v_pk_fma_f32 v[228:229], v[32:33], v[32:33], v[228:229]
	v_pk_fma_f32 v[228:229], v[34:35], v[34:35], v[228:229]
	v_pk_fma_f32 v[228:229], v[36:37], v[36:37], v[228:229]
	v_pk_fma_f32 v[228:229], v[38:39], v[38:39], v[228:229]
	v_pk_fma_f32 v[228:229], v[20:21], v[20:21], v[228:229]
	v_pk_fma_f32 v[228:229], v[22:23], v[22:23], v[228:229]
	v_add_f32_e32 v228, v228, v229
	s_nop 1
	v_add_f32_dpp v228, v228, v228 quad_perm:[1,0,3,2] row_mask:0xf bank_mask:0xf bound_ctrl:1
	s_nop 1
	v_add_f32_dpp v228, v228, v228 quad_perm:[2,3,0,1] row_mask:0xf bank_mask:0xf bound_ctrl:1
	s_nop 1
	v_add_f32_dpp v228, v228, v228 row_half_mirror row_mask:0xf bank_mask:0xf bound_ctrl:1
	s_nop 1
	v_add_f32_dpp v228, v228, v228 row_mirror row_mask:0xf bank_mask:0xf bound_ctrl:1
	v_mov_b32_e32 v2, v228
	s_nop 1
	v_permlane16_swap_b32 v228, v2
	s_nop 0
	v_add_f32_e32 v228, v228, v2
	v_mov_b32_e32 v2, v228
	s_nop 1
	v_permlane32_swap_b32 v228, v2
	s_nop 0
	v_add_f32_e32 v228, v228, v2
	v_mul_f32_e32 v0, 0x3a000000, v228
	v_add_f32_e32 v0, 0x3727c5ac, v0
	v_rsq_f32_e32 v0, v0
	s_nop 0
	v_pk_mul_f32 v[228:229], v[140:141], v[0:1] op_sel_hi:[1,0]
	v_pk_fma_f32 v[126:127], v[126:127], v[228:229], v[172:173]
	v_pk_mul_f32 v[228:229], v[142:143], v[0:1] op_sel_hi:[1,0]
	v_pk_fma_f32 v[128:129], v[128:129], v[228:229], v[174:175]
	v_pk_mul_f32 v[228:229], v[144:145], v[0:1] op_sel_hi:[1,0]
	v_pk_fma_f32 v[130:131], v[130:131], v[228:229], v[176:177]
	v_pk_mul_f32 v[228:229], v[146:147], v[0:1] op_sel_hi:[1,0]
	v_pk_fma_f32 v[132:133], v[132:133], v[228:229], v[178:179]
	v_pk_mul_f32 v[228:229], v[148:149], v[0:1] op_sel_hi:[1,0]
	v_pk_fma_f32 v[240:241], v[240:241], v[228:229], v[180:181]
	v_pk_mul_f32 v[228:229], v[150:151], v[0:1] op_sel_hi:[1,0]
	v_pk_fma_f32 v[242:243], v[242:243], v[228:229], v[182:183]
	v_pk_mul_f32 v[228:229], v[152:153], v[0:1] op_sel_hi:[1,0]
	v_pk_fma_f32 v[244:245], v[244:245], v[228:229], v[184:185]
	v_pk_mul_f32 v[228:229], v[154:155], v[0:1] op_sel_hi:[1,0]
	v_pk_fma_f32 v[246:247], v[246:247], v[228:229], v[186:187]
	v_pk_mul_f32 v[228:229], v[156:157], v[0:1] op_sel_hi:[1,0]
	v_pk_fma_f32 v[248:249], v[248:249], v[228:229], v[188:189]
	v_pk_mul_f32 v[228:229], v[158:159], v[0:1] op_sel_hi:[1,0]
	v_pk_fma_f32 v[250:251], v[250:251], v[228:229], v[190:191]
	v_pk_mul_f32 v[228:229], v[160:161], v[0:1] op_sel_hi:[1,0]
	v_pk_fma_f32 v[32:33], v[32:33], v[228:229], v[192:193]
	v_pk_mul_f32 v[228:229], v[162:163], v[0:1] op_sel_hi:[1,0]
	v_pk_fma_f32 v[34:35], v[34:35], v[228:229], v[194:195]
	v_pk_mul_f32 v[228:229], v[164:165], v[0:1] op_sel_hi:[1,0]
	v_pk_fma_f32 v[36:37], v[36:37], v[228:229], v[196:197]
	v_pk_mul_f32 v[228:229], v[166:167], v[0:1] op_sel_hi:[1,0]
	v_pk_fma_f32 v[38:39], v[38:39], v[228:229], v[198:199]
	v_pk_mul_f32 v[228:229], v[168:169], v[0:1] op_sel_hi:[1,0]
	v_pk_fma_f32 v[20:21], v[20:21], v[228:229], v[200:201]
	v_pk_mul_f32 v[228:229], v[170:171], v[0:1] op_sel_hi:[1,0]
	v_pk_fma_f32 v[22:23], v[22:23], v[228:229], v[202:203]
	v_cvt_pk_bf16_f32 v204, v126, v127
	v_cvt_pk_bf16_f32 v205, v128, v129
	v_cvt_pk_bf16_f32 v206, v130, v131
	v_cvt_pk_bf16_f32 v207, v132, v133
	v_cvt_pk_bf16_f32 v208, v240, v241
	v_cvt_pk_bf16_f32 v209, v242, v243
	v_cvt_pk_bf16_f32 v210, v244, v245
	v_cvt_pk_bf16_f32 v211, v246, v247
	v_cvt_pk_bf16_f32 v212, v248, v249
	v_cvt_pk_bf16_f32 v213, v250, v251
	v_cvt_pk_bf16_f32 v214, v32, v33
	v_cvt_pk_bf16_f32 v215, v34, v35
	v_cvt_pk_bf16_f32 v216, v36, v37
	v_cvt_pk_bf16_f32 v217, v38, v39
	v_cvt_pk_bf16_f32 v218, v20, v21
	v_cvt_pk_bf16_f32 v219, v22, v23
	global_store_dwordx2 v1, v[204:205], s[90:91] offset:0
	global_store_dwordx2 v1, v[206:207], s[90:91] offset:512
	global_store_dwordx2 v1, v[208:209], s[90:91] offset:1024
	global_store_dwordx2 v1, v[210:211], s[90:91] offset:1536
	global_store_dwordx2 v1, v[212:213], s[90:91] offset:2048
	global_store_dwordx2 v1, v[214:215], s[90:91] offset:2560
	global_store_dwordx2 v1, v[216:217], s[90:91] offset:3072
	global_store_dwordx2 v1, v[218:219], s[90:91] offset:3584
	s_add_u32 s90, s90, 0x800000
	s_addc_u32 s91, s91, 0

.LBB0_2453:
	s_cmp_lt_i32 s30, 19
	s_cselect_b64 s[4:5], -1, 0
	s_and_b64 s[4:5], s[4:5], s[6:7]
	s_andn2_b64 vcc, exec, s[4:5]
	s_cbranch_vccnz .LBB0_2469
	s_load_dwordx4 s[8:11], s[0:1], 0x158
	s_load_dwordx2 s[6:7], s[0:1], 0x168
	v_lshl_add_u32 v32, s2, 3, v230
	s_movk_i32 s3, 0x2000
	v_cmp_gt_i32_e32 vcc, s3, v32
	s_waitcnt lgkmcnt(0)
	s_mov_b64 s[14:15], 0
	s_cmp_lg_u64 s[6:7], 0
	s_cselect_b64 s[12:13], -1, 0
	s_and_saveexec_b64 s[16:17], vcc
	s_cbranch_execz .LBB0_2461
	s_load_dwordx4 s[60:63], s[0:1], 0x158
	s_load_dwordx2 s[92:93], s[0:1], 0x168
	v_lshl_add_u32 v2, s2, 3, v230
	v_lshlrev_b32_e32 v137, 4, v136
	v_lshlrev_b32_e32 v1, 3, v136
	v_lshl_add_u32 v1, v2, 12, v1
	v_add_u32_e32 v4, 0x1000, v137
	v_lshl_add_u32 v75, v2, 13, v137
	v_add_u32_e32 v135, 0x1000, v75
	s_add_u32 s88, s28, 0xe600000
	s_addc_u32 s89, s29, 0
	global_load_dwordx2 v[204:205], v1, s[88:89] offset:0
	global_load_dwordx2 v[206:207], v1, s[88:89] offset:512
	global_load_dwordx2 v[208:209], v1, s[88:89] offset:1024
	global_load_dwordx2 v[210:211], v1, s[88:89] offset:1536
	global_load_dwordx2 v[212:213], v1, s[88:89] offset:2048
	global_load_dwordx2 v[214:215], v1, s[88:89] offset:2560
	global_load_dwordx2 v[216:217], v1, s[88:89] offset:3072
	global_load_dwordx2 v[218:219], v1, s[88:89] offset:3584
	s_add_u32 s88, s88, 0x800000
	s_addc_u32 s89, s89, 0
	s_waitcnt lgkmcnt(0)
	global_load_dwordx4 v[140:143], v137, s[60:61] offset:0
	global_load_dwordx4 v[144:147], v137, s[60:61] offset:1024
	global_load_dwordx4 v[148:151], v137, s[60:61] offset:2048
	global_load_dwordx4 v[152:155], v137, s[60:61] offset:3072
	global_load_dwordx4 v[156:159], v4, s[60:61] offset:0
	global_load_dwordx4 v[160:163], v4, s[60:61] offset:1024
	global_load_dwordx4 v[164:167], v4, s[60:61] offset:2048
	global_load_dwordx4 v[168:171], v4, s[60:61] offset:3072
	global_load_dwordx4 v[172:175], v137, s[62:63] offset:0
	global_load_dwordx4 v[176:179], v137, s[62:63] offset:1024
	global_load_dwordx4 v[180:183], v137, s[62:63] offset:2048
	global_load_dwordx4 v[184:187], v137, s[62:63] offset:3072
	global_load_dwordx4 v[188:191], v4, s[62:63] offset:0
	global_load_dwordx4 v[192:195], v4, s[62:63] offset:1024
	global_load_dwordx4 v[196:199], v4, s[62:63] offset:2048
	global_load_dwordx4 v[200:203], v4, s[62:63] offset:3072
	global_load_dwordx2 v[110:111], v1, s[88:89] offset:0
	global_load_dwordx2 v[112:113], v1, s[88:89] offset:512
	global_load_dwordx2 v[114:115], v1, s[88:89] offset:1024
	global_load_dwordx2 v[116:117], v1, s[88:89] offset:1536
	global_load_dwordx2 v[118:119], v1, s[88:89] offset:2048
	global_load_dwordx2 v[120:121], v1, s[88:89] offset:2560
	global_load_dwordx2 v[122:123], v1, s[88:89] offset:3072
	global_load_dwordx2 v[124:125], v1, s[88:89] offset:3584
	s_add_u32 s88, s88, 0x800000
	s_addc_u32 s89, s89, 0
	global_load_dwordx2 v[24:25], v1, s[88:89] offset:0
	global_load_dwordx2 v[26:27], v1, s[88:89] offset:512
	global_load_dwordx2 v[8:9], v1, s[88:89] offset:1024
	global_load_dwordx2 v[10:11], v1, s[88:89] offset:1536
	global_load_dwordx2 v[220:221], v1, s[88:89] offset:2048
	global_load_dwordx2 v[222:223], v1, s[88:89] offset:2560
	global_load_dwordx2 v[224:225], v1, s[88:89] offset:3072
	global_load_dwordx2 v[226:227], v1, s[88:89] offset:3584
	s_add_u32 s88, s88, 0x800000
	s_addc_u32 s89, s89, 0
	s_mov_b64 s[90:91], s[92:93]
	s_waitcnt vmcnt(32)
	v_lshlrev_b32_e32 v126, 16, v204
	v_and_b32_e32 v127, 0xffff0000, v204
	v_lshlrev_b32_e32 v128, 16, v205
	v_and_b32_e32 v129, 0xffff0000, v205
	v_lshlrev_b32_e32 v130, 16, v206
	v_and_b32_e32 v131, 0xffff0000, v206
	v_lshlrev_b32_e32 v132, 16, v207
	v_and_b32_e32 v133, 0xffff0000, v207
	v_lshlrev_b32_e32 v240, 16, v208
	v_and_b32_e32 v241, 0xffff0000, v208
	v_lshlrev_b32_e32 v242, 16, v209
	v_and_b32_e32 v243, 0xffff0000, v209
	v_lshlrev_b32_e32 v244, 16, v210
	v_and_b32_e32 v245, 0xffff0000, v210
	v_lshlrev_b32_e32 v246, 16, v211
	v_and_b32_e32 v247, 0xffff0000, v211
	v_lshlrev_b32_e32 v248, 16, v212
	v_and_b32_e32 v249, 0xffff0000, v212
	v_lshlrev_b32_e32 v250, 16, v213
	v_and_b32_e32 v251, 0xffff0000, v213
	v_lshlrev_b32_e32 v32, 16, v214
	v_and_b32_e32 v33, 0xffff0000, v214
	v_lshlrev_b32_e32 v34, 16, v215
	v_and_b32_e32 v35, 0xffff0000, v215
	v_lshlrev_b32_e32 v36, 16, v216
	v_and_b32_e32 v37, 0xffff0000, v216
	v_lshlrev_b32_e32 v38, 16, v217
	v_and_b32_e32 v39, 0xffff0000, v217
	v_lshlrev_b32_e32 v20, 16, v218
	v_and_b32_e32 v21, 0xffff0000, v218
	v_lshlrev_b32_e32 v22, 16, v219
	v_and_b32_e32 v23, 0xffff0000, v219
	v_pk_add_f32 v[228:229], v[126:127], v[128:129]
	v_pk_add_f32 v[228:229], v[228:229], v[130:131]
	v_pk_add_f32 v[228:229], v[228:229], v[132:133]
	v_pk_add_f32 v[228:229], v[228:229], v[240:241]
	v_pk_add_f32 v[228:229], v[228:229], v[242:243]
	v_pk_add_f32 v[228:229], v[228:229], v[244:245]
	v_pk_add_f32 v[228:229], v[228:229], v[246:247]
	v_pk_add_f32 v[228:229], v[228:229], v[248:249]
	v_pk_add_f32 v[228:229], v[228:229], v[250:251]
	v_pk_add_f32 v[228:229], v[228:229], v[32:33]
	v_pk_add_f32 v[228:229], v[228:229], v[34:35]
	v_pk_add_f32 v[228:229], v[228:229], v[36:37]
	v_pk_add_f32 v[228:229], v[228:229], v[38:39]
	v_pk_add_f32 v[228:229], v[228:229], v[20:21]
	v_pk_add_f32 v[228:229], v[228:229], v[22:23]
	v_add_f32_e32 v228, v228, v229
	s_nop 1
	v_add_f32_dpp v228, v228, v228 quad_perm:[1,0,3,2] row_mask:0xf bank_mask:0xf bound_ctrl:1
	s_nop 1
	v_add_f32_dpp v228, v228, v228 quad_perm:[2,3,0,1] row_mask:0xf bank_mask:0xf bound_ctrl:1
	s_nop 1
	v_add_f32_dpp v228, v228, v228 row_half_mirror row_mask:0xf bank_mask:0xf bound_ctrl:1
	s_nop 1
	v_add_f32_dpp v228, v228, v228 row_mirror row_mask:0xf bank_mask:0xf bound_ctrl:1
	v_mov_b32_e32 v2, v228
	s_nop 1
	v_permlane16_swap_b32 v228, v2
	s_nop 0
	v_add_f32_e32 v228, v228, v2
	v_mov_b32_e32 v2, v228
	s_nop 1
	v_permlane32_swap_b32 v228, v2
	s_nop 0
	v_add_f32_e32 v228, v228, v2
	v_mul_f32_e32 v134, 0x3a000000, v228
	v_pk_add_f32 v[126:127], v[126:127], v[134:135] op_sel_hi:[1,0] neg_lo:[0,1] neg_hi:[0,1]
	v_pk_add_f32 v[128:129], v[128:129], v[134:135] op_sel_hi:[1,0] neg_lo:[0,1] neg_hi:[0,1]
	v_pk_add_f32 v[130:131], v[130:131], v[134:135] op_sel_hi:[1,0] neg_lo:[0,1] neg_hi:[0,1]
	v_pk_add_f32 v[132:133], v[132:133], v[134:135] op_sel_hi:[1,0] neg_lo:[0,1] neg_hi:[0,1]
	v_pk_add_f32 v[240:241], v[240:241], v[134:135] op_sel_hi:[1,0] neg_lo:[0,1] neg_hi:[0,1]
	v_pk_add_f32 v[242:243], v[242:243], v[134:135] op_sel_hi:[1,0] neg_lo:[0,1] neg_hi:[0,1]
	v_pk_add_f32 v[244:245], v[244:245], v[134:135] op_sel_hi:[1,0] neg_lo:[0,1] neg_hi:[0,1]
	v_pk_add_f32 v[246:247], v[246:247], v[134:135] op_sel_hi:[1,0] neg_lo:[0,1] neg_hi:[0,1]
	v_pk_add_f32 v[248:249], v[248:249], v[134:135] op_sel_hi:[1,0] neg_lo:[0,1] neg_hi:[0,1]
	v_pk_add_f32 v[250:251], v[250:251], v[134:135] op_sel_hi:[1,0] neg_lo:[0,1] neg_hi:[0,1]
	v_pk_add_f32 v[32:33], v[32:33], v[134:135] op_sel_hi:[1,0] neg_lo:[0,1] neg_hi:[0,1]
	v_pk_add_f32 v[34:35], v[34:35], v[134:135] op_sel_hi:[1,0] neg_lo:[0,1] neg_hi:[0,1]
	v_pk_add_f32 v[36:37], v[36:37], v[134:135] op_sel_hi:[1,0] neg_lo:[0,1] neg_hi:[0,1]
	v_pk_add_f32 v[38:39], v[38:39], v[134:135] op_sel_hi:[1,0] neg_lo:[0,1] neg_hi:[0,1]
	v_pk_add_f32 v[20:21], v[20:21], v[134:135] op_sel_hi:[1,0] neg_lo:[0,1] neg_hi:[0,1]
	v_pk_add_f32 v[22:23], v[22:23], v[134:135] op_sel_hi:[1,0] neg_lo:[0,1] neg_hi:[0,1]
	v_pk_mul_f32 v[228:229], v[126:127], v[126:127]
	v_pk_fma_f32 v[228:229], v[128:129], v[128:129], v[228:229]
	v_pk_fma_f32 v[228:229], v[130:131], v[130:131], v[228:229]
	v_pk_fma_f32 v[228:229], v[132:133], v[132:133], v[228:229]
	v_pk_fma_f32 v[228:229], v[240:241], v[240:241], v[228:229]
	v_pk_fma_f32 v[228:229], v[242:243], v[242:243], v[228:229]
	v_pk_fma_f32 v[228:229], v[244:245], v[244:245], v[228:229]
	v_pk_fma_f32 v[228:229], v[246:247], v[246:247], v[228:229]
	v_pk_fma_f32 v[228:229], v[248:249], v[248:249], v[228:229]
	v_pk_fma_f32 v[228:229], v[250:251], v[250:251], v[228:229]
	v_pk_fma_f32 v[228:229], v[32:33], v[32:33], v[228:229]
	v_pk_fma_f32 v[228:229], v[34:35], v[34:35], v[228:229]
	v_pk_fma_f32 v[228:229], v[36:37], v[36:37], v[228:229]
	v_pk_fma_f32 v[228:229], v[38:39], v[38:39], v[228:229]
	v_pk_fma_f32 v[228:229], v[20:21], v[20:21], v[228:229]
	v_pk_fma_f32 v[228:229], v[22:23], v[22:23], v[228:229]
	v_add_f32_e32 v228, v228, v229
	s_nop 1
	v_add_f32_dpp v228, v228, v228 quad_perm:[1,0,3,2] row_mask:0xf bank_mask:0xf bound_ctrl:1
	s_nop 1
	v_add_f32_dpp v228, v228, v228 quad_perm:[2,3,0,1] row_mask:0xf bank_mask:0xf bound_ctrl:1
	s_nop 1
	v_add_f32_dpp v228, v228, v228 row_half_mirror row_mask:0xf bank_mask:0xf bound_ctrl:1
	s_nop 1
	v_add_f32_dpp v228, v228, v228 row_mirror row_mask:0xf bank_mask:0xf bound_ctrl:1
	v_mov_b32_e32 v2, v228
	s_nop 1
	v_permlane16_swap_b32 v228, v2
	s_nop 0
	v_add_f32_e32 v228, v228, v2
	v_mov_b32_e32 v2, v228
	s_nop 1
	v_permlane32_swap_b32 v228, v2
	s_nop 0
	v_add_f32_e32 v228, v228, v2
	v_mul_f32_e32 v0, 0x3a000000, v228
	v_add_f32_e32 v0, 0x3727c5ac, v0
	v_rsq_f32_e32 v0, v0
	s_waitcnt vmcnt(16)
	v_pk_mul_f32 v[228:229], v[140:141], v[0:1] op_sel_hi:[1,0]
	v_pk_fma_f32 v[126:127], v[126:127], v[228:229], v[172:173]
	v_pk_mul_f32 v[228:229], v[142:143], v[0:1] op_sel_hi:[1,0]
	v_pk_fma_f32 v[128:129], v[128:129], v[228:229], v[174:175]
	v_pk_mul_f32 v[228:229], v[144:145], v[0:1] op_sel_hi:[1,0]
	v_pk_fma_f32 v[130:131], v[130:131], v[228:229], v[176:177]
	v_pk_mul_f32 v[228:229], v[146:147], v[0:1] op_sel_hi:[1,0]
	v_pk_fma_f32 v[132:133], v[132:133], v[228:229], v[178:179]
	v_pk_mul_f32 v[228:229], v[148:149], v[0:1] op_sel_hi:[1,0]
	v_pk_fma_f32 v[240:241], v[240:241], v[228:229], v[180:181]
	v_pk_mul_f32 v[228:229], v[150:151], v[0:1] op_sel_hi:[1,0]
	v_pk_fma_f32 v[242:243], v[242:243], v[228:229], v[182:183]
	v_pk_mul_f32 v[228:229], v[152:153], v[0:1] op_sel_hi:[1,0]
	v_pk_fma_f32 v[244:245], v[244:245], v[228:229], v[184:185]
	v_pk_mul_f32 v[228:229], v[154:155], v[0:1] op_sel_hi:[1,0]
	v_pk_fma_f32 v[246:247], v[246:247], v[228:229], v[186:187]
	v_pk_mul_f32 v[228:229], v[156:157], v[0:1] op_sel_hi:[1,0]
	v_pk_fma_f32 v[248:249], v[248:249], v[228:229], v[188:189]
	v_pk_mul_f32 v[228:229], v[158:159], v[0:1] op_sel_hi:[1,0]
	v_pk_fma_f32 v[250:251], v[250:251], v[228:229], v[190:191]
	v_pk_mul_f32 v[228:229], v[160:161], v[0:1] op_sel_hi:[1,0]
	v_pk_fma_f32 v[32:33], v[32:33], v[228:229], v[192:193]
	v_pk_mul_f32 v[228:229], v[162:163], v[0:1] op_sel_hi:[1,0]
	v_pk_fma_f32 v[34:35], v[34:35], v[228:229], v[194:195]
	v_pk_mul_f32 v[228:229], v[164:165], v[0:1] op_sel_hi:[1,0]
	v_pk_fma_f32 v[36:37], v[36:37], v[228:229], v[196:197]
	v_pk_mul_f32 v[228:229], v[166:167], v[0:1] op_sel_hi:[1,0]
	v_pk_fma_f32 v[38:39], v[38:39], v[228:229], v[198:199]
	v_pk_mul_f32 v[228:229], v[168:169], v[0:1] op_sel_hi:[1,0]
	v_pk_fma_f32 v[20:21], v[20:21], v[228:229], v[200:201]
	v_pk_mul_f32 v[228:229], v[170:171], v[0:1] op_sel_hi:[1,0]
	v_pk_fma_f32 v[22:23], v[22:23], v[228:229], v[202:203]
	global_store_dwordx4 v75, v[126:129], s[90:91] offset:0
	global_store_dwordx4 v75, v[130:133], s[90:91] offset:1024
	global_store_dwordx4 v75, v[240:243], s[90:91] offset:2048
	global_store_dwordx4 v75, v[244:247], s[90:91] offset:3072
	global_store_dwordx4 v135, v[248:251], s[90:91] offset:0
	global_store_dwordx4 v135, v[32:35], s[90:91] offset:1024
	global_store_dwordx4 v135, v[36:39], s[90:91] offset:2048
	global_store_dwordx4 v135, v[20:23], s[90:91] offset:3072
	s_add_u32 s90, s90, 0x1000000
	s_addc_u32 s91, s91, 0
	global_load_dwordx2 v[204:205], v1, s[88:89] offset:0
	global_load_dwordx2 v[206:207], v1, s[88:89] offset:512
	global_load_dwordx2 v[208:209], v1, s[88:89] offset:1024
	global_load_dwordx2 v[210:211], v1, s[88:89] offset:1536
	global_load_dwordx2 v[212:213], v1, s[88:89] offset:2048
	global_load_dwordx2 v[214:215], v1, s[88:89] offset:2560
	global_load_dwordx2 v[216:217], v1, s[88:89] offset:3072
	global_load_dwordx2 v[218:219], v1, s[88:89] offset:3584
	s_add_u32 s88, s88, 0x800000
	s_addc_u32 s89, s89, 0
	s_waitcnt vmcnt(24)
	v_lshlrev_b32_e32 v126, 16, v110
	v_and_b32_e32 v127, 0xffff0000, v110
	v_lshlrev_b32_e32 v128, 16, v111
	v_and_b32_e32 v129, 0xffff0000, v111
	v_lshlrev_b32_e32 v130, 16, v112
	v_and_b32_e32 v131, 0xffff0000, v112
	v_lshlrev_b32_e32 v132, 16, v113
	v_and_b32_e32 v133, 0xffff0000, v113
	v_lshlrev_b32_e32 v240, 16, v114
	v_and_b32_e32 v241, 0xffff0000, v114
	v_lshlrev_b32_e32 v242, 16, v115
	v_and_b32_e32 v243, 0xffff0000, v115
	v_lshlrev_b32_e32 v244, 16, v116
	v_and_b32_e32 v245, 0xffff0000, v116
	v_lshlrev_b32_e32 v246, 16, v117
	v_and_b32_e32 v247, 0xffff0000, v117
	v_lshlrev_b32_e32 v248, 16, v118
	v_and_b32_e32 v249, 0xffff0000, v118
	v_lshlrev_b32_e32 v250, 16, v119
	v_and_b32_e32 v251, 0xffff0000, v119
	v_lshlrev_b32_e32 v32, 16, v120
	v_and_b32_e32 v33, 0xffff0000, v120
	v_lshlrev_b32_e32 v34, 16, v121
	v_and_b32_e32 v35, 0xffff0000, v121
	v_lshlrev_b32_e32 v36, 16, v122
	v_and_b32_e32 v37, 0xffff0000, v122
	v_lshlrev_b32_e32 v38, 16, v123
	v_and_b32_e32 v39, 0xffff0000, v123
	v_lshlrev_b32_e32 v20, 16, v124
	v_and_b32_e32 v21, 0xffff0000, v124
	v_lshlrev_b32_e32 v22, 16, v125
	v_and_b32_e32 v23, 0xffff0000, v125
	v_pk_add_f32 v[228:229], v[126:127], v[128:129]
	v_pk_add_f32 v[228:229], v[228:229], v[130:131]
	v_pk_add_f32 v[228:229], v[228:229], v[132:133]
	v_pk_add_f32 v[228:229], v[228:229], v[240:241]
	v_pk_add_f32 v[228:229], v[228:229], v[242:243]
	v_pk_add_f32 v[228:229], v[228:229], v[244:245]
	v_pk_add_f32 v[228:229], v[228:229], v[246:247]
	v_pk_add_f32 v[228:229], v[228:229], v[248:249]
	v_pk_add_f32 v[228:229], v[228:229], v[250:251]
	v_pk_add_f32 v[228:229], v[228:229], v[32:33]
	v_pk_add_f32 v[228:229], v[228:229], v[34:35]
	v_pk_add_f32 v[228:229], v[228:229], v[36:37]
	v_pk_add_f32 v[228:229], v[228:229], v[38:39]
	v_pk_add_f32 v[228:229], v[228:229], v[20:21]
	v_pk_add_f32 v[228:229], v[228:229], v[22:23]
	v_add_f32_e32 v228, v228, v229
	s_nop 1
	v_add_f32_dpp v228, v228, v228 quad_perm:[1,0,3,2] row_mask:0xf bank_mask:0xf bound_ctrl:1
	s_nop 1
	v_add_f32_dpp v228, v228, v228 quad_perm:[2,3,0,1] row_mask:0xf bank_mask:0xf bound_ctrl:1
	s_nop 1
	v_add_f32_dpp v228, v228, v228 row_half_mirror row_mask:0xf bank_mask:0xf bound_ctrl:1
	s_nop 1
	v_add_f32_dpp v228, v228, v228 row_mirror row_mask:0xf bank_mask:0xf bound_ctrl:1
	v_mov_b32_e32 v2, v228
	s_nop 1
	v_permlane16_swap_b32 v228, v2
	s_nop 0
	v_add_f32_e32 v228, v228, v2
	v_mov_b32_e32 v2, v228
	s_nop 1
	v_permlane32_swap_b32 v228, v2
	s_nop 0
	v_add_f32_e32 v228, v228, v2
	v_mul_f32_e32 v134, 0x3a000000, v228
	v_pk_add_f32 v[126:127], v[126:127], v[134:135] op_sel_hi:[1,0] neg_lo:[0,1] neg_hi:[0,1]
	v_pk_add_f32 v[128:129], v[128:129], v[134:135] op_sel_hi:[1,0] neg_lo:[0,1] neg_hi:[0,1]
	v_pk_add_f32 v[130:131], v[130:131], v[134:135] op_sel_hi:[1,0] neg_lo:[0,1] neg_hi:[0,1]
	v_pk_add_f32 v[132:133], v[132:133], v[134:135] op_sel_hi:[1,0] neg_lo:[0,1] neg_hi:[0,1]
	v_pk_add_f32 v[240:241], v[240:241], v[134:135] op_sel_hi:[1,0] neg_lo:[0,1] neg_hi:[0,1]
	v_pk_add_f32 v[242:243], v[242:243], v[134:135] op_sel_hi:[1,0] neg_lo:[0,1] neg_hi:[0,1]
	v_pk_add_f32 v[244:245], v[244:245], v[134:135] op_sel_hi:[1,0] neg_lo:[0,1] neg_hi:[0,1]
	v_pk_add_f32 v[246:247], v[246:247], v[134:135] op_sel_hi:[1,0] neg_lo:[0,1] neg_hi:[0,1]
	v_pk_add_f32 v[248:249], v[248:249], v[134:135] op_sel_hi:[1,0] neg_lo:[0,1] neg_hi:[0,1]
	v_pk_add_f32 v[250:251], v[250:251], v[134:135] op_sel_hi:[1,0] neg_lo:[0,1] neg_hi:[0,1]
	v_pk_add_f32 v[32:33], v[32:33], v[134:135] op_sel_hi:[1,0] neg_lo:[0,1] neg_hi:[0,1]
	v_pk_add_f32 v[34:35], v[34:35], v[134:135] op_sel_hi:[1,0] neg_lo:[0,1] neg_hi:[0,1]
	v_pk_add_f32 v[36:37], v[36:37], v[134:135] op_sel_hi:[1,0] neg_lo:[0,1] neg_hi:[0,1]
	v_pk_add_f32 v[38:39], v[38:39], v[134:135] op_sel_hi:[1,0] neg_lo:[0,1] neg_hi:[0,1]
	v_pk_add_f32 v[20:21], v[20:21], v[134:135] op_sel_hi:[1,0] neg_lo:[0,1] neg_hi:[0,1]
	v_pk_add_f32 v[22:23], v[22:23], v[134:135] op_sel_hi:[1,0] neg_lo:[0,1] neg_hi:[0,1]
	v_pk_mul_f32 v[228:229], v[126:127], v[126:127]
	v_pk_fma_f32 v[228:229], v[128:129], v[128:129], v[228:229]
	v_pk_fma_f32 v[228:229], v[130:131], v[130:131], v[228:229]
	v_pk_fma_f32 v[228:229], v[132:133], v[132:133], v[228:229]
	v_pk_fma_f32 v[228:229], v[240:241], v[240:241], v[228:229]
	v_pk_fma_f32 v[228:229], v[242:243], v[242:243], v[228:229]
	v_pk_fma_f32 v[228:229], v[244:245], v[244:245], v[228:229]
	v_pk_fma_f32 v[228:229], v[246:247], v[246:247], v[228:229]
	v_pk_fma_f32 v[228:229], v[248:249], v[248:249], v[228:229]
	v_pk_fma_f32 v[228:229], v[250:251], v[250:251], v[228:229]
	v_pk_fma_f32 v[228:229], v[32:33], v[32:33], v[228:229]
	v_pk_fma_f32 v[228:229], v[34:35], v[34:35], v[228:229]
	v_pk_fma_f32 v[228:229], v[36:37], v[36:37], v[228:229]
	v_pk_fma_f32 v[228:229], v[38:39], v[38:39], v[228:229]
	v_pk_fma_f32 v[228:229], v[20:21], v[20:21], v[228:229]
	v_pk_fma_f32 v[228:229], v[22:23], v[22:23], v[228:229]
	v_add_f32_e32 v228, v228, v229
	s_nop 1
	v_add_f32_dpp v228, v228, v228 quad_perm:[1,0,3,2] row_mask:0xf bank_mask:0xf bound_ctrl:1
	s_nop 1
	v_add_f32_dpp v228, v228, v228 quad_perm:[2,3,0,1] row_mask:0xf bank_mask:0xf bound_ctrl:1
	s_nop 1
	v_add_f32_dpp v228, v228, v228 row_half_mirror row_mask:0xf bank_mask:0xf bound_ctrl:1
	s_nop 1
	v_add_f32_dpp v228, v228, v228 row_mirror row_mask:0xf bank_mask:0xf bound_ctrl:1
	v_mov_b32_e32 v2, v228
	s_nop 1
	v_permlane16_swap_b32 v228, v2
	s_nop 0
	v_add_f32_e32 v228, v228, v2
	v_mov_b32_e32 v2, v228
	s_nop 1
	v_permlane32_swap_b32 v228, v2
	s_nop 0
	v_add_f32_e32 v228, v228, v2
	v_mul_f32_e32 v0, 0x3a000000, v228
	v_add_f32_e32 v0, 0x3727c5ac, v0
	v_rsq_f32_e32 v0, v0
	s_nop 0
	v_pk_mul_f32 v[228:229], v[140:141], v[0:1] op_sel_hi:[1,0]
	v_pk_fma_f32 v[126:127], v[126:127], v[228:229], v[172:173]
	v_pk_mul_f32 v[228:229], v[142:143], v[0:1] op_sel_hi:[1,0]
	v_pk_fma_f32 v[128:129], v[128:129], v[228:229], v[174:175]
	v_pk_mul_f32 v[228:229], v[144:145], v[0:1] op_sel_hi:[1,0]
	v_pk_fma_f32 v[130:131], v[130:131], v[228:229], v[176:177]
	v_pk_mul_f32 v[228:229], v[146:147], v[0:1] op_sel_hi:[1,0]
	v_pk_fma_f32 v[132:133], v[132:133], v[228:229], v[178:179]
	v_pk_mul_f32 v[228:229], v[148:149], v[0:1] op_sel_hi:[1,0]
	v_pk_fma_f32 v[240:241], v[240:241], v[228:229], v[180:181]
	v_pk_mul_f32 v[228:229], v[150:151], v[0:1] op_sel_hi:[1,0]
	v_pk_fma_f32 v[242:243], v[242:243], v[228:229], v[182:183]
	v_pk_mul_f32 v[228:229], v[152:153], v[0:1] op_sel_hi:[1,0]
	v_pk_fma_f32 v[244:245], v[244:245], v[228:229], v[184:185]
	v_pk_mul_f32 v[228:229], v[154:155], v[0:1] op_sel_hi:[1,0]
	v_pk_fma_f32 v[246:247], v[246:247], v[228:229], v[186:187]
	v_pk_mul_f32 v[228:229], v[156:157], v[0:1] op_sel_hi:[1,0]
	v_pk_fma_f32 v[248:249], v[248:249], v[228:229], v[188:189]
	v_pk_mul_f32 v[228:229], v[158:159], v[0:1] op_sel_hi:[1,0]
	v_pk_fma_f32 v[250:251], v[250:251], v[228:229], v[190:191]
	v_pk_mul_f32 v[228:229], v[160:161], v[0:1] op_sel_hi:[1,0]
	v_pk_fma_f32 v[32:33], v[32:33], v[228:229], v[192:193]
	v_pk_mul_f32 v[228:229], v[162:163], v[0:1] op_sel_hi:[1,0]
	v_pk_fma_f32 v[34:35], v[34:35], v[228:229], v[194:195]
	v_pk_mul_f32 v[228:229], v[164:165], v[0:1] op_sel_hi:[1,0]
	v_pk_fma_f32 v[36:37], v[36:37], v[228:229], v[196:197]
	v_pk_mul_f32 v[228:229], v[166:167], v[0:1] op_sel_hi:[1,0]
	v_pk_fma_f32 v[38:39], v[38:39], v[228:229], v[198:199]
	v_pk_mul_f32 v[228:229], v[168:169], v[0:1] op_sel_hi:[1,0]
	v_pk_fma_f32 v[20:21], v[20:21], v[228:229], v[200:201]
	v_pk_mul_f32 v[228:229], v[170:171], v[0:1] op_sel_hi:[1,0]
	v_pk_fma_f32 v[22:23], v[22:23], v[228:229], v[202:203]
	global_store_dwordx4 v75, v[126:129], s[90:91] offset:0
	global_store_dwordx4 v75, v[130:133], s[90:91] offset:1024
	global_store_dwordx4 v75, v[240:243], s[90:91] offset:2048
	global_store_dwordx4 v75, v[244:247], s[90:91] offset:3072
	global_store_dwordx4 v135, v[248:251], s[90:91] offset:0
	global_store_dwordx4 v135, v[32:35], s[90:91] offset:1024
	global_store_dwordx4 v135, v[36:39], s[90:91] offset:2048
	global_store_dwordx4 v135, v[20:23], s[90:91] offset:3072
	s_add_u32 s90, s90, 0x1000000
	s_addc_u32 s91, s91, 0
	s_waitcnt vmcnt(24)
	v_lshlrev_b32_e32 v126, 16, v24
	v_and_b32_e32 v127, 0xffff0000, v24
	v_lshlrev_b32_e32 v128, 16, v25
	v_and_b32_e32 v129, 0xffff0000, v25
	v_lshlrev_b32_e32 v130, 16, v26
	v_and_b32_e32 v131, 0xffff0000, v26
	v_lshlrev_b32_e32 v132, 16, v27
	v_and_b32_e32 v133, 0xffff0000, v27
	v_lshlrev_b32_e32 v240, 16, v8
	v_and_b32_e32 v241, 0xffff0000, v8
	v_lshlrev_b32_e32 v242, 16, v9
	v_and_b32_e32 v243, 0xffff0000, v9
	v_lshlrev_b32_e32 v244, 16, v10
	v_and_b32_e32 v245, 0xffff0000, v10
	v_lshlrev_b32_e32 v246, 16, v11
	v_and_b32_e32 v247, 0xffff0000, v11
	v_lshlrev_b32_e32 v248, 16, v220
	v_and_b32_e32 v249, 0xffff0000, v220
	v_lshlrev_b32_e32 v250, 16, v221
	v_and_b32_e32 v251, 0xffff0000, v221
	v_lshlrev_b32_e32 v32, 16, v222
	v_and_b32_e32 v33, 0xffff0000, v222
	v_lshlrev_b32_e32 v34, 16, v223
	v_and_b32_e32 v35, 0xffff0000, v223
	v_lshlrev_b32_e32 v36, 16, v224
	v_and_b32_e32 v37, 0xffff0000, v224
	v_lshlrev_b32_e32 v38, 16, v225
	v_and_b32_e32 v39, 0xffff0000, v225
	v_lshlrev_b32_e32 v20, 16, v226
	v_and_b32_e32 v21, 0xffff0000, v226
	v_lshlrev_b32_e32 v22, 16, v227
	v_and_b32_e32 v23, 0xffff0000, v227
	v_pk_add_f32 v[228:229], v[126:127], v[128:129]
	v_pk_add_f32 v[228:229], v[228:229], v[130:131]
	v_pk_add_f32 v[228:229], v[228:229], v[132:133]
	v_pk_add_f32 v[228:229], v[228:229], v[240:241]
	v_pk_add_f32 v[228:229], v[228:229], v[242:243]
	v_pk_add_f32 v[228:229], v[228:229], v[244:245]
	v_pk_add_f32 v[228:229], v[228:229], v[246:247]
	v_pk_add_f32 v[228:229], v[228:229], v[248:249]
	v_pk_add_f32 v[228:229], v[228:229], v[250:251]
	v_pk_add_f32 v[228:229], v[228:229], v[32:33]
	v_pk_add_f32 v[228:229], v[228:229], v[34:35]
	v_pk_add_f32 v[228:229], v[228:229], v[36:37]
	v_pk_add_f32 v[228:229], v[228:229], v[38:39]
	v_pk_add_f32 v[228:229], v[228:229], v[20:21]
	v_pk_add_f32 v[228:229], v[228:229], v[22:23]
	v_add_f32_e32 v228, v228, v229
	s_nop 1
	v_add_f32_dpp v228, v228, v228 quad_perm:[1,0,3,2] row_mask:0xf bank_mask:0xf bound_ctrl:1
	s_nop 1
	v_add_f32_dpp v228, v228, v228 quad_perm:[2,3,0,1] row_mask:0xf bank_mask:0xf bound_ctrl:1
	s_nop 1
	v_add_f32_dpp v228, v228, v228 row_half_mirror row_mask:0xf bank_mask:0xf bound_ctrl:1
	s_nop 1
	v_add_f32_dpp v228, v228, v228 row_mirror row_mask:0xf bank_mask:0xf bound_ctrl:1
	v_mov_b32_e32 v2, v228
	s_nop 1
	v_permlane16_swap_b32 v228, v2
	s_nop 0
	v_add_f32_e32 v228, v228, v2
	v_mov_b32_e32 v2, v228
	s_nop 1
	v_permlane32_swap_b32 v228, v2
	s_nop 0
	v_add_f32_e32 v228, v228, v2
	v_mul_f32_e32 v134, 0x3a000000, v228
	v_pk_add_f32 v[126:127], v[126:127], v[134:135] op_sel_hi:[1,0] neg_lo:[0,1] neg_hi:[0,1]
	v_pk_add_f32 v[128:129], v[128:129], v[134:135] op_sel_hi:[1,0] neg_lo:[0,1] neg_hi:[0,1]
	v_pk_add_f32 v[130:131], v[130:131], v[134:135] op_sel_hi:[1,0] neg_lo:[0,1] neg_hi:[0,1]
	v_pk_add_f32 v[132:133], v[132:133], v[134:135] op_sel_hi:[1,0] neg_lo:[0,1] neg_hi:[0,1]
	v_pk_add_f32 v[240:241], v[240:241], v[134:135] op_sel_hi:[1,0] neg_lo:[0,1] neg_hi:[0,1]
	v_pk_add_f32 v[242:243], v[242:243], v[134:135] op_sel_hi:[1,0] neg_lo:[0,1] neg_hi:[0,1]
	v_pk_add_f32 v[244:245], v[244:245], v[134:135] op_sel_hi:[1,0] neg_lo:[0,1] neg_hi:[0,1]
	v_pk_add_f32 v[246:247], v[246:247], v[134:135] op_sel_hi:[1,0] neg_lo:[0,1] neg_hi:[0,1]
	v_pk_add_f32 v[248:249], v[248:249], v[134:135] op_sel_hi:[1,0] neg_lo:[0,1] neg_hi:[0,1]
	v_pk_add_f32 v[250:251], v[250:251], v[134:135] op_sel_hi:[1,0] neg_lo:[0,1] neg_hi:[0,1]
	v_pk_add_f32 v[32:33], v[32:33], v[134:135] op_sel_hi:[1,0] neg_lo:[0,1] neg_hi:[0,1]
	v_pk_add_f32 v[34:35], v[34:35], v[134:135] op_sel_hi:[1,0] neg_lo:[0,1] neg_hi:[0,1]
	v_pk_add_f32 v[36:37], v[36:37], v[134:135] op_sel_hi:[1,0] neg_lo:[0,1] neg_hi:[0,1]
	v_pk_add_f32 v[38:39], v[38:39], v[134:135] op_sel_hi:[1,0] neg_lo:[0,1] neg_hi:[0,1]
	v_pk_add_f32 v[20:21], v[20:21], v[134:135] op_sel_hi:[1,0] neg_lo:[0,1] neg_hi:[0,1]
	v_pk_add_f32 v[22:23], v[22:23], v[134:135] op_sel_hi:[1,0] neg_lo:[0,1] neg_hi:[0,1]
	v_pk_mul_f32 v[228:229], v[126:127], v[126:127]
	v_pk_fma_f32 v[228:229], v[128:129], v[128:129], v[228:229]
	v_pk_fma_f32 v[228:229], v[130:131], v[130:131], v[228:229]
	v_pk_fma_f32 v[228:229], v[132:133], v[132:133], v[228:229]
	v_pk_fma_f32 v[228:229], v[240:241], v[240:241], v[228:229]
	v_pk_fma_f32 v[228:229], v[242:243], v[242:243], v[228:229]
	v_pk_fma_f32 v[228:229], v[244:245], v[244:245], v[228:229]
	v_pk_fma_f32 v[228:229], v[246:247], v[246:247], v[228:229]
	v_pk_fma_f32 v[228:229], v[248:249], v[248:249], v[228:229]
	v_pk_fma_f32 v[228:229], v[250:251], v[250:251], v[228:229]
	v_pk_fma_f32 v[228:229], v[32:33], v[32:33], v[228:229]
	v_pk_fma_f32 v[228:229], v[34:35], v[34:35], v[228:229]
	v_pk_fma_f32 v[228:229], v[36:37], v[36:37], v[228:229]
	v_pk_fma_f32 v[228:229], v[38:39], v[38:39], v[228:229]
	v_pk_fma_f32 v[228:229], v[20:21], v[20:21], v[228:229]
	v_pk_fma_f32 v[228:229], v[22:23], v[22:23], v[228:229]
	v_add_f32_e32 v228, v228, v229
	s_nop 1
	v_add_f32_dpp v228, v228, v228 quad_perm:[1,0,3,2] row_mask:0xf bank_mask:0xf bound_ctrl:1
	s_nop 1
	v_add_f32_dpp v228, v228, v228 quad_perm:[2,3,0,1] row_mask:0xf bank_mask:0xf bound_ctrl:1
	s_nop 1
	v_add_f32_dpp v228, v228, v228 row_half_mirror row_mask:0xf bank_mask:0xf bound_ctrl:1
	s_nop 1
	v_add_f32_dpp v228, v228, v228 row_mirror row_mask:0xf bank_mask:0xf bound_ctrl:1
	v_mov_b32_e32 v2, v228
	s_nop 1
	v_permlane16_swap_b32 v228, v2
	s_nop 0
	v_add_f32_e32 v228, v228, v2
	v_mov_b32_e32 v2, v228
	s_nop 1
	v_permlane32_swap_b32 v228, v2
	s_nop 0
	v_add_f32_e32 v228, v228, v2
	v_mul_f32_e32 v0, 0x3a000000, v228
	v_add_f32_e32 v0, 0x3727c5ac, v0
	v_rsq_f32_e32 v0, v0
	s_nop 0
	v_pk_mul_f32 v[228:229], v[140:141], v[0:1] op_sel_hi:[1,0]
	v_pk_fma_f32 v[126:127], v[126:127], v[228:229], v[172:173]
	v_pk_mul_f32 v[228:229], v[142:143], v[0:1] op_sel_hi:[1,0]
	v_pk_fma_f32 v[128:129], v[128:129], v[228:229], v[174:175]
	v_pk_mul_f32 v[228:229], v[144:145], v[0:1] op_sel_hi:[1,0]
	v_pk_fma_f32 v[130:131], v[130:131], v[228:229], v[176:177]
	v_pk_mul_f32 v[228:229], v[146:147], v[0:1] op_sel_hi:[1,0]
	v_pk_fma_f32 v[132:133], v[132:133], v[228:229], v[178:179]
	v_pk_mul_f32 v[228:229], v[148:149], v[0:1] op_sel_hi:[1,0]
	v_pk_fma_f32 v[240:241], v[240:241], v[228:229], v[180:181]
	v_pk_mul_f32 v[228:229], v[150:151], v[0:1] op_sel_hi:[1,0]
	v_pk_fma_f32 v[242:243], v[242:243], v[228:229], v[182:183]
	v_pk_mul_f32 v[228:229], v[152:153], v[0:1] op_sel_hi:[1,0]
	v_pk_fma_f32 v[244:245], v[244:245], v[228:229], v[184:185]
	v_pk_mul_f32 v[228:229], v[154:155], v[0:1] op_sel_hi:[1,0]
	v_pk_fma_f32 v[246:247], v[246:247], v[228:229], v[186:187]
	v_pk_mul_f32 v[228:229], v[156:157], v[0:1] op_sel_hi:[1,0]
	v_pk_fma_f32 v[248:249], v[248:249], v[228:229], v[188:189]
	v_pk_mul_f32 v[228:229], v[158:159], v[0:1] op_sel_hi:[1,0]
	v_pk_fma_f32 v[250:251], v[250:251], v[228:229], v[190:191]
	v_pk_mul_f32 v[228:229], v[160:161], v[0:1] op_sel_hi:[1,0]
	v_pk_fma_f32 v[32:33], v[32:33], v[228:229], v[192:193]
	v_pk_mul_f32 v[228:229], v[162:163], v[0:1] op_sel_hi:[1,0]
	v_pk_fma_f32 v[34:35], v[34:35], v[228:229], v[194:195]
	v_pk_mul_f32 v[228:229], v[164:165], v[0:1] op_sel_hi:[1,0]
	v_pk_fma_f32 v[36:37], v[36:37], v[228:229], v[196:197]
	v_pk_mul_f32 v[228:229], v[166:167], v[0:1] op_sel_hi:[1,0]
	v_pk_fma_f32 v[38:39], v[38:39], v[228:229], v[198:199]
	v_pk_mul_f32 v[228:229], v[168:169], v[0:1] op_sel_hi:[1,0]
	v_pk_fma_f32 v[20:21], v[20:21], v[228:229], v[200:201]
	v_pk_mul_f32 v[228:229], v[170:171], v[0:1] op_sel_hi:[1,0]
	v_pk_fma_f32 v[22:23], v[22:23], v[228:229], v[202:203]
	global_store_dwordx4 v75, v[126:129], s[90:91] offset:0
	global_store_dwordx4 v75, v[130:133], s[90:91] offset:1024
	global_store_dwordx4 v75, v[240:243], s[90:91] offset:2048
	global_store_dwordx4 v75, v[244:247], s[90:91] offset:3072
	global_store_dwordx4 v135, v[248:251], s[90:91] offset:0
	global_store_dwordx4 v135, v[32:35], s[90:91] offset:1024
	global_store_dwordx4 v135, v[36:39], s[90:91] offset:2048
	global_store_dwordx4 v135, v[20:23], s[90:91] offset:3072
	s_add_u32 s90, s90, 0x1000000
	s_addc_u32 s91, s91, 0
	s_waitcnt vmcnt(16)
	v_lshlrev_b32_e32 v126, 16, v204
	v_and_b32_e32 v127, 0xffff0000, v204
	v_lshlrev_b32_e32 v128, 16, v205
	v_and_b32_e32 v129, 0xffff0000, v205
	v_lshlrev_b32_e32 v130, 16, v206
	v_and_b32_e32 v131, 0xffff0000, v206
	v_lshlrev_b32_e32 v132, 16, v207
	v_and_b32_e32 v133, 0xffff0000, v207
	v_lshlrev_b32_e32 v240, 16, v208
	v_and_b32_e32 v241, 0xffff0000, v208
	v_lshlrev_b32_e32 v242, 16, v209
	v_and_b32_e32 v243, 0xffff0000, v209
	v_lshlrev_b32_e32 v244, 16, v210
	v_and_b32_e32 v245, 0xffff0000, v210
	v_lshlrev_b32_e32 v246, 16, v211
	v_and_b32_e32 v247, 0xffff0000, v211
	v_lshlrev_b32_e32 v248, 16, v212
	v_and_b32_e32 v249, 0xffff0000, v212
	v_lshlrev_b32_e32 v250, 16, v213
	v_and_b32_e32 v251, 0xffff0000, v213
	v_lshlrev_b32_e32 v32, 16, v214
	v_and_b32_e32 v33, 0xffff0000, v214
	v_lshlrev_b32_e32 v34, 16, v215
	v_and_b32_e32 v35, 0xffff0000, v215
	v_lshlrev_b32_e32 v36, 16, v216
	v_and_b32_e32 v37, 0xffff0000, v216
	v_lshlrev_b32_e32 v38, 16, v217
	v_and_b32_e32 v39, 0xffff0000, v217
	v_lshlrev_b32_e32 v20, 16, v218
	v_and_b32_e32 v21, 0xffff0000, v218
	v_lshlrev_b32_e32 v22, 16, v219
	v_and_b32_e32 v23, 0xffff0000, v219
	v_pk_add_f32 v[228:229], v[126:127], v[128:129]
	v_pk_add_f32 v[228:229], v[228:229], v[130:131]
	v_pk_add_f32 v[228:229], v[228:229], v[132:133]
	v_pk_add_f32 v[228:229], v[228:229], v[240:241]
	v_pk_add_f32 v[228:229], v[228:229], v[242:243]
	v_pk_add_f32 v[228:229], v[228:229], v[244:245]
	v_pk_add_f32 v[228:229], v[228:229], v[246:247]
	v_pk_add_f32 v[228:229], v[228:229], v[248:249]
	v_pk_add_f32 v[228:229], v[228:229], v[250:251]
	v_pk_add_f32 v[228:229], v[228:229], v[32:33]
	v_pk_add_f32 v[228:229], v[228:229], v[34:35]
	v_pk_add_f32 v[228:229], v[228:229], v[36:37]
	v_pk_add_f32 v[228:229], v[228:229], v[38:39]
	v_pk_add_f32 v[228:229], v[228:229], v[20:21]
	v_pk_add_f32 v[228:229], v[228:229], v[22:23]
	v_add_f32_e32 v228, v228, v229
	s_nop 1
	v_add_f32_dpp v228, v228, v228 quad_perm:[1,0,3,2] row_mask:0xf bank_mask:0xf bound_ctrl:1
	s_nop 1
	v_add_f32_dpp v228, v228, v228 quad_perm:[2,3,0,1] row_mask:0xf bank_mask:0xf bound_ctrl:1
	s_nop 1
	v_add_f32_dpp v228, v228, v228 row_half_mirror row_mask:0xf bank_mask:0xf bound_ctrl:1
	s_nop 1
	v_add_f32_dpp v228, v228, v228 row_mirror row_mask:0xf bank_mask:0xf bound_ctrl:1
	v_mov_b32_e32 v2, v228
	s_nop 1
	v_permlane16_swap_b32 v228, v2
	s_nop 0
	v_add_f32_e32 v228, v228, v2
	v_mov_b32_e32 v2, v228
	s_nop 1
	v_permlane32_swap_b32 v228, v2
	s_nop 0
	v_add_f32_e32 v228, v228, v2
	v_mul_f32_e32 v134, 0x3a000000, v228
	v_pk_add_f32 v[126:127], v[126:127], v[134:135] op_sel_hi:[1,0] neg_lo:[0,1] neg_hi:[0,1]
	v_pk_add_f32 v[128:129], v[128:129], v[134:135] op_sel_hi:[1,0] neg_lo:[0,1] neg_hi:[0,1]
	v_pk_add_f32 v[130:131], v[130:131], v[134:135] op_sel_hi:[1,0] neg_lo:[0,1] neg_hi:[0,1]
	v_pk_add_f32 v[132:133], v[132:133], v[134:135] op_sel_hi:[1,0] neg_lo:[0,1] neg_hi:[0,1]
	v_pk_add_f32 v[240:241], v[240:241], v[134:135] op_sel_hi:[1,0] neg_lo:[0,1] neg_hi:[0,1]
	v_pk_add_f32 v[242:243], v[242:243], v[134:135] op_sel_hi:[1,0] neg_lo:[0,1] neg_hi:[0,1]
	v_pk_add_f32 v[244:245], v[244:245], v[134:135] op_sel_hi:[1,0] neg_lo:[0,1] neg_hi:[0,1]
	v_pk_add_f32 v[246:247], v[246:247], v[134:135] op_sel_hi:[1,0] neg_lo:[0,1] neg_hi:[0,1]
	v_pk_add_f32 v[248:249], v[248:249], v[134:135] op_sel_hi:[1,0] neg_lo:[0,1] neg_hi:[0,1]
	v_pk_add_f32 v[250:251], v[250:251], v[134:135] op_sel_hi:[1,0] neg_lo:[0,1] neg_hi:[0,1]
	v_pk_add_f32 v[32:33], v[32:33], v[134:135] op_sel_hi:[1,0] neg_lo:[0,1] neg_hi:[0,1]
	v_pk_add_f32 v[34:35], v[34:35], v[134:135] op_sel_hi:[1,0] neg_lo:[0,1] neg_hi:[0,1]
	v_pk_add_f32 v[36:37], v[36:37], v[134:135] op_sel_hi:[1,0] neg_lo:[0,1] neg_hi:[0,1]
	v_pk_add_f32 v[38:39], v[38:39], v[134:135] op_sel_hi:[1,0] neg_lo:[0,1] neg_hi:[0,1]
	v_pk_add_f32 v[20:21], v[20:21], v[134:135] op_sel_hi:[1,0] neg_lo:[0,1] neg_hi:[0,1]
	v_pk_add_f32 v[22:23], v[22:23], v[134:135] op_sel_hi:[1,0] neg_lo:[0,1] neg_hi:[0,1]
	v_pk_mul_f32 v[228:229], v[126:127], v[126:127]
	v_pk_fma_f32 v[228:229], v[128:129], v[128:129], v[228:229]
	v_pk_fma_f32 v[228:229], v[130:131], v[130:131], v[228:229]
	v_pk_fma_f32 v[228:229], v[132:133], v[132:133], v[228:229]
	v_pk_fma_f32 v[228:229], v[240:241], v[240:241], v[228:229]
	v_pk_fma_f32 v[228:229], v[242:243], v[242:243], v[228:229]
	v_pk_fma_f32 v[228:229], v[244:245], v[244:245], v[228:229]
	v_pk_fma_f32 v[228:229], v[246:247], v[246:247], v[228:229]
	v_pk_fma_f32 v[228:229], v[248:249], v[248:249], v[228:229]
	v_pk_fma_f32 v[228:229], v[250:251], v[250:251], v[228:229]
	v_pk_fma_f32 v[228:229], v[32:33], v[32:33], v[228:229]
	v_pk_fma_f32 v[228:229], v[34:35], v[34:35], v[228:229]
	v_pk_fma_f32 v[228:229], v[36:37], v[36:37], v[228:229]
	v_pk_fma_f32 v[228:229], v[38:39], v[38:39], v[228:229]
	v_pk_fma_f32 v[228:229], v[20:21], v[20:21], v[228:229]
	v_pk_fma_f32 v[228:229], v[22:23], v[22:23], v[228:229]
	v_add_f32_e32 v228, v228, v229
	s_nop 1
	v_add_f32_dpp v228, v228, v228 quad_perm:[1,0,3,2] row_mask:0xf bank_mask:0xf bound_ctrl:1
	s_nop 1
	v_add_f32_dpp v228, v228, v228 quad_perm:[2,3,0,1] row_mask:0xf bank_mask:0xf bound_ctrl:1
	s_nop 1
	v_add_f32_dpp v228, v228, v228 row_half_mirror row_mask:0xf bank_mask:0xf bound_ctrl:1
	s_nop 1
	v_add_f32_dpp v228, v228, v228 row_mirror row_mask:0xf bank_mask:0xf bound_ctrl:1
	v_mov_b32_e32 v2, v228
	s_nop 1
	v_permlane16_swap_b32 v228, v2
	s_nop 0
	v_add_f32_e32 v228, v228, v2
	v_mov_b32_e32 v2, v228
	s_nop 1
	v_permlane32_swap_b32 v228, v2
	s_nop 0
	v_add_f32_e32 v228, v228, v2
	v_mul_f32_e32 v0, 0x3a000000, v228
	v_add_f32_e32 v0, 0x3727c5ac, v0
	v_rsq_f32_e32 v0, v0
	s_nop 0
	v_pk_mul_f32 v[228:229], v[140:141], v[0:1] op_sel_hi:[1,0]
	v_pk_fma_f32 v[126:127], v[126:127], v[228:229], v[172:173]
	v_pk_mul_f32 v[228:229], v[142:143], v[0:1] op_sel_hi:[1,0]
	v_pk_fma_f32 v[128:129], v[128:129], v[228:229], v[174:175]
	v_pk_mul_f32 v[228:229], v[144:145], v[0:1] op_sel_hi:[1,0]
	v_pk_fma_f32 v[130:131], v[130:131], v[228:229], v[176:177]
	v_pk_mul_f32 v[228:229], v[146:147], v[0:1] op_sel_hi:[1,0]
	v_pk_fma_f32 v[132:133], v[132:133], v[228:229], v[178:179]
	v_pk_mul_f32 v[228:229], v[148:149], v[0:1] op_sel_hi:[1,0]
	v_pk_fma_f32 v[240:241], v[240:241], v[228:229], v[180:181]
	v_pk_mul_f32 v[228:229], v[150:151], v[0:1] op_sel_hi:[1,0]
	v_pk_fma_f32 v[242:243], v[242:243], v[228:229], v[182:183]
	v_pk_mul_f32 v[228:229], v[152:153], v[0:1] op_sel_hi:[1,0]
	v_pk_fma_f32 v[244:245], v[244:245], v[228:229], v[184:185]
	v_pk_mul_f32 v[228:229], v[154:155], v[0:1] op_sel_hi:[1,0]
	v_pk_fma_f32 v[246:247], v[246:247], v[228:229], v[186:187]
	v_pk_mul_f32 v[228:229], v[156:157], v[0:1] op_sel_hi:[1,0]
	v_pk_fma_f32 v[248:249], v[248:249], v[228:229], v[188:189]
	v_pk_mul_f32 v[228:229], v[158:159], v[0:1] op_sel_hi:[1,0]
	v_pk_fma_f32 v[250:251], v[250:251], v[228:229], v[190:191]
	v_pk_mul_f32 v[228:229], v[160:161], v[0:1] op_sel_hi:[1,0]
	v_pk_fma_f32 v[32:33], v[32:33], v[228:229], v[192:193]
	v_pk_mul_f32 v[228:229], v[162:163], v[0:1] op_sel_hi:[1,0]
	v_pk_fma_f32 v[34:35], v[34:35], v[228:229], v[194:195]
	v_pk_mul_f32 v[228:229], v[164:165], v[0:1] op_sel_hi:[1,0]
	v_pk_fma_f32 v[36:37], v[36:37], v[228:229], v[196:197]
	v_pk_mul_f32 v[228:229], v[166:167], v[0:1] op_sel_hi:[1,0]
	v_pk_fma_f32 v[38:39], v[38:39], v[228:229], v[198:199]
	v_pk_mul_f32 v[228:229], v[168:169], v[0:1] op_sel_hi:[1,0]
	v_pk_fma_f32 v[20:21], v[20:21], v[228:229], v[200:201]
	v_pk_mul_f32 v[228:229], v[170:171], v[0:1] op_sel_hi:[1,0]
	v_pk_fma_f32 v[22:23], v[22:23], v[228:229], v[202:203]
	global_store_dwordx4 v75, v[126:129], s[90:91] offset:0
	global_store_dwordx4 v75, v[130:133], s[90:91] offset:1024
	global_store_dwordx4 v75, v[240:243], s[90:91] offset:2048
	global_store_dwordx4 v75, v[244:247], s[90:91] offset:3072
	global_store_dwordx4 v135, v[248:251], s[90:91] offset:0
	global_store_dwordx4 v135, v[32:35], s[90:91] offset:1024
	global_store_dwordx4 v135, v[36:39], s[90:91] offset:2048
	global_store_dwordx4 v135, v[20:23], s[90:91] offset:3072
	s_add_u32 s90, s90, 0x1000000
	s_addc_u32 s91, s91, 0
